# nt cache policy on more read-once loads: conv/LN inputs, spatial-gate u tiles, residual rows of the rms phases, q slabs, mid-K gate tiles
# baseline (speedup 1.0000x reference)
.LBB0_330:
	v_ashrrev_i32_e32 v8, 5, v94
	v_and_b32_e32 v52, -4, v8
	v_cmp_gt_i32_e64 s[4:5], s29, v52
	v_and_b32_e32 v48, 0x3f8, v95
	v_cmp_lt_i32_e64 s[6:7], s25, v52
	v_cndmask_b32_e64 v99, 4, v96, s[4:5]
	v_and_b32_e32 v100, v99, v8
	v_cmp_ne_u32_e32 vcc, 0, v100
	s_and_saveexec_b64 s[46:47], vcc
	s_xor_b64 s[46:47], exec, s[46:47]
	s_cbranch_execz .LBB0_332
	v_mov_b64_e32 v[10:11], s[14:15]
	v_add_u32_e32 v0, -1, v52
	v_lshlrev_b32_e32 v12, 1, v48
	v_mov_b32_e32 v13, v49
	v_mad_i64_i32 v[0:1], s[52:53], v0, s48, v[10:11]
	v_lshl_add_u64 v[4:5], v[0:1], 0, v[12:13]
	v_add_co_u32_e32 v0, vcc, s49, v4
	v_add_u32_e32 v9, -2, v52
	s_nop 0
	v_addc_co_u32_e32 v1, vcc, 0, v5, vcc
	v_add_co_u32_e32 v4, vcc, s29, v4
	v_mad_i64_i32 v[10:11], s[52:53], v9, s48, v[10:11]
	s_nop 0
	v_addc_co_u32_e32 v5, vcc, 0, v5, vcc
	v_lshl_add_u64 v[14:15], v[10:11], 0, v[12:13]
	v_add_co_u32_e32 v10, vcc, 0x1000, v14
	flat_load_dwordx4 v[0:3], v[0:1] offset:2048 nt
	s_nop 0
	v_addc_co_u32_e32 v11, vcc, 0, v15, vcc
	v_add_co_u32_e32 v14, vcc, s29, v14
	flat_load_dwordx4 v[4:7], v[4:5] nt
	s_nop 0
	v_addc_co_u32_e32 v15, vcc, 0, v15, vcc
	flat_load_dwordx4 v[10:13], v[10:11] offset:2048 nt
	s_waitcnt vmcnt(0) lgkmcnt(0)
	v_lshlrev_b32_e32 v18, 16, v0
	flat_load_dwordx4 v[14:17], v[14:15] nt
	v_and_b32_e32 v19, 0xffff0000, v0
	v_lshlrev_b32_e32 v0, 16, v1
	v_and_b32_e32 v1, 0xffff0000, v1
	v_lshlrev_b32_e32 v20, 16, v4
	v_and_b32_e32 v21, 0xffff0000, v4
	v_lshlrev_b32_e32 v22, 16, v5
	v_and_b32_e32 v23, 0xffff0000, v5
	v_lshlrev_b32_e32 v24, 16, v2
	v_and_b32_e32 v25, 0xffff0000, v2
	v_lshlrev_b32_e32 v26, 16, v6
	v_and_b32_e32 v27, 0xffff0000, v6
	v_lshlrev_b32_e32 v2, 16, v3
	v_and_b32_e32 v3, 0xffff0000, v3
	v_lshlrev_b32_e32 v28, 16, v7
	v_and_b32_e32 v29, 0xffff0000, v7
	v_lshlrev_b32_e32 v30, 16, v10
	v_and_b32_e32 v31, 0xffff0000, v10
	v_lshlrev_b32_e32 v10, 16, v11
	v_and_b32_e32 v11, 0xffff0000, v11
	v_lshlrev_b32_e32 v32, 16, v12
	v_and_b32_e32 v33, 0xffff0000, v12
	v_lshlrev_b32_e32 v12, 16, v13
	v_and_b32_e32 v13, 0xffff0000, v13
	v_pk_mul_f32 v[4:5], v[18:19], v[20:21]
	v_pk_mul_f32 v[6:7], v[0:1], v[22:23]
	v_pk_mul_f32 v[0:1], v[24:25], v[26:27]
	v_pk_mul_f32 v[2:3], v[2:3], v[28:29]
	v_mov_b32_e32 v57, v0
	v_mov_b32_e32 v55, v2
	v_mov_b32_e32 v61, v6
	v_mov_b32_e32 v63, v4
	s_waitcnt vmcnt(0) lgkmcnt(0)
	v_lshlrev_b32_e32 v18, 16, v14
	v_and_b32_e32 v19, 0xffff0000, v14
	v_lshlrev_b32_e32 v14, 16, v15
	v_and_b32_e32 v15, 0xffff0000, v15
	v_lshlrev_b32_e32 v20, 16, v16
	v_and_b32_e32 v21, 0xffff0000, v16
	v_lshlrev_b32_e32 v16, 16, v17
	v_and_b32_e32 v17, 0xffff0000, v17
	v_pk_mul_f32 v[18:19], v[30:31], v[18:19]
	v_pk_mul_f32 v[10:11], v[10:11], v[14:15]
	v_pk_mul_f32 v[14:15], v[32:33], v[20:21]
	v_pk_mul_f32 v[12:13], v[12:13], v[16:17]
	v_mov_b32_e32 v0, v15
	v_mov_b32_e32 v2, v13
	v_mov_b32_e32 v54, v12
	v_mov_b32_e32 v56, v14
	v_mov_b32_e32 v6, v11
	v_mov_b32_e32 v60, v10
	v_mov_b32_e32 v4, v19
	v_mov_b32_e32 v62, v18
.LBB0_332:
	s_or_saveexec_b64 s[46:47], s[46:47]
	v_add_u32_e32 v9, 0xffffe000, v8
	v_lshrrev_b32_e32 v50, 3, v9
	s_xor_b64 exec, exec, s[46:47]
	s_cbranch_execz .LBB0_338
	s_and_saveexec_b64 s[52:53], s[6:7]
	s_xor_b64 s[6:7], exec, s[52:53]
	s_cbranch_execz .LBB0_335
	v_mov_b32_e32 v51, v49
	v_lshlrev_b64 v[0:1], 13, v[50:51]
	s_waitcnt lgkmcnt(0)
	v_lshl_add_u64 v[0:1], s[38:39], 0, v[0:1]
	v_lshlrev_b32_e32 v2, 2, v48
	v_mov_b32_e32 v3, v49
	v_lshl_add_u64 v[4:5], v[0:1], 0, v[2:3]
	global_load_dwordx4 v[10:13], v[4:5], off nt
	global_load_dwordx4 v[14:17], v[4:5], off offset:16 nt
	v_lshl_add_u64 v[0:1], v[4:5], 0, s[42:43]
	v_add_co_u32_e32 v4, vcc, 0x1000, v4
	global_load_dwordx4 v[0:3], v[0:1], off offset:16 nt
	s_nop 0
	v_addc_co_u32_e32 v5, vcc, 0, v5, vcc
	global_load_dwordx4 v[4:7], v[4:5], off nt
	s_waitcnt vmcnt(0)
	v_mov_b32_e32 v60, v12
	s_waitcnt vmcnt(2)
	v_mov_b32_e32 v54, v16
	v_mov_b32_e32 v56, v14
	v_mov_b32_e32 v62, v10
	s_waitcnt vmcnt(1)
	v_mov_b32_e32 v55, v2
	v_mov_b32_e32 v57, v0
	v_mov_b32_e32 v2, v17
	s_waitcnt vmcnt(0)
	v_mov_b32_e32 v61, v6
	v_mov_b32_e32 v63, v4
	v_mov_b32_e32 v0, v15
	v_mov_b32_e32 v6, v13
	v_mov_b32_e32 v4, v11

.LBB0_338:
	s_or_b64 exec, exec, s[46:47]
	v_mov_b64_e32 v[26:27], s[14:15]
	v_mad_i64_i32 v[10:11], s[6:7], v52, s48, v[26:27]
	v_lshlrev_b64 v[58:59], 1, v[48:49]
	v_lshl_add_u64 v[10:11], v[10:11], 0, v[58:59]
	v_add_co_u32_e32 v18, vcc, s49, v10
	v_or_b32_e32 v68, 1, v52
	s_nop 0
	v_addc_co_u32_e32 v19, vcc, 0, v11, vcc
	v_add_co_u32_e32 v10, vcc, s29, v10
	v_mad_i64_i32 v[22:23], s[6:7], v68, s48, v[26:27]
	s_nop 0
	v_addc_co_u32_e32 v11, vcc, 0, v11, vcc
	v_lshl_add_u64 v[28:29], v[22:23], 0, v[58:59]
	v_add_co_u32_e32 v30, vcc, s49, v28
	flat_load_dwordx4 v[10:13], v[10:11] nt
	s_nop 0
	flat_load_dwordx4 v[14:17], v[18:19] offset:2048 nt
	s_nop 0
	flat_load_dwordx4 v[18:21], v[18:19] nt
	v_addc_co_u32_e32 v31, vcc, 0, v29, vcc
	flat_load_dwordx4 v[22:25], v[30:31] offset:2048 nt
	v_add_co_u32_e32 v28, vcc, s29, v28
	v_or_b32_e32 v64, 2, v52
	s_nop 0
	v_addc_co_u32_e32 v29, vcc, 0, v29, vcc
	flat_load_dwordx4 v[36:39], v[28:29] nt
	flat_load_dwordx4 v[40:43], v[30:31] nt
	v_or_b32_e32 v66, 3, v8
	v_mad_i64_i32 v[8:9], s[6:7], v64, s48, v[26:27]
	v_lshl_add_u64 v[8:9], v[8:9], 0, v[58:59]
	v_add_co_u32_e32 v28, vcc, s49, v8
	v_mad_i64_i32 v[26:27], s[6:7], v66, s48, v[26:27]
	s_nop 0
	v_addc_co_u32_e32 v29, vcc, 0, v9, vcc
	v_add_co_u32_e32 v8, vcc, s29, v8
	flat_load_dwordx4 v[102:105], v[28:29] offset:2048 nt
	flat_load_dwordx4 v[106:109], v[28:29] nt
	v_addc_co_u32_e32 v9, vcc, 0, v9, vcc
	flat_load_dwordx4 v[110:113], v[8:9] nt
	v_lshl_add_u64 v[26:27], v[26:27], 0, v[58:59]
	v_add_co_u32_e32 v8, vcc, s49, v26
	v_ashrrev_i32_e32 v53, 31, v52
	s_nop 0
	v_addc_co_u32_e32 v9, vcc, 0, v27, vcc
	v_add_co_u32_e32 v26, vcc, s29, v26
	v_lshlrev_b64 v[52:53], 12, v[52:53]
	s_nop 0
	v_addc_co_u32_e32 v27, vcc, 0, v27, vcc
	flat_load_dwordx4 v[114:117], v[8:9] offset:2048 nt
	flat_load_dwordx4 v[118:121], v[26:27] nt
	flat_load_dwordx4 v[122:125], v[8:9] nt
	v_lshl_add_u64 v[52:53], s[34:35], 0, v[52:53]
	v_lshl_add_u64 v[52:53], v[52:53], 0, v[58:59]
	v_ashrrev_i32_e32 v69, 31, v68
	v_ashrrev_i32_e32 v65, 31, v64
	v_ashrrev_i32_e32 v67, 31, v66
	s_waitcnt vmcnt(0) lgkmcnt(0)
	v_lshlrev_b32_e32 v128, 16, v10
	v_and_b32_e32 v132, 0xffff0000, v10
	v_lshlrev_b32_e32 v90, 16, v11
	v_and_b32_e32 v86, 0xffff0000, v11
	v_lshlrev_b32_e32 v82, 16, v12
	v_lshlrev_b32_e32 v131, 16, v22
	v_and_b32_e32 v135, 0xffff0000, v22
	v_lshlrev_b32_e32 v93, 16, v23
	v_and_b32_e32 v89, 0xffff0000, v23
	v_lshl_add_u64 v[22:23], v[48:49], 2, s[10:11]
	v_add_co_u32_e32 v10, vcc, s29, v22
	global_load_dwordx4 v[32:35], v[22:23], off offset:16 nt
	global_load_dwordx4 v[44:47], v[22:23], off nt
	v_addc_co_u32_e32 v11, vcc, 0, v23, vcc
	global_load_dwordx4 v[28:31], v[10:11], off offset:-4096 nt
	v_lshl_add_u64 v[8:9], v[22:23], 0, s[42:43]
	v_lshlrev_b32_e32 v85, 16, v24
	v_and_b32_e32 v81, 0xffff0000, v24
	v_lshlrev_b32_e32 v77, 16, v25
	v_and_b32_e32 v73, 0xffff0000, v25
	global_load_dwordx4 v[24:27], v[8:9], off offset:16 nt
	v_lshlrev_b32_e32 v129, 16, v36
	v_and_b32_e32 v133, 0xffff0000, v36
	v_lshlrev_b32_e32 v91, 16, v37
	v_and_b32_e32 v87, 0xffff0000, v37
	v_lshlrev_b32_e32 v83, 16, v38
	v_and_b32_e32 v79, 0xffff0000, v38
	v_lshlrev_b32_e32 v75, 16, v39
	v_and_b32_e32 v71, 0xffff0000, v39
	global_load_dwordx4 v[36:39], v[10:11], off nt
	v_and_b32_e32 v78, 0xffff0000, v12
	v_lshlrev_b32_e32 v74, 16, v13
	v_and_b32_e32 v70, 0xffff0000, v13
	v_lshlrev_b32_e32 v8, 16, v102
	v_and_b32_e32 v9, 0xffff0000, v102
	v_lshlrev_b32_e32 v12, 16, v110
	v_and_b32_e32 v13, 0xffff0000, v110
	v_lshlrev_b32_e32 v130, 16, v14
	v_and_b32_e32 v134, 0xffff0000, v14
	v_lshlrev_b32_e32 v92, 16, v15
	v_and_b32_e32 v88, 0xffff0000, v15
	v_pk_mul_f32 v[8:9], v[8:9], v[12:13]
	v_lshlrev_b32_e32 v12, 16, v103
	v_and_b32_e32 v13, 0xffff0000, v103
	v_lshlrev_b32_e32 v14, 16, v111
	v_and_b32_e32 v15, 0xffff0000, v111
	v_pk_mul_f32 v[10:11], v[12:13], v[14:15]
	v_lshlrev_b32_e32 v12, 16, v104
	v_and_b32_e32 v13, 0xffff0000, v104
	v_lshlrev_b32_e32 v14, 16, v112
	v_and_b32_e32 v15, 0xffff0000, v112
	v_lshlrev_b32_e32 v84, 16, v16
	v_and_b32_e32 v80, 0xffff0000, v16
	v_lshlrev_b32_e32 v76, 16, v17
	v_and_b32_e32 v72, 0xffff0000, v17
	v_pk_mul_f32 v[12:13], v[12:13], v[14:15]
	v_lshlrev_b32_e32 v14, 16, v105
	v_and_b32_e32 v15, 0xffff0000, v105
	v_lshlrev_b32_e32 v16, 16, v113
	v_and_b32_e32 v17, 0xffff0000, v113
	v_lshlrev_b32_e32 v51, 16, v18
	v_and_b32_e32 v101, 0xffff0000, v18
	v_lshlrev_b32_e32 v136, 16, v19
	v_and_b32_e32 v137, 0xffff0000, v19
	v_pk_mul_f32 v[14:15], v[14:15], v[16:17]
	v_lshlrev_b32_e32 v16, 16, v114
	v_and_b32_e32 v17, 0xffff0000, v114
	v_lshlrev_b32_e32 v18, 16, v118
	v_and_b32_e32 v19, 0xffff0000, v118
	v_lshlrev_b32_e32 v138, 16, v20
	v_and_b32_e32 v139, 0xffff0000, v20
	v_lshlrev_b32_e32 v140, 16, v21
	v_and_b32_e32 v141, 0xffff0000, v21
	v_pk_mul_f32 v[16:17], v[16:17], v[18:19]
	v_lshlrev_b32_e32 v18, 16, v115
	v_and_b32_e32 v19, 0xffff0000, v115
	v_lshlrev_b32_e32 v20, 16, v119
	v_and_b32_e32 v21, 0xffff0000, v119
	v_lshlrev_b32_e32 v142, 16, v40
	v_and_b32_e32 v143, 0xffff0000, v40
	v_lshlrev_b32_e32 v144, 16, v41
	v_and_b32_e32 v145, 0xffff0000, v41
	v_pk_mul_f32 v[18:19], v[18:19], v[20:21]
	v_lshlrev_b32_e32 v20, 16, v116
	v_and_b32_e32 v21, 0xffff0000, v116
	v_lshlrev_b32_e32 v40, 16, v120
	v_and_b32_e32 v41, 0xffff0000, v120
	v_lshl_add_u64 v[22:23], v[22:23], 0, s[44:45]
	v_lshlrev_b32_e32 v146, 16, v42
	v_and_b32_e32 v147, 0xffff0000, v42
	v_lshlrev_b32_e32 v148, 16, v43
	v_and_b32_e32 v149, 0xffff0000, v43
	v_pk_mul_f32 v[20:21], v[20:21], v[40:41]
	global_load_dwordx4 v[40:43], v[22:23], off offset:16 nt
	v_lshlrev_b32_e32 v22, 16, v117
	v_and_b32_e32 v23, 0xffff0000, v117
	v_lshlrev_b32_e32 v102, 16, v121
	v_and_b32_e32 v103, 0xffff0000, v121
	v_pk_mul_f32 v[22:23], v[22:23], v[102:103]
	s_waitcnt vmcnt(4)
	v_mov_b32_e32 v102, v44
	s_waitcnt vmcnt(3)
	v_mov_b32_e32 v103, v28
	v_pk_mul_f32 v[102:103], v[62:63], v[102:103]
	v_mov_b32_e32 v104, v28
	v_add_f32_e32 v62, v102, v103
	v_mov_b32_e32 v102, v45
	v_mov_b32_e32 v103, v29
	v_pk_mul_f32 v[102:103], v[4:5], v[102:103]
	v_pk_mul_f32 v[90:91], v[90:91], v[92:93]
	v_add_f32_e32 v4, v102, v103
	v_mov_b32_e32 v102, v46
	v_mov_b32_e32 v103, v30
	v_pk_mul_f32 v[102:103], v[60:61], v[102:103]
	s_waitcnt vmcnt(1)
	v_mov_b32_e32 v105, v36
	v_add_f32_e32 v60, v102, v103
	v_mov_b32_e32 v102, v47
	v_mov_b32_e32 v103, v31
	v_pk_mul_f32 v[102:103], v[6:7], v[102:103]
	v_mov_b32_e32 v92, v30
	v_add_f32_e32 v6, v102, v103
	v_mov_b32_e32 v102, v32
	v_mov_b32_e32 v103, v24
	v_pk_mul_f32 v[102:103], v[56:57], v[102:103]
	v_mov_b32_e32 v93, v38
	v_add_f32_e32 v56, v102, v103
	v_mov_b32_e32 v102, v33
	v_mov_b32_e32 v103, v25
	v_pk_mul_f32 v[102:103], v[0:1], v[102:103]
	v_fmac_f32_e32 v60, v90, v38
	v_add_f32_e32 v0, v102, v103
	v_mov_b32_e32 v102, v34
	v_mov_b32_e32 v103, v26
	v_pk_mul_f32 v[102:103], v[54:55], v[102:103]
	v_pk_mul_f32 v[92:93], v[90:91], v[92:93]
	v_add_f32_e32 v54, v102, v103
	v_mov_b32_e32 v102, v35
	v_mov_b32_e32 v103, v27
	v_pk_mul_f32 v[102:103], v[2:3], v[102:103]
	v_pk_mul_f32 v[82:83], v[82:83], v[84:85]
	v_add_f32_e32 v2, v102, v103
	v_pk_mul_f32 v[102:103], v[128:129], v[130:131]
	v_pk_mul_f32 v[74:75], v[74:75], v[76:77]
	v_fmac_f32_e32 v62, v102, v36
	v_pk_mul_f32 v[104:105], v[102:103], v[104:105]
	v_mul_f32_e32 v51, v62, v51
	v_fma_f32 v62, v63, v44, v104
	v_add_f32_e32 v62, v62, v105
	v_mul_f32_e32 v114, v62, v142
	v_pk_mul_f32 v[62:63], v[132:133], v[134:135]
	v_mov_b32_e32 v104, v29
	v_mov_b32_e32 v105, v37
	v_pk_mul_f32 v[104:105], v[62:63], v[104:105]
	v_fmac_f32_e32 v4, v62, v37
	v_fma_f32 v5, v5, v45, v104
	v_mul_f32_e32 v4, v4, v101
	v_add_f32_e32 v5, v5, v105
	v_cvt_pk_bf16_f32 v4, v51, v4
	v_mul_f32_e32 v51, v5, v143
	v_mul_f32_e32 v5, v60, v136
	v_fma_f32 v60, v61, v46, v92
	v_add_f32_e32 v60, v60, v93
	v_mul_f32_e32 v92, v60, v144
	v_pk_mul_f32 v[60:61], v[86:87], v[88:89]
	v_mov_b32_e32 v86, v31
	v_fmac_f32_e32 v6, v60, v39
	v_mov_b32_e32 v87, v39
	v_mul_f32_e32 v6, v6, v137
	v_pk_mul_f32 v[86:87], v[60:61], v[86:87]
	v_cvt_pk_bf16_f32 v5, v5, v6
	v_lshlrev_b32_e32 v150, 16, v106
	v_fma_f32 v6, v7, v47, v86
	v_add_f32_e32 v6, v6, v87
	v_mul_f32_e32 v86, v6, v145
	v_mov_b32_e32 v6, v24
	s_waitcnt vmcnt(0)
	v_mov_b32_e32 v7, v40
	v_fmac_f32_e32 v56, v82, v40
	v_pk_mul_f32 v[6:7], v[82:83], v[6:7]
	v_mul_f32_e32 v84, v56, v138
	v_fma_f32 v6, v57, v32, v6
	v_pk_mul_f32 v[56:57], v[78:79], v[80:81]
	v_mov_b32_e32 v78, v25
	v_fmac_f32_e32 v0, v56, v41
	v_mov_b32_e32 v79, v41
	v_add_f32_e32 v6, v6, v7
	v_mul_f32_e32 v0, v0, v139
	v_pk_mul_f32 v[78:79], v[56:57], v[78:79]
	v_mul_f32_e32 v85, v6, v146
	v_cvt_pk_bf16_f32 v6, v84, v0
	v_fma_f32 v0, v1, v33, v78
	v_add_f32_e32 v0, v0, v79
	v_mul_f32_e32 v78, v0, v147
	v_mov_b32_e32 v0, v26
	v_mov_b32_e32 v1, v42
	v_fmac_f32_e32 v54, v74, v42
	v_pk_mul_f32 v[0:1], v[74:75], v[0:1]
	v_mul_f32_e32 v7, v54, v140
	v_fma_f32 v0, v55, v34, v0
	v_pk_mul_f32 v[54:55], v[70:71], v[72:73]
	v_add_f32_e32 v0, v0, v1
	v_fmac_f32_e32 v2, v54, v43
	v_mul_f32_e32 v76, v0, v148
	v_mul_f32_e32 v0, v2, v141
	v_cvt_pk_bf16_f32 v7, v7, v0
	v_add_co_u32_e32 v0, vcc, s50, v52
	v_and_b32_e32 v106, 0xffff0000, v106
	s_nop 0
	v_addc_co_u32_e32 v1, vcc, 0, v53, vcc
	flat_store_dwordx4 v[0:1], v[4:7] offset:2048
	v_mov_b32_e32 v0, v27
	v_mov_b32_e32 v1, v43
	v_lshlrev_b64 v[4:5], 12, v[68:69]
	v_pk_mul_f32 v[0:1], v[54:55], v[0:1]
	v_lshl_add_u64 v[4:5], s[34:35], 0, v[4:5]
	v_fma_f32 v0, v3, v35, v0
	v_lshl_add_u64 v[4:5], v[4:5], 0, v[58:59]
	v_add_f32_e32 v0, v0, v1
	v_add_co_u32_e32 v4, vcc, s50, v4
	v_mul_f32_e32 v3, v0, v149
	v_cvt_pk_bf16_f32 v0, v114, v51
	v_cvt_pk_bf16_f32 v1, v92, v86
	s_nop 0
	v_addc_co_u32_e32 v5, vcc, 0, v5, vcc
	v_cvt_pk_bf16_f32 v2, v85, v78
	v_cvt_pk_bf16_f32 v3, v76, v3
	flat_store_dwordx4 v[4:5], v[0:3] offset:2048
	v_mov_b32_e32 v4, v44
	v_mov_b32_e32 v5, v36
	v_mov_b32_e32 v0, v102
	v_mov_b32_e32 v1, v8
	v_pk_mul_f32 v[0:1], v[0:1], v[4:5]
	v_mov_b32_e32 v36, v45
	v_fma_f32 v0, v103, v28, v0
	v_add_f32_e32 v0, v0, v1
	v_mul_f32_e32 v2, v0, v150
	v_mov_b32_e32 v0, v62
	v_mov_b32_e32 v1, v9
	v_pk_mul_f32 v[0:1], v[0:1], v[36:37]
	v_mov_b32_e32 v6, v46
	v_fma_f32 v0, v63, v29, v0
	v_add_f32_e32 v0, v0, v1
	v_mul_f32_e32 v3, v0, v106
	v_mov_b32_e32 v0, v90
	v_mov_b32_e32 v1, v10
	v_mov_b32_e32 v7, v38
	v_pk_mul_f32 v[0:1], v[0:1], v[6:7]
	v_lshlrev_b32_e32 v151, 16, v107
	v_fma_f32 v0, v91, v30, v0
	v_add_f32_e32 v0, v0, v1
	v_mul_f32_e32 v46, v0, v151
	v_mov_b32_e32 v0, v60
	v_mov_b32_e32 v1, v11
	v_mov_b32_e32 v38, v47
	v_pk_mul_f32 v[0:1], v[0:1], v[38:39]
	v_and_b32_e32 v107, 0xffff0000, v107
	v_fma_f32 v0, v61, v31, v0
	v_add_f32_e32 v0, v0, v1
	v_mul_f32_e32 v47, v0, v107
	v_mov_b32_e32 v0, v82
	v_mov_b32_e32 v1, v12
	v_mov_b32_e32 v44, v32
	v_mov_b32_e32 v45, v40
	v_pk_mul_f32 v[0:1], v[0:1], v[44:45]
	v_lshlrev_b32_e32 v152, 16, v108
	v_fma_f32 v0, v83, v24, v0
	v_add_f32_e32 v0, v0, v1
	v_mul_f32_e32 v51, v0, v152
	v_mov_b32_e32 v0, v56
	v_mov_b32_e32 v1, v13
	v_mov_b32_e32 v40, v33
	v_pk_mul_f32 v[0:1], v[0:1], v[40:41]
	v_and_b32_e32 v108, 0xffff0000, v108
	v_fma_f32 v0, v57, v25, v0
	v_add_f32_e32 v0, v0, v1
	v_mul_f32_e32 v52, v0, v108
	v_mov_b32_e32 v0, v74
	v_mov_b32_e32 v1, v14
	v_mov_b32_e32 v32, v34
	v_mov_b32_e32 v33, v42
	v_pk_mul_f32 v[0:1], v[0:1], v[32:33]
	v_lshlrev_b32_e32 v153, 16, v109
	v_fma_f32 v0, v75, v26, v0
	v_add_f32_e32 v0, v0, v1
	v_mul_f32_e32 v34, v0, v153
	v_mov_b32_e32 v0, v54
	v_mov_b32_e32 v1, v15
	v_mov_b32_e32 v42, v35
	v_pk_mul_f32 v[0:1], v[0:1], v[42:43]
	v_and_b32_e32 v109, 0xffff0000, v109
	v_fma_f32 v0, v55, v27, v0
	v_add_f32_e32 v0, v0, v1
	v_mul_f32_e32 v35, v0, v109
	v_cvt_pk_bf16_f32 v0, v2, v3
	v_cvt_pk_bf16_f32 v1, v46, v47
	v_cvt_pk_bf16_f32 v2, v51, v52
	v_cvt_pk_bf16_f32 v3, v34, v35
	v_lshlrev_b64 v[34:35], 12, v[64:65]
	v_lshl_add_u64 v[34:35], s[34:35], 0, v[34:35]
	v_lshl_add_u64 v[34:35], v[34:35], 0, v[58:59]
	v_add_co_u32_e32 v34, vcc, s50, v34
	v_lshlrev_b32_e32 v110, 16, v122
	s_nop 0
	v_addc_co_u32_e32 v35, vcc, 0, v35, vcc
	flat_store_dwordx4 v[34:35], v[0:3] offset:2048
	v_and_b32_e32 v111, 0xffff0000, v122
	v_lshlrev_b32_e32 v112, 16, v123
	v_pk_mov_b32 v[0:1], v[102:103], v[16:17] op_sel:[1,0]
	v_and_b32_e32 v113, 0xffff0000, v123
	v_pk_mul_f32 v[0:1], v[0:1], v[4:5]
	v_lshlrev_b32_e32 v122, 16, v124
	v_fma_f32 v0, v8, v28, v0
	v_add_f32_e32 v0, v0, v1
	v_mul_f32_e32 v2, v0, v110
	v_mov_b32_e32 v0, v63
	v_mov_b32_e32 v1, v17
	v_pk_mul_f32 v[0:1], v[0:1], v[36:37]
	v_and_b32_e32 v123, 0xffff0000, v124
	v_fma_f32 v0, v9, v29, v0
	v_add_f32_e32 v0, v0, v1
	v_mul_f32_e32 v3, v0, v111
	v_pk_mov_b32 v[0:1], v[90:91], v[18:19] op_sel:[1,0]
	v_lshlrev_b32_e32 v124, 16, v125
	v_pk_mul_f32 v[0:1], v[0:1], v[6:7]
	v_and_b32_e32 v125, 0xffff0000, v125
	v_fma_f32 v0, v10, v30, v0
	v_add_f32_e32 v0, v0, v1
	v_mul_f32_e32 v4, v0, v112
	v_mov_b32_e32 v0, v61
	v_mov_b32_e32 v1, v19
	v_pk_mul_f32 v[0:1], v[0:1], v[38:39]
	s_nop 0
	v_fma_f32 v0, v11, v31, v0
	v_add_f32_e32 v0, v0, v1
	v_mul_f32_e32 v5, v0, v113
	v_pk_mov_b32 v[0:1], v[82:83], v[20:21] op_sel:[1,0]
	s_nop 0
	v_pk_mul_f32 v[0:1], v[0:1], v[44:45]
	s_nop 0
	v_fma_f32 v0, v12, v24, v0
	v_add_f32_e32 v0, v0, v1
	v_mul_f32_e32 v6, v0, v122
	v_mov_b32_e32 v0, v57
	v_mov_b32_e32 v1, v21
	v_pk_mul_f32 v[0:1], v[0:1], v[40:41]
	s_nop 0
	v_fma_f32 v0, v13, v25, v0
	v_add_f32_e32 v0, v0, v1
	v_mul_f32_e32 v7, v0, v123
	v_pk_mov_b32 v[0:1], v[74:75], v[22:23] op_sel:[1,0]
	s_nop 0
	v_pk_mul_f32 v[0:1], v[0:1], v[32:33]
	s_nop 0
	v_fma_f32 v0, v14, v26, v0
	v_add_f32_e32 v0, v0, v1
	v_mul_f32_e32 v24, v0, v124
	v_mov_b32_e32 v0, v55
	v_mov_b32_e32 v1, v23
	v_pk_mul_f32 v[0:1], v[0:1], v[42:43]
	s_nop 0
	v_fma_f32 v0, v15, v27, v0
	v_add_f32_e32 v0, v0, v1
	v_mul_f32_e32 v25, v0, v125
	v_cvt_pk_bf16_f32 v0, v2, v3
	v_cvt_pk_bf16_f32 v1, v4, v5
	v_lshlrev_b64 v[4:5], 12, v[66:67]
	v_lshl_add_u64 v[4:5], s[34:35], 0, v[4:5]
	v_lshl_add_u64 v[4:5], v[4:5], 0, v[58:59]
	v_add_co_u32_e32 v4, vcc, 0x17200000, v4
	v_cvt_pk_bf16_f32 v2, v6, v7
	v_cvt_pk_bf16_f32 v3, v24, v25
	s_nop 1
	v_addc_co_u32_e32 v5, vcc, 0, v5, vcc
	v_cmp_eq_u32_e32 vcc, v100, v99
	flat_store_dwordx4 v[4:5], v[0:3] offset:2048
	s_and_saveexec_b64 s[6:7], vcc
	s_cbranch_execz .LBB0_329
	s_mov_b64 vcc, s[4:5]
	v_ashrrev_i32_e32 v0, 16, v94
	v_cndmask_b32_e32 v0, v50, v0, vcc
	v_cndmask_b32_e64 v2, v97, v98, s[4:5]
	v_mov_b32_e32 v3, v49
	v_ashrrev_i32_e32 v1, 31, v0
	v_lshl_add_u64 v[2:3], s[20:21], 0, v[2:3]
	v_lshlrev_b64 v[0:1], 13, v[0:1]
	v_lshl_add_u64 v[0:1], v[2:3], 0, v[0:1]
	v_lshl_add_u64 v[0:1], v[48:49], 2, v[0:1]
	flat_store_dwordx4 v[0:1], v[8:11]
	flat_store_dwordx4 v[0:1], v[12:15] offset:16
	v_add_co_u32_e32 v0, vcc, 0x1000, v0
	s_nop 1
	v_addc_co_u32_e32 v1, vcc, 0, v1, vcc
	flat_store_dwordx4 v[0:1], v[16:19]
	flat_store_dwordx4 v[0:1], v[20:23] offset:16
	s_branch .LBB0_329

.LBB0_342:
	s_and_b32 s56, s29, -8
	s_mul_i32 s3, s56, 0x4800
	s_add_i32 s50, s56, 0x2000
	s_ashr_i32 s51, s50, 31
	s_add_i32 s5, s3, 0x9000000
	s_mul_hi_i32 s4, s50, 0x4800
	s_add_u32 s52, s14, s5
	s_addc_u32 s53, s15, s4
	v_lshl_add_u64 v[24:25], s[52:53], 0, v[78:79]
	v_add_co_u32_e32 v12, vcc, s64, v24
	flat_load_dwordx4 v[0:3], v[24:25] offset:2048 nt
	flat_load_dwordx4 v[4:7], v[24:25] offset:3072 nt
	v_addc_co_u32_e32 v13, vcc, 0, v25, vcc
	flat_load_dwordx4 v[8:11], v[12:13] nt
	s_nop 0
	flat_load_dwordx4 v[12:15], v[12:13] offset:1024 nt
	v_add_co_u32_e32 v20, vcc, s65, v24
	s_add_i32 s48, s56, 0x2004
	s_nop 0
	v_addc_co_u32_e32 v21, vcc, 0, v25, vcc
	v_add_co_u32_e32 v28, vcc, s66, v24
	flat_load_dwordx4 v[16:19], v[20:21] offset:2048 nt
	s_nop 0
	flat_load_dwordx4 v[20:23], v[20:21] offset:3072 nt
	v_addc_co_u32_e32 v29, vcc, 0, v25, vcc
	flat_load_dwordx4 v[24:27], v[28:29] nt
	s_nop 0
	flat_load_dwordx4 v[28:31], v[28:29] offset:1024 nt
	s_ashr_i32 s57, s56, 31
	s_ashr_i32 s49, s48, 31
	s_add_i32 s55, s3, 0x9012000
	s_mul_hi_i32 s54, s48, 0x4800
	s_waitcnt vmcnt(0) lgkmcnt(0)
	v_lshlrev_b32_e32 v65, 16, v0
	v_and_b32_e32 v67, 0xffff0000, v0
	v_lshlrev_b32_e32 v69, 16, v1
	v_lshlrev_b32_e32 v64, 16, v8
	v_and_b32_e32 v66, 0xffff0000, v8
	v_lshlrev_b32_e32 v68, 16, v9
	v_and_b32_e32 v70, 0xffff0000, v9
	v_lshlrev_b32_e32 v8, 16, v12
	v_lshlrev_b32_e32 v9, 16, v4
	v_and_b32_e32 v71, 0xffff0000, v1
	v_and_b32_e32 v83, 0xffff0000, v4
	v_and_b32_e32 v82, 0xffff0000, v12
	v_pk_add_f32 v[0:1], v[64:65], v[8:9]
	v_lshlrev_b32_e32 v84, 16, v13
	v_lshlrev_b32_e32 v85, 16, v5
	v_and_b32_e32 v4, 0xffff0000, v13
	v_pk_add_f32 v[0:1], v[0:1], 0 op_sel_hi:[1,0]
	v_pk_add_f32 v[12:13], v[66:67], v[82:83]
	v_and_b32_e32 v32, 0xffff0000, v2
	v_lshlrev_b32_e32 v33, 16, v2
	v_and_b32_e32 v34, 0xffff0000, v6
	v_lshlrev_b32_e32 v35, 16, v6
	v_and_b32_e32 v40, 0xffff0000, v10
	v_lshlrev_b32_e32 v41, 16, v10
	v_and_b32_e32 v42, 0xffff0000, v14
	v_lshlrev_b32_e32 v43, 16, v14
	v_and_b32_e32 v5, 0xffff0000, v5
	v_pk_add_f32 v[0:1], v[12:13], v[0:1]
	v_pk_add_f32 v[12:13], v[68:69], v[84:85]
	v_pk_add_f32 v[36:37], v[32:33], v[34:35]
	v_pk_add_f32 v[44:45], v[40:41], v[42:43]
	v_pk_add_f32 v[0:1], v[12:13], v[0:1]
	v_pk_add_f32 v[12:13], v[70:71], v[4:5]
	v_and_b32_e32 v2, 0xffff0000, v3
	v_lshlrev_b32_e32 v3, 16, v3
	v_and_b32_e32 v6, 0xffff0000, v7
	v_lshlrev_b32_e32 v7, 16, v7
	v_and_b32_e32 v10, 0xffff0000, v11
	v_lshlrev_b32_e32 v11, 16, v11
	v_and_b32_e32 v14, 0xffff0000, v15
	v_lshlrev_b32_e32 v15, 16, v15
	v_pk_add_f32 v[0:1], v[12:13], v[0:1]
	v_mov_b32_e32 v12, v45
	v_mov_b32_e32 v13, v37
	v_pk_add_f32 v[38:39], v[2:3], v[6:7]
	v_pk_add_f32 v[46:47], v[10:11], v[14:15]
	v_pk_add_f32 v[0:1], v[12:13], v[0:1]
	v_mov_b32_e32 v45, v36
	v_pk_add_f32 v[0:1], v[44:45], v[0:1]
	v_mov_b32_e32 v12, v47
	v_mov_b32_e32 v13, v39
	v_pk_add_f32 v[0:1], v[12:13], v[0:1]
	v_mov_b32_e32 v47, v38
	v_pk_add_f32 v[0:1], v[46:47], v[0:1]
	ds_bpermute_b32 v13, v128, v1
	ds_bpermute_b32 v12, v128, v0
	v_and_b32_e32 v37, 0xffff0000, v20
	v_and_b32_e32 v36, 0xffff0000, v28
	v_lshlrev_b32_e32 v39, 16, v21
	v_lshlrev_b32_e32 v38, 16, v29
	s_waitcnt lgkmcnt(0)
	v_pk_add_f32 v[0:1], v[0:1], v[12:13]
	ds_bpermute_b32 v13, v129, v1
	ds_bpermute_b32 v12, v129, v0
	v_and_b32_e32 v48, 0xffff0000, v18
	v_lshlrev_b32_e32 v49, 16, v18
	v_and_b32_e32 v50, 0xffff0000, v22
	v_lshlrev_b32_e32 v51, 16, v22
	s_waitcnt lgkmcnt(0)
	v_pk_add_f32 v[0:1], v[0:1], v[12:13]
	ds_bpermute_b32 v13, v130, v1
	ds_bpermute_b32 v12, v130, v0
	v_and_b32_e32 v56, 0xffff0000, v26
	v_lshlrev_b32_e32 v57, 16, v26
	v_and_b32_e32 v58, 0xffff0000, v30
	v_lshlrev_b32_e32 v59, 16, v30
	s_waitcnt lgkmcnt(0)
	v_pk_add_f32 v[0:1], v[0:1], v[12:13]
	ds_bpermute_b32 v13, v131, v1
	ds_bpermute_b32 v12, v131, v0
	v_and_b32_e32 v21, 0xffff0000, v21
	v_pk_add_f32 v[52:53], v[48:49], v[50:51]
	v_pk_add_f32 v[60:61], v[56:57], v[58:59]
	v_and_b32_e32 v18, 0xffff0000, v19
	s_waitcnt lgkmcnt(0)
	v_pk_add_f32 v[0:1], v[0:1], v[12:13]
	ds_bpermute_b32 v13, v132, v1
	ds_bpermute_b32 v12, v132, v0
	v_lshlrev_b32_e32 v19, 16, v19
	v_and_b32_e32 v22, 0xffff0000, v23
	v_lshlrev_b32_e32 v23, 16, v23
	v_and_b32_e32 v26, 0xffff0000, v27
	s_waitcnt lgkmcnt(0)
	v_pk_add_f32 v[0:1], v[0:1], v[12:13]
	ds_bpermute_b32 v13, v133, v1
	ds_bpermute_b32 v12, v133, v0
	v_lshlrev_b32_e32 v27, 16, v27
	v_and_b32_e32 v30, 0xffff0000, v31
	v_lshlrev_b32_e32 v31, 16, v31
	v_pk_add_f32 v[54:55], v[18:19], v[22:23]
	s_waitcnt lgkmcnt(0)
	v_pk_add_f32 v[12:13], v[0:1], v[12:13]
	v_pk_add_f32 v[62:63], v[26:27], v[30:31]
	v_pk_mul_f32 v[0:1], v[12:13], s[46:47] op_sel_hi:[1,0]
	v_pk_fma_f32 v[8:9], v[12:13], s[46:47], v[8:9] op_sel_hi:[1,0,1] neg_lo:[1,0,0] neg_hi:[1,0,0]
	v_pk_add_f32 v[34:35], v[34:35], v[0:1] op_sel:[0,1] neg_lo:[0,1] neg_hi:[0,1]
	v_pk_add_f32 v[6:7], v[6:7], v[0:1] op_sel:[0,1] neg_lo:[0,1] neg_hi:[0,1]
	v_pk_add_f32 v[32:33], v[32:33], v[0:1] op_sel:[0,1] neg_lo:[0,1] neg_hi:[0,1]
	v_pk_mul_f32 v[34:35], v[34:35], v[34:35]
	v_pk_add_f32 v[2:3], v[2:3], v[0:1] op_sel:[0,1] neg_lo:[0,1] neg_hi:[0,1]
	v_pk_mul_f32 v[6:7], v[6:7], v[6:7]
	v_pk_fma_f32 v[32:33], v[32:33], v[32:33], v[34:35]
	v_pk_fma_f32 v[6:7], v[2:3], v[2:3], v[6:7]
	v_pk_fma_f32 v[2:3], v[12:13], s[46:47], v[64:65] op_sel_hi:[1,0,1] neg_lo:[1,0,0] neg_hi:[1,0,0]
	v_pk_mul_f32 v[8:9], v[8:9], v[8:9]
	v_pk_fma_f32 v[34:35], v[12:13], s[46:47], v[82:83] op_sel_hi:[1,0,1] neg_lo:[1,0,0] neg_hi:[1,0,0]
	v_pk_fma_f32 v[2:3], v[2:3], v[2:3], v[8:9]
	v_pk_fma_f32 v[8:9], v[12:13], s[46:47], v[66:67] op_sel_hi:[1,0,1] neg_lo:[1,0,0] neg_hi:[1,0,0]
	v_pk_mul_f32 v[34:35], v[34:35], v[34:35]
	v_pk_fma_f32 v[4:5], v[12:13], s[46:47], v[4:5] op_sel_hi:[1,0,1] neg_lo:[1,0,0] neg_hi:[1,0,0]
	v_pk_fma_f32 v[8:9], v[8:9], v[8:9], v[34:35]
	v_pk_fma_f32 v[34:35], v[12:13], s[46:47], v[84:85] op_sel_hi:[1,0,1] neg_lo:[1,0,0] neg_hi:[1,0,0]
	v_pk_add_f32 v[2:3], v[2:3], v[8:9]
	v_pk_fma_f32 v[8:9], v[12:13], s[46:47], v[68:69] op_sel_hi:[1,0,1] neg_lo:[1,0,0] neg_hi:[1,0,0]
	v_pk_mul_f32 v[34:35], v[34:35], v[34:35]
	v_pk_mul_f32 v[4:5], v[4:5], v[4:5]
	v_pk_fma_f32 v[8:9], v[8:9], v[8:9], v[34:35]
	v_lshlrev_b32_e32 v34, 16, v25
	v_pk_add_f32 v[2:3], v[8:9], v[2:3]
	v_pk_fma_f32 v[8:9], v[12:13], s[46:47], v[70:71] op_sel_hi:[1,0,1] neg_lo:[1,0,0] neg_hi:[1,0,0]
	v_lshlrev_b32_e32 v13, 16, v16
	v_pk_fma_f32 v[4:5], v[8:9], v[8:9], v[4:5]
	v_pk_add_f32 v[8:9], v[42:43], v[0:1] op_sel_hi:[1,0] neg_lo:[0,1] neg_hi:[0,1]
	v_pk_add_f32 v[2:3], v[4:5], v[2:3]
	v_pk_add_f32 v[4:5], v[40:41], v[0:1] op_sel_hi:[1,0] neg_lo:[0,1] neg_hi:[0,1]
	v_pk_mul_f32 v[8:9], v[8:9], v[8:9]
	v_lshlrev_b32_e32 v12, 16, v24
	v_pk_fma_f32 v[4:5], v[4:5], v[4:5], v[8:9]
	v_mov_b32_e32 v9, v33
	v_mov_b32_e32 v8, v5
	v_pk_add_f32 v[8:9], v[8:9], v[2:3]
	v_pk_add_f32 v[2:3], v[10:11], v[0:1] op_sel_hi:[1,0] neg_lo:[0,1] neg_hi:[0,1]
	v_pk_add_f32 v[10:11], v[14:15], v[0:1] op_sel_hi:[1,0] neg_lo:[0,1] neg_hi:[0,1]
	v_and_b32_e32 v15, 0xffff0000, v16
	v_pk_mul_f32 v[10:11], v[10:11], v[10:11]
	v_and_b32_e32 v14, 0xffff0000, v24
	v_and_b32_e32 v16, 0xffff0000, v25
	v_lshlrev_b32_e32 v25, 16, v20
	v_lshlrev_b32_e32 v24, 16, v28
	v_pk_fma_f32 v[10:11], v[2:3], v[2:3], v[10:11]
	v_pk_add_f32 v[2:3], v[12:13], v[24:25]
	v_lshlrev_b32_e32 v35, 16, v17
	v_and_b32_e32 v20, 0xffff0000, v29
	v_pk_add_f32 v[2:3], v[2:3], 0 op_sel_hi:[1,0]
	v_pk_add_f32 v[28:29], v[14:15], v[36:37]
	v_and_b32_e32 v17, 0xffff0000, v17
	v_pk_add_f32 v[2:3], v[28:29], v[2:3]
	v_pk_add_f32 v[28:29], v[34:35], v[38:39]
	v_mov_b32_e32 v5, v32
	v_pk_add_f32 v[2:3], v[28:29], v[2:3]
	v_pk_add_f32 v[28:29], v[16:17], v[20:21]
	v_pk_add_f32 v[4:5], v[4:5], v[8:9]
	v_pk_add_f32 v[2:3], v[28:29], v[2:3]
	v_mov_b32_e32 v28, v61
	v_mov_b32_e32 v29, v53
	v_pk_add_f32 v[2:3], v[28:29], v[2:3]
	v_mov_b32_e32 v61, v52
	v_pk_add_f32 v[2:3], v[60:61], v[2:3]
	v_mov_b32_e32 v28, v63
	v_mov_b32_e32 v29, v55
	v_pk_add_f32 v[2:3], v[28:29], v[2:3]
	v_mov_b32_e32 v63, v54
	v_pk_add_f32 v[2:3], v[62:63], v[2:3]
	ds_bpermute_b32 v29, v128, v3
	ds_bpermute_b32 v28, v128, v2
	v_mov_b32_e32 v8, v11
	v_mov_b32_e32 v9, v7
	v_pk_add_f32 v[4:5], v[8:9], v[4:5]
	v_mov_b32_e32 v11, v6
	v_pk_add_f32 v[4:5], v[10:11], v[4:5]
	ds_bpermute_b32 v7, v128, v5
	ds_bpermute_b32 v6, v128, v4
	s_waitcnt lgkmcnt(2)
	v_pk_add_f32 v[2:3], v[2:3], v[28:29]
	ds_bpermute_b32 v29, v129, v3
	ds_bpermute_b32 v28, v129, v2
	s_waitcnt lgkmcnt(2)
	v_pk_add_f32 v[4:5], v[4:5], v[6:7]
	ds_bpermute_b32 v7, v129, v5
	ds_bpermute_b32 v6, v129, v4
	s_waitcnt lgkmcnt(2)
	v_pk_add_f32 v[2:3], v[2:3], v[28:29]
	ds_bpermute_b32 v29, v130, v3
	ds_bpermute_b32 v28, v130, v2
	s_waitcnt lgkmcnt(2)
	v_pk_add_f32 v[4:5], v[4:5], v[6:7]
	ds_bpermute_b32 v7, v130, v5
	ds_bpermute_b32 v6, v130, v4
	s_waitcnt lgkmcnt(2)
	v_pk_add_f32 v[2:3], v[2:3], v[28:29]
	ds_bpermute_b32 v29, v131, v3
	ds_bpermute_b32 v28, v131, v2
	s_waitcnt lgkmcnt(2)
	v_pk_add_f32 v[4:5], v[4:5], v[6:7]
	ds_bpermute_b32 v7, v131, v5
	ds_bpermute_b32 v6, v131, v4
	s_waitcnt lgkmcnt(2)
	v_pk_add_f32 v[2:3], v[2:3], v[28:29]
	ds_bpermute_b32 v29, v132, v3
	ds_bpermute_b32 v28, v132, v2
	s_waitcnt lgkmcnt(2)
	v_pk_add_f32 v[4:5], v[4:5], v[6:7]
	ds_bpermute_b32 v7, v132, v5
	ds_bpermute_b32 v6, v132, v4
	s_waitcnt lgkmcnt(2)
	v_pk_add_f32 v[2:3], v[2:3], v[28:29]
	ds_bpermute_b32 v29, v133, v3
	ds_bpermute_b32 v28, v133, v2
	s_waitcnt lgkmcnt(2)
	v_pk_add_f32 v[4:5], v[4:5], v[6:7]
	ds_bpermute_b32 v7, v133, v5
	ds_bpermute_b32 v6, v133, v4
	s_waitcnt lgkmcnt(2)
	v_pk_add_f32 v[28:29], v[2:3], v[28:29]
	s_waitcnt lgkmcnt(0)
	v_pk_add_f32 v[4:5], v[4:5], v[6:7]
	v_pk_mul_f32 v[2:3], v[28:29], s[46:47] op_sel_hi:[1,0]
	v_pk_fma_f32 v[4:5], v[4:5], s[46:47], v[80:81] op_sel_hi:[1,0,0]
	v_pk_add_f32 v[22:23], v[22:23], v[2:3] op_sel:[0,1] neg_lo:[0,1] neg_hi:[0,1]
	v_pk_add_f32 v[18:19], v[18:19], v[2:3] op_sel:[0,1] neg_lo:[0,1] neg_hi:[0,1]
	v_pk_mul_f32 v[22:23], v[22:23], v[22:23]
	v_pk_fma_f32 v[12:13], v[28:29], s[46:47], v[12:13] op_sel_hi:[1,0,1] neg_lo:[1,0,0] neg_hi:[1,0,0]
	v_pk_fma_f32 v[18:19], v[18:19], v[18:19], v[22:23]
	v_pk_fma_f32 v[22:23], v[28:29], s[46:47], v[24:25] op_sel_hi:[1,0,1] neg_lo:[1,0,0] neg_hi:[1,0,0]
	v_mul_f32_e32 v6, 0x4b800000, v5
	v_pk_mul_f32 v[22:23], v[22:23], v[22:23]
	v_cmp_gt_f32_e64 s[4:5], s67, v5
	v_pk_fma_f32 v[12:13], v[12:13], v[12:13], v[22:23]
	v_pk_fma_f32 v[22:23], v[28:29], s[46:47], v[36:37] op_sel_hi:[1,0,1] neg_lo:[1,0,0] neg_hi:[1,0,0]
	v_cndmask_b32_e64 v5, v5, v6, s[4:5]
	v_pk_fma_f32 v[14:15], v[28:29], s[46:47], v[14:15] op_sel_hi:[1,0,1] neg_lo:[1,0,0] neg_hi:[1,0,0]
	v_pk_mul_f32 v[22:23], v[22:23], v[22:23]
	v_rsq_f32_e32 v5, v5
	v_pk_fma_f32 v[14:15], v[14:15], v[14:15], v[22:23]
	v_pk_fma_f32 v[22:23], v[28:29], s[46:47], v[38:39] op_sel_hi:[1,0,1] neg_lo:[1,0,0] neg_hi:[1,0,0]
	v_pk_add_f32 v[12:13], v[12:13], v[14:15]
	v_pk_fma_f32 v[14:15], v[28:29], s[46:47], v[34:35] op_sel_hi:[1,0,1] neg_lo:[1,0,0] neg_hi:[1,0,0]
	v_pk_mul_f32 v[22:23], v[22:23], v[22:23]
	v_mul_f32_e32 v6, 0x45800000, v5
	v_pk_fma_f32 v[14:15], v[14:15], v[14:15], v[22:23]
	v_cmp_gt_f32_e32 vcc, s67, v4
	v_pk_add_f32 v[12:13], v[14:15], v[12:13]
	v_pk_fma_f32 v[14:15], v[28:29], s[46:47], v[16:17] op_sel_hi:[1,0,1] neg_lo:[1,0,0] neg_hi:[1,0,0]
	v_pk_fma_f32 v[16:17], v[28:29], s[46:47], v[20:21] op_sel_hi:[1,0,1] neg_lo:[1,0,0] neg_hi:[1,0,0]
	v_cndmask_b32_e64 v22, v5, v6, s[4:5]
	v_pk_mul_f32 v[16:17], v[16:17], v[16:17]
	v_mul_f32_e32 v5, 0x4b800000, v4
	v_pk_add_f32 v[42:43], v[50:51], v[2:3] op_sel:[0,1] neg_lo:[0,1] neg_hi:[0,1]
	v_pk_fma_f32 v[14:15], v[14:15], v[14:15], v[16:17]
	v_pk_add_f32 v[16:17], v[58:59], v[2:3] op_sel_hi:[1,0] neg_lo:[0,1] neg_hi:[0,1]
	v_cndmask_b32_e32 v4, v4, v5, vcc
	v_pk_add_f32 v[40:41], v[48:49], v[2:3] op_sel:[0,1] neg_lo:[0,1] neg_hi:[0,1]
	v_pk_mul_f32 v[42:43], v[42:43], v[42:43]
	v_pk_add_f32 v[12:13], v[14:15], v[12:13]
	v_pk_add_f32 v[14:15], v[56:57], v[2:3] op_sel_hi:[1,0] neg_lo:[0,1] neg_hi:[0,1]
	v_pk_mul_f32 v[16:17], v[16:17], v[16:17]
	v_rsq_f32_e32 v4, v4
	v_pk_fma_f32 v[40:41], v[40:41], v[40:41], v[42:43]
	v_pk_fma_f32 v[14:15], v[14:15], v[14:15], v[16:17]
	v_mov_b32_e32 v17, v41
	v_mov_b32_e32 v16, v15
	v_pk_add_f32 v[20:21], v[30:31], v[2:3] op_sel_hi:[1,0] neg_lo:[0,1] neg_hi:[0,1]
	v_pk_add_f32 v[12:13], v[16:17], v[12:13]
	v_pk_add_f32 v[16:17], v[26:27], v[2:3] op_sel_hi:[1,0] neg_lo:[0,1] neg_hi:[0,1]
	v_pk_mul_f32 v[20:21], v[20:21], v[20:21]
	v_mul_f32_e32 v5, 0x45800000, v4
	v_pk_fma_f32 v[16:17], v[16:17], v[16:17], v[20:21]
	v_mov_b32_e32 v15, v40
	v_cndmask_b32_e32 v24, v4, v5, vcc
	v_pk_add_f32 v[4:5], v[14:15], v[12:13]
	v_mov_b32_e32 v6, v17
	v_mov_b32_e32 v7, v19
	v_pk_add_f32 v[4:5], v[6:7], v[4:5]
	v_mov_b32_e32 v17, v18
	v_pk_add_f32 v[4:5], v[16:17], v[4:5]
	ds_bpermute_b32 v7, v128, v5
	ds_bpermute_b32 v6, v128, v4
	s_waitcnt lgkmcnt(0)
	v_pk_add_f32 v[4:5], v[4:5], v[6:7]
	ds_bpermute_b32 v7, v129, v5
	ds_bpermute_b32 v6, v129, v4
	s_waitcnt lgkmcnt(0)
	v_pk_add_f32 v[4:5], v[4:5], v[6:7]
	ds_bpermute_b32 v7, v130, v5
	ds_bpermute_b32 v6, v130, v4
	s_waitcnt lgkmcnt(0)
	v_pk_add_f32 v[4:5], v[4:5], v[6:7]
	ds_bpermute_b32 v7, v131, v5
	ds_bpermute_b32 v6, v131, v4
	s_waitcnt lgkmcnt(0)
	v_pk_add_f32 v[4:5], v[4:5], v[6:7]
	ds_bpermute_b32 v7, v132, v5
	ds_bpermute_b32 v6, v132, v4
	s_waitcnt lgkmcnt(0)
	v_pk_add_f32 v[4:5], v[4:5], v[6:7]
	ds_bpermute_b32 v7, v133, v5
	ds_bpermute_b32 v6, v133, v4
	s_waitcnt lgkmcnt(0)
	v_pk_add_f32 v[4:5], v[4:5], v[6:7]
	s_nop 0
	v_pk_fma_f32 v[4:5], v[4:5], s[46:47], v[80:81] op_sel_hi:[1,0,0]
	s_nop 0
	v_mul_f32_e32 v6, 0x4b800000, v5
	v_cmp_gt_f32_e64 s[4:5], s67, v5
	v_cmp_gt_f32_e32 vcc, s67, v4
	s_nop 0
	v_cndmask_b32_e64 v5, v5, v6, s[4:5]
	v_rsq_f32_e32 v5, v5
	s_nop 0
	v_mul_f32_e32 v6, 0x45800000, v5
	v_cndmask_b32_e64 v6, v5, v6, s[4:5]
	v_mul_f32_e32 v5, 0x4b800000, v4
	v_cndmask_b32_e32 v4, v4, v5, vcc
	v_rsq_f32_e32 v4, v4
	v_mad_i64_i32 v[20:21], s[4:5], s48, v134, v[76:77]
	flat_load_dwordx4 v[8:11], v[20:21] offset:2048 nt
	flat_load_dwordx4 v[12:15], v[20:21] offset:3072 nt
	v_mul_f32_e32 v5, 0x45800000, v4
	v_cndmask_b32_e32 v4, v4, v5, vcc
	v_add_co_u32_e32 v26, vcc, s64, v20
	s_waitcnt vmcnt(0) lgkmcnt(0)
	v_lshlrev_b32_e32 v87, 16, v8
	v_addc_co_u32_e32 v27, vcc, 0, v21, vcc
	flat_load_dwordx4 v[16:19], v[26:27] nt
	s_nop 0
	flat_load_dwordx4 v[26:29], v[26:27] offset:1024 nt
	v_add_co_u32_e32 v34, vcc, s65, v20
	v_and_b32_e32 v89, 0xffff0000, v8
	s_nop 0
	v_addc_co_u32_e32 v35, vcc, 0, v21, vcc
	v_add_co_u32_e32 v20, vcc, s66, v20
	flat_load_dwordx4 v[30:33], v[34:35] offset:2048 nt
	s_nop 0
	flat_load_dwordx4 v[34:37], v[34:35] offset:3072 nt
	v_addc_co_u32_e32 v21, vcc, 0, v21, vcc
	flat_load_dwordx4 v[38:41], v[20:21] nt
	flat_load_dwordx4 v[42:45], v[20:21] offset:1024 nt
	v_and_b32_e32 v93, 0xffff0000, v12
	v_lshlrev_b32_e32 v91, 16, v9
	v_lshlrev_b32_e32 v95, 16, v13
	v_and_b32_e32 v20, 0xffff0000, v10
	v_lshlrev_b32_e32 v21, 16, v10
	v_and_b32_e32 v46, 0xffff0000, v14
	v_lshlrev_b32_e32 v47, 16, v14
	v_and_b32_e32 v9, 0xffff0000, v9
	v_and_b32_e32 v13, 0xffff0000, v13
	v_pk_add_f32 v[48:49], v[20:21], v[46:47]
	v_and_b32_e32 v10, 0xffff0000, v11
	v_lshlrev_b32_e32 v11, 16, v11
	v_and_b32_e32 v14, 0xffff0000, v15
	v_lshlrev_b32_e32 v15, 16, v15
	v_pk_add_f32 v[50:51], v[10:11], v[14:15]
	s_waitcnt vmcnt(0) lgkmcnt(0)
	v_lshlrev_b32_e32 v86, 16, v16
	v_and_b32_e32 v88, 0xffff0000, v16
	v_lshlrev_b32_e32 v90, 16, v17
	v_and_b32_e32 v8, 0xffff0000, v17
	v_lshlrev_b32_e32 v16, 16, v26
	v_lshlrev_b32_e32 v17, 16, v12
	v_and_b32_e32 v92, 0xffff0000, v26
	v_lshlrev_b32_e32 v94, 16, v27
	v_and_b32_e32 v12, 0xffff0000, v27
	v_pk_add_f32 v[26:27], v[86:87], v[16:17]
	v_pk_add_f32 v[96:97], v[88:89], v[92:93]
	v_pk_add_f32 v[26:27], v[26:27], 0 op_sel_hi:[1,0]
	v_and_b32_e32 v52, 0xffff0000, v18
	v_lshlrev_b32_e32 v53, 16, v18
	v_and_b32_e32 v54, 0xffff0000, v28
	v_lshlrev_b32_e32 v55, 16, v28
	v_pk_add_f32 v[26:27], v[96:97], v[26:27]
	v_pk_add_f32 v[96:97], v[90:91], v[94:95]
	v_pk_add_f32 v[56:57], v[52:53], v[54:55]
	v_pk_add_f32 v[26:27], v[96:97], v[26:27]
	v_pk_add_f32 v[96:97], v[8:9], v[12:13]
	v_and_b32_e32 v18, 0xffff0000, v19
	v_lshlrev_b32_e32 v19, 16, v19
	v_and_b32_e32 v28, 0xffff0000, v29
	v_lshlrev_b32_e32 v29, 16, v29
	v_pk_add_f32 v[26:27], v[96:97], v[26:27]
	v_mov_b32_e32 v96, v57
	v_mov_b32_e32 v97, v49
	v_pk_add_f32 v[58:59], v[18:19], v[28:29]
	v_pk_add_f32 v[26:27], v[96:97], v[26:27]
	v_mov_b32_e32 v57, v48
	v_pk_add_f32 v[26:27], v[56:57], v[26:27]
	v_mov_b32_e32 v48, v59
	v_mov_b32_e32 v49, v51
	v_pk_add_f32 v[26:27], v[48:49], v[26:27]
	v_mov_b32_e32 v59, v50
	v_pk_add_f32 v[26:27], v[58:59], v[26:27]
	ds_bpermute_b32 v49, v128, v27
	ds_bpermute_b32 v48, v128, v26
	v_and_b32_e32 v60, 0xffff0000, v32
	v_lshlrev_b32_e32 v61, 16, v32
	v_and_b32_e32 v62, 0xffff0000, v36
	v_lshlrev_b32_e32 v63, 16, v36
	s_waitcnt lgkmcnt(0)
	v_pk_add_f32 v[26:27], v[26:27], v[48:49]
	ds_bpermute_b32 v49, v129, v27
	ds_bpermute_b32 v48, v129, v26
	v_and_b32_e32 v68, 0xffff0000, v40
	v_lshlrev_b32_e32 v69, 16, v40
	v_and_b32_e32 v70, 0xffff0000, v44
	v_lshlrev_b32_e32 v71, 16, v44
	s_waitcnt lgkmcnt(0)
	v_pk_add_f32 v[26:27], v[26:27], v[48:49]
	ds_bpermute_b32 v49, v130, v27
	ds_bpermute_b32 v48, v130, v26
	v_pk_add_f32 v[64:65], v[60:61], v[62:63]
	v_pk_add_f32 v[82:83], v[68:69], v[70:71]
	v_and_b32_e32 v32, 0xffff0000, v33
	v_lshlrev_b32_e32 v33, 16, v33
	s_waitcnt lgkmcnt(0)
	v_pk_add_f32 v[26:27], v[26:27], v[48:49]
	ds_bpermute_b32 v49, v131, v27
	ds_bpermute_b32 v48, v131, v26
	v_and_b32_e32 v36, 0xffff0000, v37
	v_lshlrev_b32_e32 v37, 16, v37
	v_and_b32_e32 v40, 0xffff0000, v41
	v_lshlrev_b32_e32 v41, 16, v41
	s_waitcnt lgkmcnt(0)
	v_pk_add_f32 v[26:27], v[26:27], v[48:49]
	ds_bpermute_b32 v49, v132, v27
	ds_bpermute_b32 v48, v132, v26
	v_and_b32_e32 v44, 0xffff0000, v45
	v_lshlrev_b32_e32 v45, 16, v45
	v_pk_add_f32 v[66:67], v[32:33], v[36:37]
	v_pk_add_f32 v[84:85], v[40:41], v[44:45]
	s_waitcnt lgkmcnt(0)
	v_pk_add_f32 v[26:27], v[26:27], v[48:49]
	ds_bpermute_b32 v49, v133, v27
	ds_bpermute_b32 v48, v133, v26
	s_waitcnt lgkmcnt(0)
	v_pk_add_f32 v[48:49], v[26:27], v[48:49]
	s_nop 0
	v_pk_mul_f32 v[26:27], v[48:49], s[46:47] op_sel_hi:[1,0]
	v_pk_fma_f32 v[16:17], v[48:49], s[46:47], v[16:17] op_sel_hi:[1,0,1] neg_lo:[1,0,0] neg_hi:[1,0,0]
	v_pk_add_f32 v[46:47], v[46:47], v[26:27] op_sel:[0,1] neg_lo:[0,1] neg_hi:[0,1]
	v_pk_add_f32 v[14:15], v[14:15], v[26:27] op_sel:[0,1] neg_lo:[0,1] neg_hi:[0,1]
	v_pk_add_f32 v[20:21], v[20:21], v[26:27] op_sel:[0,1] neg_lo:[0,1] neg_hi:[0,1]
	v_pk_mul_f32 v[46:47], v[46:47], v[46:47]
	v_pk_add_f32 v[10:11], v[10:11], v[26:27] op_sel:[0,1] neg_lo:[0,1] neg_hi:[0,1]
	v_pk_mul_f32 v[14:15], v[14:15], v[14:15]
	v_pk_fma_f32 v[20:21], v[20:21], v[20:21], v[46:47]
	v_pk_fma_f32 v[10:11], v[10:11], v[10:11], v[14:15]
	v_pk_fma_f32 v[14:15], v[48:49], s[46:47], v[86:87] op_sel_hi:[1,0,1] neg_lo:[1,0,0] neg_hi:[1,0,0]
	v_pk_mul_f32 v[16:17], v[16:17], v[16:17]
	v_pk_fma_f32 v[46:47], v[48:49], s[46:47], v[92:93] op_sel_hi:[1,0,1] neg_lo:[1,0,0] neg_hi:[1,0,0]
	v_pk_fma_f32 v[14:15], v[14:15], v[14:15], v[16:17]
	v_pk_fma_f32 v[16:17], v[48:49], s[46:47], v[88:89] op_sel_hi:[1,0,1] neg_lo:[1,0,0] neg_hi:[1,0,0]
	v_pk_mul_f32 v[46:47], v[46:47], v[46:47]
	v_pk_fma_f32 v[12:13], v[48:49], s[46:47], v[12:13] op_sel_hi:[1,0,1] neg_lo:[1,0,0] neg_hi:[1,0,0]
	v_pk_fma_f32 v[16:17], v[16:17], v[16:17], v[46:47]
	v_pk_fma_f32 v[46:47], v[48:49], s[46:47], v[94:95] op_sel_hi:[1,0,1] neg_lo:[1,0,0] neg_hi:[1,0,0]
	v_pk_add_f32 v[14:15], v[14:15], v[16:17]
	v_pk_fma_f32 v[16:17], v[48:49], s[46:47], v[90:91] op_sel_hi:[1,0,1] neg_lo:[1,0,0] neg_hi:[1,0,0]
	v_pk_mul_f32 v[46:47], v[46:47], v[46:47]
	v_pk_fma_f32 v[8:9], v[48:49], s[46:47], v[8:9] op_sel_hi:[1,0,1] neg_lo:[1,0,0] neg_hi:[1,0,0]
	v_pk_fma_f32 v[16:17], v[16:17], v[16:17], v[46:47]
	v_pk_mul_f32 v[12:13], v[12:13], v[12:13]
	v_pk_add_f32 v[14:15], v[16:17], v[14:15]
	v_pk_fma_f32 v[8:9], v[8:9], v[8:9], v[12:13]
	v_pk_add_f32 v[12:13], v[52:53], v[26:27] op_sel_hi:[1,0] neg_lo:[0,1] neg_hi:[0,1]
	v_pk_add_f32 v[8:9], v[8:9], v[14:15]
	v_pk_add_f32 v[14:15], v[54:55], v[26:27] op_sel_hi:[1,0] neg_lo:[0,1] neg_hi:[0,1]
	v_pk_add_f32 v[16:17], v[28:29], v[26:27] op_sel_hi:[1,0] neg_lo:[0,1] neg_hi:[0,1]
	v_pk_mul_f32 v[14:15], v[14:15], v[14:15]
	v_pk_mul_f32 v[16:17], v[16:17], v[16:17]
	v_pk_fma_f32 v[12:13], v[12:13], v[12:13], v[14:15]
	v_mov_b32_e32 v15, v21
	v_mov_b32_e32 v14, v13
	v_pk_add_f32 v[8:9], v[14:15], v[8:9]
	v_pk_add_f32 v[14:15], v[18:19], v[26:27] op_sel_hi:[1,0] neg_lo:[0,1] neg_hi:[0,1]
	v_and_b32_e32 v19, 0xffff0000, v30
	v_pk_fma_f32 v[14:15], v[14:15], v[14:15], v[16:17]
	v_lshlrev_b32_e32 v17, 16, v30
	v_lshlrev_b32_e32 v16, 16, v38
	v_and_b32_e32 v18, 0xffff0000, v38
	v_lshlrev_b32_e32 v28, 16, v39
	v_and_b32_e32 v30, 0xffff0000, v39
	v_lshlrev_b32_e32 v39, 16, v34
	v_lshlrev_b32_e32 v38, 16, v42
	v_and_b32_e32 v47, 0xffff0000, v34
	v_and_b32_e32 v46, 0xffff0000, v42
	v_lshlrev_b32_e32 v48, 16, v43
	v_and_b32_e32 v34, 0xffff0000, v43
	v_pk_add_f32 v[42:43], v[16:17], v[38:39]
	v_lshlrev_b32_e32 v29, 16, v31
	v_lshlrev_b32_e32 v49, 16, v35
	v_pk_add_f32 v[42:43], v[42:43], 0 op_sel_hi:[1,0]
	v_pk_add_f32 v[50:51], v[18:19], v[46:47]
	v_and_b32_e32 v31, 0xffff0000, v31
	v_and_b32_e32 v35, 0xffff0000, v35
	v_pk_add_f32 v[42:43], v[50:51], v[42:43]
	v_pk_add_f32 v[50:51], v[28:29], v[48:49]
	v_mov_b32_e32 v13, v20
	v_pk_add_f32 v[42:43], v[50:51], v[42:43]
	v_pk_add_f32 v[50:51], v[30:31], v[34:35]
	v_pk_add_f32 v[8:9], v[12:13], v[8:9]
	v_pk_add_f32 v[42:43], v[50:51], v[42:43]
	v_mov_b32_e32 v50, v83
	v_mov_b32_e32 v51, v65
	v_pk_add_f32 v[42:43], v[50:51], v[42:43]
	v_mov_b32_e32 v83, v64
	v_pk_add_f32 v[42:43], v[82:83], v[42:43]
	v_mov_b32_e32 v50, v85
	v_mov_b32_e32 v51, v67
	v_pk_add_f32 v[42:43], v[50:51], v[42:43]
	v_mov_b32_e32 v85, v66
	v_pk_add_f32 v[42:43], v[84:85], v[42:43]
	ds_bpermute_b32 v51, v128, v43
	ds_bpermute_b32 v50, v128, v42
	v_mov_b32_e32 v12, v15
	v_mov_b32_e32 v13, v11
	v_pk_add_f32 v[8:9], v[12:13], v[8:9]
	v_mov_b32_e32 v15, v10
	s_waitcnt lgkmcnt(0)
	v_pk_add_f32 v[42:43], v[42:43], v[50:51]
	ds_bpermute_b32 v51, v129, v43
	ds_bpermute_b32 v50, v129, v42
	v_pk_add_f32 v[8:9], v[14:15], v[8:9]
	ds_bpermute_b32 v11, v128, v9
	ds_bpermute_b32 v10, v128, v8
	v_mov_b32_e32 v83, v75
	s_waitcnt lgkmcnt(2)
	v_pk_add_f32 v[42:43], v[42:43], v[50:51]
	ds_bpermute_b32 v51, v130, v43
	ds_bpermute_b32 v50, v130, v42
	s_waitcnt lgkmcnt(2)
	v_pk_add_f32 v[8:9], v[8:9], v[10:11]
	ds_bpermute_b32 v11, v129, v9
	ds_bpermute_b32 v10, v129, v8
	s_waitcnt lgkmcnt(2)
	v_pk_add_f32 v[42:43], v[42:43], v[50:51]
	ds_bpermute_b32 v51, v131, v43
	ds_bpermute_b32 v50, v131, v42
	s_waitcnt lgkmcnt(2)
	v_pk_add_f32 v[8:9], v[8:9], v[10:11]
	ds_bpermute_b32 v11, v130, v9
	ds_bpermute_b32 v10, v130, v8
	s_waitcnt lgkmcnt(2)
	v_pk_add_f32 v[42:43], v[42:43], v[50:51]
	ds_bpermute_b32 v51, v132, v43
	ds_bpermute_b32 v50, v132, v42
	s_waitcnt lgkmcnt(2)
	v_pk_add_f32 v[8:9], v[8:9], v[10:11]
	ds_bpermute_b32 v11, v131, v9
	ds_bpermute_b32 v10, v131, v8
	s_waitcnt lgkmcnt(2)
	v_pk_add_f32 v[42:43], v[42:43], v[50:51]
	ds_bpermute_b32 v51, v133, v43
	ds_bpermute_b32 v50, v133, v42
	s_waitcnt lgkmcnt(2)
	v_pk_add_f32 v[8:9], v[8:9], v[10:11]
	ds_bpermute_b32 v11, v132, v9
	ds_bpermute_b32 v10, v132, v8
	s_waitcnt lgkmcnt(2)
	v_pk_add_f32 v[42:43], v[42:43], v[50:51]
	s_nop 0
	v_pk_mul_f32 v[84:85], v[42:43], s[46:47] op_sel_hi:[1,0]
	v_pk_fma_f32 v[16:17], v[42:43], s[46:47], v[16:17] op_sel_hi:[1,0,1] neg_lo:[1,0,0] neg_hi:[1,0,0]
	v_pk_add_f32 v[36:37], v[36:37], v[84:85] op_sel:[0,1] neg_lo:[0,1] neg_hi:[0,1]
	v_pk_add_f32 v[32:33], v[32:33], v[84:85] op_sel:[0,1] neg_lo:[0,1] neg_hi:[0,1]
	v_pk_mul_f32 v[36:37], v[36:37], v[36:37]
	s_waitcnt lgkmcnt(0)
	v_pk_add_f32 v[8:9], v[8:9], v[10:11]
	v_pk_fma_f32 v[32:33], v[32:33], v[32:33], v[36:37]
	v_pk_fma_f32 v[36:37], v[42:43], s[46:47], v[38:39] op_sel_hi:[1,0,1] neg_lo:[1,0,0] neg_hi:[1,0,0]
	ds_bpermute_b32 v11, v133, v9
	ds_bpermute_b32 v10, v133, v8
	v_pk_mul_f32 v[36:37], v[36:37], v[36:37]
	v_pk_fma_f32 v[18:19], v[42:43], s[46:47], v[18:19] op_sel_hi:[1,0,1] neg_lo:[1,0,0] neg_hi:[1,0,0]
	v_pk_fma_f32 v[16:17], v[16:17], v[16:17], v[36:37]
	v_pk_fma_f32 v[36:37], v[42:43], s[46:47], v[46:47] op_sel_hi:[1,0,1] neg_lo:[1,0,0] neg_hi:[1,0,0]
	s_waitcnt lgkmcnt(0)
	v_pk_add_f32 v[8:9], v[8:9], v[10:11]
	v_pk_mul_f32 v[36:37], v[36:37], v[36:37]
	v_pk_fma_f32 v[8:9], v[8:9], s[46:47], v[80:81] op_sel_hi:[1,0,0]
	v_pk_fma_f32 v[18:19], v[18:19], v[18:19], v[36:37]
	v_mul_f32_e32 v5, 0x4b800000, v9
	v_pk_add_f32 v[16:17], v[16:17], v[18:19]
	v_pk_fma_f32 v[18:19], v[42:43], s[46:47], v[28:29] op_sel_hi:[1,0,1] neg_lo:[1,0,0] neg_hi:[1,0,0]
	v_pk_fma_f32 v[28:29], v[42:43], s[46:47], v[48:49] op_sel_hi:[1,0,1] neg_lo:[1,0,0] neg_hi:[1,0,0]
	v_cmp_gt_f32_e64 s[4:5], s67, v9
	v_pk_mul_f32 v[28:29], v[28:29], v[28:29]
	v_pk_add_f32 v[52:53], v[62:63], v[84:85] op_sel:[0,1] neg_lo:[0,1] neg_hi:[0,1]
	v_pk_fma_f32 v[18:19], v[18:19], v[18:19], v[28:29]
	v_pk_fma_f32 v[28:29], v[42:43], s[46:47], v[34:35] op_sel_hi:[1,0,1] neg_lo:[1,0,0] neg_hi:[1,0,0]
	v_pk_add_f32 v[16:17], v[18:19], v[16:17]
	v_pk_fma_f32 v[18:19], v[42:43], s[46:47], v[30:31] op_sel_hi:[1,0,1] neg_lo:[1,0,0] neg_hi:[1,0,0]
	v_pk_mul_f32 v[28:29], v[28:29], v[28:29]
	v_cndmask_b32_e64 v5, v9, v5, s[4:5]
	v_pk_fma_f32 v[18:19], v[18:19], v[18:19], v[28:29]
	v_pk_add_f32 v[28:29], v[70:71], v[84:85] op_sel_hi:[1,0] neg_lo:[0,1] neg_hi:[0,1]
	v_rsq_f32_e32 v5, v5
	v_pk_add_f32 v[50:51], v[60:61], v[84:85] op_sel:[0,1] neg_lo:[0,1] neg_hi:[0,1]
	v_pk_mul_f32 v[52:53], v[52:53], v[52:53]
	v_pk_add_f32 v[16:17], v[18:19], v[16:17]
	v_pk_add_f32 v[18:19], v[68:69], v[84:85] op_sel_hi:[1,0] neg_lo:[0,1] neg_hi:[0,1]
	v_pk_mul_f32 v[28:29], v[28:29], v[28:29]
	v_pk_fma_f32 v[50:51], v[50:51], v[50:51], v[52:53]
	v_pk_fma_f32 v[18:19], v[18:19], v[18:19], v[28:29]
	v_mov_b32_e32 v29, v51
	v_mov_b32_e32 v28, v19
	v_pk_add_f32 v[30:31], v[44:45], v[84:85] op_sel_hi:[1,0] neg_lo:[0,1] neg_hi:[0,1]
	v_pk_add_f32 v[16:17], v[28:29], v[16:17]
	v_pk_add_f32 v[28:29], v[40:41], v[84:85] op_sel_hi:[1,0] neg_lo:[0,1] neg_hi:[0,1]
	v_pk_mul_f32 v[30:31], v[30:31], v[30:31]
	v_mul_f32_e32 v7, 0x45800000, v5
	v_pk_fma_f32 v[30:31], v[28:29], v[28:29], v[30:31]
	v_cmp_gt_f32_e32 vcc, s67, v8
	v_cndmask_b32_e64 v28, v5, v7, s[4:5]
	v_mul_f32_e32 v5, 0x4b800000, v8
	v_mov_b32_e32 v19, v50
	v_cndmask_b32_e32 v5, v8, v5, vcc
	v_pk_add_f32 v[8:9], v[18:19], v[16:17]
	v_mov_b32_e32 v10, v31
	v_mov_b32_e32 v11, v33
	v_pk_add_f32 v[8:9], v[10:11], v[8:9]
	v_mov_b32_e32 v31, v32
	v_pk_add_f32 v[8:9], v[30:31], v[8:9]
	ds_bpermute_b32 v11, v128, v9
	ds_bpermute_b32 v10, v128, v8
	v_rsq_f32_e32 v5, v5
	s_waitcnt lgkmcnt(0)
	v_pk_add_f32 v[8:9], v[8:9], v[10:11]
	ds_bpermute_b32 v11, v129, v9
	ds_bpermute_b32 v10, v129, v8
	v_mul_f32_e32 v7, 0x45800000, v5
	v_cndmask_b32_e32 v90, v5, v7, vcc
	s_waitcnt lgkmcnt(0)
	v_pk_add_f32 v[8:9], v[8:9], v[10:11]
	ds_bpermute_b32 v11, v130, v9
	ds_bpermute_b32 v10, v130, v8
	s_waitcnt lgkmcnt(0)
	v_pk_add_f32 v[8:9], v[8:9], v[10:11]
	ds_bpermute_b32 v11, v131, v9
	ds_bpermute_b32 v10, v131, v8
	s_waitcnt lgkmcnt(0)
	v_pk_add_f32 v[8:9], v[8:9], v[10:11]
	ds_bpermute_b32 v11, v132, v9
	ds_bpermute_b32 v10, v132, v8
	s_waitcnt lgkmcnt(0)
	v_pk_add_f32 v[8:9], v[8:9], v[10:11]
	ds_bpermute_b32 v11, v133, v9
	ds_bpermute_b32 v10, v133, v8
	s_waitcnt lgkmcnt(0)
	v_pk_add_f32 v[8:9], v[8:9], v[10:11]
	s_nop 0
	v_pk_fma_f32 v[8:9], v[8:9], s[46:47], v[80:81] op_sel_hi:[1,0,0]
	s_nop 0
	v_mul_f32_e32 v5, 0x4b800000, v9
	v_cmp_gt_f32_e64 s[4:5], s67, v9
	v_cmp_gt_f32_e32 vcc, s67, v8
	s_nop 0
	v_cndmask_b32_e64 v5, v9, v5, s[4:5]
	v_rsq_f32_e32 v5, v5
	s_nop 0
	v_mul_f32_e32 v7, 0x45800000, v5
	v_cndmask_b32_e64 v88, v5, v7, s[4:5]
	s_and_b32 s4, s19, 0x200
	v_or_b32_e32 v87, s4, v72
	v_lshlrev_b32_e32 v82, 1, v87
	v_mul_f32_e32 v5, 0x4b800000, v8
	v_lshlrev_b32_e32 v74, 2, v87
	v_lshl_add_u64 v[16:17], s[52:53], 0, v[82:83]
	v_cndmask_b32_e32 v5, v8, v5, vcc
	global_load_dwordx4 v[12:15], v74, s[10:11] offset:16 nt
	global_load_dwordx4 v[8:11], v74, s[10:11] nt
	global_load_dwordx4 v[40:43], v74, s[40:41] offset:16 nt
	global_load_dwordx4 v[44:47], v74, s[40:41] nt
	flat_load_dwordx4 v[30:33], v[16:17] offset:2048 nt
	s_lshl_b64 s[4:5], s[56:57], 12
	s_add_u32 s4, s7, s4
	s_addc_u32 s5, s9, s5
	s_add_i32 s62, s56, 0x2001
	s_ashr_i32 s63, s62, 31
	v_rsq_f32_e32 v5, v5
	s_waitcnt vmcnt(0) lgkmcnt(0)
	v_lshlrev_b32_e32 v16, 16, v30
	v_and_b32_e32 v17, 0xffff0000, v30
	v_lshlrev_b32_e32 v18, 16, v31
	v_and_b32_e32 v19, 0xffff0000, v31
	v_lshlrev_b32_e32 v20, 16, v32
	v_and_b32_e32 v21, 0xffff0000, v32
	v_lshlrev_b32_e32 v30, 16, v33
	v_and_b32_e32 v31, 0xffff0000, v33
	v_pk_add_f32 v[16:17], v[16:17], v[0:1] op_sel:[0,1] neg_lo:[0,1] neg_hi:[0,1]
	v_pk_add_f32 v[18:19], v[18:19], v[0:1] op_sel:[0,1] neg_lo:[0,1] neg_hi:[0,1]
	v_pk_add_f32 v[20:21], v[20:21], v[0:1] op_sel:[0,1] neg_lo:[0,1] neg_hi:[0,1]
	v_pk_add_f32 v[30:31], v[30:31], v[0:1] op_sel:[0,1] neg_lo:[0,1] neg_hi:[0,1]
	v_pk_mul_f32 v[16:17], v[22:23], v[16:17] op_sel_hi:[0,1]
	v_pk_mul_f32 v[18:19], v[22:23], v[18:19] op_sel_hi:[0,1]
	v_pk_mul_f32 v[20:21], v[22:23], v[20:21] op_sel_hi:[0,1]
	v_pk_mul_f32 v[22:23], v[22:23], v[30:31] op_sel_hi:[0,1]
	v_lshl_add_u64 v[30:31], s[4:5], 0, v[74:75]
	s_add_i32 s4, s3, 0x9004800
	s_mul_hi_i32 s5, s62, 0x4800
	s_add_u32 s4, s14, s4
	v_pk_fma_f32 v[16:17], v[8:9], v[16:17], v[44:45]
	v_pk_fma_f32 v[18:19], v[10:11], v[18:19], v[46:47]
	s_addc_u32 s5, s15, s5
	v_pk_fma_f32 v[20:21], v[12:13], v[20:21], v[40:41]
	v_pk_fma_f32 v[22:23], v[14:15], v[22:23], v[42:43]
	flat_store_dwordx4 v[30:31], v[16:19]
	flat_store_dwordx4 v[30:31], v[20:23] offset:16
	v_lshl_add_u64 v[30:31], s[4:5], 0, v[82:83]
	flat_load_dwordx4 v[30:33], v[30:31] offset:2048 nt
	s_or_b32 s4, s56, 1
	s_ashr_i32 s5, s4, 31
	s_lshl_b64 s[4:5], s[4:5], 12
	s_add_u32 s4, s7, s4
	s_addc_u32 s5, s9, s5
	s_add_i32 s60, s56, 0x2002
	s_ashr_i32 s61, s60, 31
	v_mul_f32_e32 v7, 0x45800000, v5
	v_cndmask_b32_e32 v86, v5, v7, vcc
	s_waitcnt vmcnt(0) lgkmcnt(0)
	v_lshlrev_b32_e32 v34, 16, v30
	v_and_b32_e32 v35, 0xffff0000, v30
	v_lshlrev_b32_e32 v30, 16, v31
	v_and_b32_e32 v31, 0xffff0000, v31
	v_pk_add_f32 v[30:31], v[30:31], v[0:1] op_sel_hi:[1,0] neg_lo:[0,1] neg_hi:[0,1]
	v_pk_add_f32 v[34:35], v[34:35], v[0:1] op_sel_hi:[1,0] neg_lo:[0,1] neg_hi:[0,1]
	v_pk_mul_f32 v[30:31], v[24:25], v[30:31] op_sel_hi:[0,1]
	v_pk_fma_f32 v[70:71], v[10:11], v[30:31], v[46:47]
	v_lshlrev_b32_e32 v30, 16, v32
	v_and_b32_e32 v31, 0xffff0000, v32
	v_pk_add_f32 v[30:31], v[30:31], v[0:1] op_sel_hi:[1,0] neg_lo:[0,1] neg_hi:[0,1]
	v_pk_mul_f32 v[34:35], v[24:25], v[34:35] op_sel_hi:[0,1]
	v_pk_mul_f32 v[30:31], v[24:25], v[30:31] op_sel_hi:[0,1]
	v_pk_fma_f32 v[64:65], v[12:13], v[30:31], v[40:41]
	v_lshlrev_b32_e32 v30, 16, v33
	v_and_b32_e32 v31, 0xffff0000, v33
	v_pk_add_f32 v[0:1], v[30:31], v[0:1] op_sel_hi:[1,0] neg_lo:[0,1] neg_hi:[0,1]
	v_pk_fma_f32 v[68:69], v[8:9], v[34:35], v[44:45]
	v_pk_mul_f32 v[0:1], v[24:25], v[0:1] op_sel_hi:[0,1]
	v_pk_fma_f32 v[66:67], v[14:15], v[0:1], v[42:43]
	v_lshl_add_u64 v[0:1], s[4:5], 0, v[74:75]
	s_add_i32 s4, s3, 0x9009000
	s_mul_hi_i32 s5, s60, 0x4800
	s_add_u32 s4, s14, s4
	s_addc_u32 s5, s15, s5
	flat_store_dwordx4 v[0:1], v[68:71]
	flat_store_dwordx4 v[0:1], v[64:67] offset:16
	v_lshl_add_u64 v[0:1], s[4:5], 0, v[82:83]
	flat_load_dwordx4 v[30:33], v[0:1] offset:2048 nt
	s_or_b32 s4, s56, 2
	s_ashr_i32 s5, s4, 31
	s_lshl_b64 s[4:5], s[4:5], 12
	s_add_u32 s4, s7, s4
	s_addc_u32 s5, s9, s5
	s_add_i32 s58, s56, 0x2003
	s_ashr_i32 s59, s58, 31
	s_waitcnt vmcnt(0) lgkmcnt(0)
	v_lshlrev_b32_e32 v0, 16, v30
	v_and_b32_e32 v1, 0xffff0000, v30
	v_pk_add_f32 v[0:1], v[0:1], v[2:3] op_sel:[0,1] neg_lo:[0,1] neg_hi:[0,1]
	s_nop 0
	v_pk_mul_f32 v[0:1], v[6:7], v[0:1] op_sel_hi:[0,1]
	v_pk_fma_f32 v[60:61], v[8:9], v[0:1], v[44:45]
	v_lshlrev_b32_e32 v0, 16, v31
	v_and_b32_e32 v1, 0xffff0000, v31
	v_pk_add_f32 v[0:1], v[0:1], v[2:3] op_sel:[0,1] neg_lo:[0,1] neg_hi:[0,1]
	s_nop 0
	v_pk_mul_f32 v[0:1], v[6:7], v[0:1] op_sel_hi:[0,1]
	v_pk_fma_f32 v[62:63], v[10:11], v[0:1], v[46:47]
	v_lshlrev_b32_e32 v0, 16, v32
	v_and_b32_e32 v1, 0xffff0000, v32
	v_pk_add_f32 v[0:1], v[0:1], v[2:3] op_sel:[0,1] neg_lo:[0,1] neg_hi:[0,1]
	s_nop 0
	v_pk_mul_f32 v[0:1], v[6:7], v[0:1] op_sel_hi:[0,1]
	v_pk_fma_f32 v[56:57], v[12:13], v[0:1], v[40:41]
	v_lshlrev_b32_e32 v0, 16, v33
	v_and_b32_e32 v1, 0xffff0000, v33
	v_pk_add_f32 v[0:1], v[0:1], v[2:3] op_sel:[0,1] neg_lo:[0,1] neg_hi:[0,1]
	s_nop 0
	v_pk_mul_f32 v[0:1], v[6:7], v[0:1] op_sel_hi:[0,1]
	v_pk_fma_f32 v[58:59], v[14:15], v[0:1], v[42:43]
	v_lshl_add_u64 v[0:1], s[4:5], 0, v[74:75]
	s_add_i32 s4, s3, 0x900d800
	s_mul_hi_i32 s5, s58, 0x4800
	s_add_u32 s4, s14, s4
	s_addc_u32 s5, s15, s5
	flat_store_dwordx4 v[0:1], v[60:63]
	flat_store_dwordx4 v[0:1], v[56:59] offset:16
	v_lshl_add_u64 v[0:1], s[4:5], 0, v[82:83]
	flat_load_dwordx4 v[30:33], v[0:1] offset:2048 nt
	s_or_b32 s4, s56, 3
	s_ashr_i32 s5, s4, 31
	s_lshl_b64 s[4:5], s[4:5], 12
	s_add_u32 s4, s7, s4
	s_addc_u32 s5, s9, s5
	s_waitcnt vmcnt(0) lgkmcnt(0)
	v_lshlrev_b32_e32 v0, 16, v30
	v_and_b32_e32 v1, 0xffff0000, v30
	v_pk_add_f32 v[0:1], v[0:1], v[2:3] op_sel_hi:[1,0] neg_lo:[0,1] neg_hi:[0,1]
	s_nop 0
	v_pk_mul_f32 v[0:1], v[4:5], v[0:1] op_sel_hi:[0,1]
	v_pk_fma_f32 v[52:53], v[8:9], v[0:1], v[44:45]
	v_lshlrev_b32_e32 v0, 16, v31
	v_and_b32_e32 v1, 0xffff0000, v31
	v_pk_add_f32 v[0:1], v[0:1], v[2:3] op_sel_hi:[1,0] neg_lo:[0,1] neg_hi:[0,1]
	s_nop 0
	v_pk_mul_f32 v[0:1], v[4:5], v[0:1] op_sel_hi:[0,1]
	v_pk_fma_f32 v[54:55], v[10:11], v[0:1], v[46:47]
	v_lshlrev_b32_e32 v0, 16, v32
	v_and_b32_e32 v1, 0xffff0000, v32
	v_pk_add_f32 v[0:1], v[0:1], v[2:3] op_sel_hi:[1,0] neg_lo:[0,1] neg_hi:[0,1]
	s_nop 0
	v_pk_mul_f32 v[0:1], v[4:5], v[0:1] op_sel_hi:[0,1]
	v_pk_fma_f32 v[48:49], v[12:13], v[0:1], v[40:41]
	v_lshlrev_b32_e32 v0, 16, v33
	v_and_b32_e32 v1, 0xffff0000, v33
	v_pk_add_f32 v[0:1], v[0:1], v[2:3] op_sel_hi:[1,0] neg_lo:[0,1] neg_hi:[0,1]
	s_nop 0
	v_pk_mul_f32 v[0:1], v[4:5], v[0:1] op_sel_hi:[0,1]
	v_pk_fma_f32 v[50:51], v[14:15], v[0:1], v[42:43]
	v_lshl_add_u64 v[0:1], s[4:5], 0, v[74:75]
	s_add_u32 s4, s14, s55
	s_addc_u32 s5, s15, s54
	flat_store_dwordx4 v[0:1], v[52:55]
	flat_store_dwordx4 v[0:1], v[48:51] offset:16
	v_lshl_add_u64 v[0:1], s[4:5], 0, v[82:83]
	flat_load_dwordx4 v[0:3], v[0:1] offset:2048 nt
	s_or_b32 s4, s29, 4
	s_ashr_i32 s5, s4, 31
	s_lshl_b64 s[4:5], s[4:5], 12
	s_add_u32 s4, s7, s4
	s_addc_u32 s5, s9, s5
	s_add_i32 s54, s56, 0x2005
	s_ashr_i32 s55, s54, 31
	s_waitcnt vmcnt(0) lgkmcnt(0)
	v_lshlrev_b32_e32 v4, 16, v0
	v_and_b32_e32 v5, 0xffff0000, v0
	v_lshlrev_b32_e32 v0, 16, v1
	v_and_b32_e32 v1, 0xffff0000, v1
	v_pk_add_f32 v[0:1], v[0:1], v[26:27] op_sel:[0,1] neg_lo:[0,1] neg_hi:[0,1]
	v_pk_add_f32 v[4:5], v[4:5], v[26:27] op_sel:[0,1] neg_lo:[0,1] neg_hi:[0,1]
	v_pk_mul_f32 v[0:1], v[28:29], v[0:1] op_sel_hi:[0,1]
	v_pk_fma_f32 v[38:39], v[10:11], v[0:1], v[46:47]
	v_lshlrev_b32_e32 v0, 16, v2
	v_and_b32_e32 v1, 0xffff0000, v2
	v_pk_add_f32 v[0:1], v[0:1], v[26:27] op_sel:[0,1] neg_lo:[0,1] neg_hi:[0,1]
	v_pk_mul_f32 v[4:5], v[28:29], v[4:5] op_sel_hi:[0,1]
	v_pk_mul_f32 v[0:1], v[28:29], v[0:1] op_sel_hi:[0,1]
	v_pk_fma_f32 v[32:33], v[12:13], v[0:1], v[40:41]
	v_lshlrev_b32_e32 v0, 16, v3
	v_and_b32_e32 v1, 0xffff0000, v3
	v_pk_add_f32 v[0:1], v[0:1], v[26:27] op_sel:[0,1] neg_lo:[0,1] neg_hi:[0,1]
	v_pk_fma_f32 v[36:37], v[8:9], v[4:5], v[44:45]
	v_pk_mul_f32 v[0:1], v[28:29], v[0:1] op_sel_hi:[0,1]
	v_pk_fma_f32 v[34:35], v[14:15], v[0:1], v[42:43]
	v_lshl_add_u64 v[0:1], s[4:5], 0, v[74:75]
	s_add_i32 s4, s3, 0x9016800
	s_mul_hi_i32 s5, s54, 0x4800
	s_add_u32 s4, s14, s4
	s_addc_u32 s5, s15, s5
	flat_store_dwordx4 v[0:1], v[36:39]
	flat_store_dwordx4 v[0:1], v[32:35] offset:16
	v_lshl_add_u64 v[0:1], s[4:5], 0, v[82:83]
	flat_load_dwordx4 v[0:3], v[0:1] offset:2048 nt
	s_or_b32 s4, s29, 5
	s_ashr_i32 s5, s4, 31
	s_lshl_b64 s[4:5], s[4:5], 12
	s_add_u32 s4, s7, s4
	s_addc_u32 s5, s9, s5
	s_add_i32 s52, s56, 0x2006
	s_ashr_i32 s53, s52, 31
	s_waitcnt vmcnt(0) lgkmcnt(0)
	v_lshlrev_b32_e32 v4, 16, v0
	v_and_b32_e32 v5, 0xffff0000, v0
	v_lshlrev_b32_e32 v0, 16, v1
	v_and_b32_e32 v1, 0xffff0000, v1
	v_pk_add_f32 v[0:1], v[0:1], v[26:27] op_sel_hi:[1,0] neg_lo:[0,1] neg_hi:[0,1]
	v_pk_add_f32 v[4:5], v[4:5], v[26:27] op_sel_hi:[1,0] neg_lo:[0,1] neg_hi:[0,1]
	v_pk_mul_f32 v[0:1], v[90:91], v[0:1] op_sel_hi:[0,1]
	v_pk_fma_f32 v[30:31], v[10:11], v[0:1], v[46:47]
	v_lshlrev_b32_e32 v0, 16, v2
	v_and_b32_e32 v1, 0xffff0000, v2
	v_pk_add_f32 v[0:1], v[0:1], v[26:27] op_sel_hi:[1,0] neg_lo:[0,1] neg_hi:[0,1]
	v_pk_mul_f32 v[4:5], v[90:91], v[4:5] op_sel_hi:[0,1]
	v_pk_mul_f32 v[0:1], v[90:91], v[0:1] op_sel_hi:[0,1]
	v_pk_fma_f32 v[24:25], v[12:13], v[0:1], v[40:41]
	v_lshlrev_b32_e32 v0, 16, v3
	v_and_b32_e32 v1, 0xffff0000, v3
	v_pk_add_f32 v[0:1], v[0:1], v[26:27] op_sel_hi:[1,0] neg_lo:[0,1] neg_hi:[0,1]
	v_pk_fma_f32 v[28:29], v[8:9], v[4:5], v[44:45]
	v_pk_mul_f32 v[0:1], v[90:91], v[0:1] op_sel_hi:[0,1]
	v_pk_fma_f32 v[26:27], v[14:15], v[0:1], v[42:43]
	v_lshl_add_u64 v[0:1], s[4:5], 0, v[74:75]
	s_add_i32 s4, s3, 0x901b000
	s_mul_hi_i32 s5, s52, 0x4800
	s_add_u32 s4, s14, s4
	s_addc_u32 s5, s15, s5
	flat_store_dwordx4 v[0:1], v[28:31]
	flat_store_dwordx4 v[0:1], v[24:27] offset:16
	v_lshl_add_u64 v[0:1], s[4:5], 0, v[82:83]
	flat_load_dwordx4 v[4:7], v[0:1] offset:2048 nt
	s_or_b32 s4, s29, 6
	s_ashr_i32 s5, s4, 31
	s_lshl_b64 s[4:5], s[4:5], 12
	s_add_u32 s4, s7, s4
	s_addc_u32 s5, s9, s5
	s_add_i32 s3, s3, 0x901f800
	s_waitcnt vmcnt(0) lgkmcnt(0)
	v_lshlrev_b32_e32 v0, 16, v4
	v_and_b32_e32 v1, 0xffff0000, v4
	v_lshlrev_b32_e32 v2, 16, v5
	v_and_b32_e32 v3, 0xffff0000, v5
	v_lshlrev_b32_e32 v4, 16, v6
	v_and_b32_e32 v5, 0xffff0000, v6
	v_lshlrev_b32_e32 v6, 16, v7
	v_and_b32_e32 v7, 0xffff0000, v7
	v_pk_add_f32 v[0:1], v[0:1], v[84:85] op_sel:[0,1] neg_lo:[0,1] neg_hi:[0,1]
	v_pk_add_f32 v[2:3], v[2:3], v[84:85] op_sel:[0,1] neg_lo:[0,1] neg_hi:[0,1]
	v_pk_add_f32 v[4:5], v[4:5], v[84:85] op_sel:[0,1] neg_lo:[0,1] neg_hi:[0,1]
	v_pk_add_f32 v[6:7], v[6:7], v[84:85] op_sel:[0,1] neg_lo:[0,1] neg_hi:[0,1]
	v_pk_mul_f32 v[0:1], v[88:89], v[0:1] op_sel_hi:[0,1]
	v_pk_mul_f32 v[2:3], v[88:89], v[2:3] op_sel_hi:[0,1]
	v_pk_mul_f32 v[4:5], v[88:89], v[4:5] op_sel_hi:[0,1]
	v_pk_mul_f32 v[6:7], v[88:89], v[6:7] op_sel_hi:[0,1]
	v_lshl_add_u64 v[88:89], s[4:5], 0, v[74:75]
	s_add_i32 s4, s56, 0x2007
	s_ashr_i32 s5, s4, 31
	s_mul_hi_i32 s12, s4, 0x4800
	s_add_u32 s56, s14, s3
	v_pk_fma_f32 v[0:1], v[8:9], v[0:1], v[44:45]
	v_pk_fma_f32 v[2:3], v[10:11], v[2:3], v[46:47]
	s_addc_u32 s57, s15, s12
	v_pk_fma_f32 v[4:5], v[12:13], v[4:5], v[40:41]
	v_pk_fma_f32 v[6:7], v[14:15], v[6:7], v[42:43]
	flat_store_dwordx4 v[88:89], v[0:3]
	flat_store_dwordx4 v[88:89], v[4:7] offset:16
	v_lshl_add_u64 v[88:89], s[56:57], 0, v[82:83]
	flat_load_dwordx4 v[88:91], v[88:89] offset:2048 nt
	s_or_b32 s56, s29, 7
	s_ashr_i32 s57, s56, 31
	s_lshl_b64 s[56:57], s[56:57], 12
	s_add_u32 s56, s7, s56
	s_addc_u32 s57, s9, s57
	s_add_i32 s68, s68, s18
	s_add_i32 s19, s19, s25
	s_add_i32 s29, s29, s47
	s_waitcnt vmcnt(0) lgkmcnt(0)
	v_lshlrev_b32_e32 v92, 16, v88
	v_and_b32_e32 v93, 0xffff0000, v88
	v_pk_add_f32 v[92:93], v[92:93], v[84:85] op_sel_hi:[1,0] neg_lo:[0,1] neg_hi:[0,1]
	s_nop 0
	v_pk_mul_f32 v[92:93], v[86:87], v[92:93] op_sel_hi:[0,1]
	v_pk_fma_f32 v[8:9], v[8:9], v[92:93], v[44:45]
	v_lshlrev_b32_e32 v44, 16, v89
	v_and_b32_e32 v45, 0xffff0000, v89
	v_pk_add_f32 v[44:45], v[44:45], v[84:85] op_sel_hi:[1,0] neg_lo:[0,1] neg_hi:[0,1]
	s_nop 0
	v_pk_mul_f32 v[44:45], v[86:87], v[44:45] op_sel_hi:[0,1]
	v_pk_fma_f32 v[10:11], v[10:11], v[44:45], v[46:47]
	v_lshlrev_b32_e32 v44, 16, v90
	v_and_b32_e32 v45, 0xffff0000, v90
	v_pk_add_f32 v[44:45], v[44:45], v[84:85] op_sel_hi:[1,0] neg_lo:[0,1] neg_hi:[0,1]
	s_nop 0
	v_pk_mul_f32 v[44:45], v[86:87], v[44:45] op_sel_hi:[0,1]
	v_pk_fma_f32 v[12:13], v[12:13], v[44:45], v[40:41]
	v_lshlrev_b32_e32 v40, 16, v91
	v_and_b32_e32 v41, 0xffff0000, v91
	v_pk_add_f32 v[40:41], v[40:41], v[84:85] op_sel_hi:[1,0] neg_lo:[0,1] neg_hi:[0,1]
	v_lshrrev_b32_e32 v44, 8, v87
	v_pk_mul_f32 v[40:41], v[86:87], v[40:41] op_sel_hi:[0,1]
	v_pk_fma_f32 v[14:15], v[14:15], v[40:41], v[42:43]
	v_lshl_add_u64 v[40:41], s[56:57], 0, v[74:75]
	flat_store_dwordx4 v[40:41], v[8:11]
	flat_store_dwordx4 v[40:41], v[12:15] offset:16
	v_lshlrev_b32_e32 v135, 9, v44
	v_lshlrev_b32_e32 v74, 16, v44
	v_lshl_add_u64 v[42:43], s[14:15], 0, v[82:83]
	v_lshl_add_u64 v[40:41], s[38:39], 0, v[82:83]
	global_load_dword v82, v135, s[44:45]
	global_load_dword v44, v74, s[42:43]
	s_waitcnt vmcnt(0)
	v_fma_f32 v83, v16, v44, v82
	v_fma_f32 v84, v17, v44, v82
	v_fma_f32 v85, v18, v44, v82
	v_fma_f32 v86, v19, v44, v82
	v_fma_f32 v87, v20, v44, v82
	v_fma_f32 v88, v21, v44, v82
	v_fma_f32 v89, v22, v44, v82
	v_fmac_f32_e32 v82, v23, v44
	v_mad_i64_i32 v[44:45], s[56:57], s50, v134, v[42:43]
	flat_load_dwordx4 v[44:47], v[44:45] nt
	s_lshl_b64 s[50:51], s[50:51], 12
	s_waitcnt vmcnt(0) lgkmcnt(0)
	v_lshlrev_b32_e32 v90, 16, v44
	v_and_b32_e32 v44, 0xffff0000, v44
	v_lshlrev_b32_e32 v91, 16, v45
	v_and_b32_e32 v45, 0xffff0000, v45
	v_mul_f32_e32 v83, v83, v90
	v_mul_f32_e32 v44, v84, v44
	v_lshlrev_b32_e32 v92, 16, v46
	v_and_b32_e32 v46, 0xffff0000, v46
	v_cvt_pk_bf16_f32 v44, v83, v44
	v_mul_f32_e32 v83, v85, v91
	v_mul_f32_e32 v45, v86, v45
	v_lshlrev_b32_e32 v93, 16, v47
	v_and_b32_e32 v47, 0xffff0000, v47
	v_cvt_pk_bf16_f32 v45, v83, v45
	v_mul_f32_e32 v83, v87, v92
	v_mul_f32_e32 v46, v88, v46
	v_cvt_pk_bf16_f32 v46, v83, v46
	v_mul_f32_e32 v83, v89, v93
	v_mul_f32_e32 v47, v82, v47
	v_cvt_pk_bf16_f32 v47, v83, v47
	v_lshl_add_u64 v[82:83], v[40:41], 0, s[50:51]
	flat_store_dwordx4 v[82:83], v[44:47]
	global_load_dword v98, v135, s[44:45] offset:4
	global_load_dwordx2 v[94:95], v74, s[42:43] offset:512
	v_mov_b32_e32 v46, v16
	v_mov_b32_e32 v47, v68
	v_mov_b32_e32 v44, v22
	v_mov_b32_e32 v45, v66
	s_waitcnt vmcnt(0)
	v_pk_mul_f32 v[82:83], v[46:47], v[94:95]
	s_nop 0
	v_add_f32_e32 v82, v98, v82
	v_add_f32_e32 v99, v82, v83
	v_mov_b32_e32 v82, v17
	v_mov_b32_e32 v83, v69
	v_pk_mul_f32 v[84:85], v[82:83], v[94:95]
	v_pk_mul_f32 v[92:93], v[44:45], v[94:95]
	v_add_f32_e32 v84, v98, v84
	v_add_f32_e32 v100, v84, v85
	v_mov_b32_e32 v84, v18
	v_mov_b32_e32 v85, v70
	v_pk_mul_f32 v[86:87], v[84:85], v[94:95]
	v_add_f32_e32 v92, v98, v92
	v_add_f32_e32 v86, v98, v86
	v_add_f32_e32 v101, v86, v87
	v_mov_b32_e32 v86, v19
	v_mov_b32_e32 v87, v71
	v_pk_mul_f32 v[88:89], v[86:87], v[94:95]
	v_add_f32_e32 v105, v92, v93
	v_add_f32_e32 v88, v98, v88
	v_add_f32_e32 v102, v88, v89
	v_mov_b32_e32 v88, v20
	v_mov_b32_e32 v89, v64
	v_pk_mul_f32 v[90:91], v[88:89], v[94:95]
	v_mov_b32_e32 v92, v23
	v_add_f32_e32 v90, v98, v90
	v_add_f32_e32 v103, v90, v91
	v_mov_b32_e32 v90, v21
	v_mov_b32_e32 v91, v65
	v_mov_b32_e32 v93, v67
	v_pk_mul_f32 v[96:97], v[90:91], v[94:95]
	v_pk_mul_f32 v[94:95], v[92:93], v[94:95]
	v_add_f32_e32 v96, v98, v96
	v_add_f32_e32 v94, v98, v94
	v_add_f32_e32 v98, v94, v95
	v_mad_i64_i32 v[94:95], s[50:51], s62, v134, v[42:43]
	v_add_f32_e32 v104, v96, v97
	flat_load_dwordx4 v[94:97], v[94:95] nt
	s_lshl_b64 s[50:51], s[62:63], 12
	s_waitcnt vmcnt(0) lgkmcnt(0)
	v_lshlrev_b32_e32 v106, 16, v94
	v_and_b32_e32 v94, 0xffff0000, v94
	v_lshlrev_b32_e32 v107, 16, v95
	v_and_b32_e32 v95, 0xffff0000, v95
	v_mul_f32_e32 v99, v99, v106
	v_mul_f32_e32 v94, v100, v94
	v_lshlrev_b32_e32 v108, 16, v96
	v_and_b32_e32 v96, 0xffff0000, v96
	v_cvt_pk_bf16_f32 v94, v99, v94
	v_mul_f32_e32 v99, v101, v107
	v_mul_f32_e32 v95, v102, v95
	v_lshlrev_b32_e32 v109, 16, v97
	v_and_b32_e32 v97, 0xffff0000, v97
	v_cvt_pk_bf16_f32 v95, v99, v95
	v_mul_f32_e32 v99, v103, v108
	v_mul_f32_e32 v96, v104, v96
	v_cvt_pk_bf16_f32 v96, v99, v96
	v_mul_f32_e32 v99, v105, v109
	v_mul_f32_e32 v97, v98, v97
	v_cvt_pk_bf16_f32 v97, v99, v97
	v_lshl_add_u64 v[98:99], v[40:41], 0, s[50:51]
	flat_store_dwordx4 v[98:99], v[94:97]
	global_load_dword v112, v135, s[44:45] offset:8
	s_nop 0
	global_load_dwordx3 v[94:96], v74, s[42:43] offset:1024
	v_mov_b32_e32 v97, v60
	v_mov_b32_e32 v103, v63
	v_mov_b32_e32 v105, v56
	v_mov_b32_e32 v107, v57
	s_waitcnt vmcnt(0)
	v_mov_b32_e32 v110, v95
	v_mov_b32_e32 v111, v96
	v_fma_f32 v100, v16, v94, v112
	v_fma_f32 v101, v17, v94, v112
	v_fma_f32 v102, v18, v94, v112
	v_fma_f32 v104, v19, v94, v112
	v_fma_f32 v106, v20, v94, v112
	v_fma_f32 v113, v21, v94, v112
	v_fma_f32 v96, v22, v94, v112
	v_fmac_f32_e32 v112, v23, v94
	v_mov_b32_e32 v94, v66
	v_mov_b32_e32 v95, v58
	v_pk_mul_f32 v[108:109], v[94:95], v[110:111]
	s_nop 0
	v_add_f32_e32 v66, v96, v108
	v_mov_b32_e32 v96, v68
	v_pk_mul_f32 v[98:99], v[96:97], v[110:111]
	v_mov_b32_e32 v108, v67
	v_add_f32_e32 v68, v100, v98
	v_add_f32_e32 v114, v68, v99
	v_mov_b32_e32 v98, v69
	v_mov_b32_e32 v99, v61
	v_pk_mul_f32 v[68:69], v[98:99], v[110:111]
	v_mov_b32_e32 v100, v70
	v_add_f32_e32 v68, v101, v68
	v_mov_b32_e32 v101, v62
	v_add_f32_e32 v115, v68, v69
	v_pk_mul_f32 v[68:69], v[100:101], v[110:111]
	s_nop 0
	v_add_f32_e32 v68, v102, v68
	v_mov_b32_e32 v102, v71
	v_add_f32_e32 v70, v68, v69
	v_pk_mul_f32 v[68:69], v[102:103], v[110:111]
	s_nop 0
	v_add_f32_e32 v68, v104, v68
	v_mov_b32_e32 v104, v64
	v_add_f32_e32 v71, v68, v69
	v_pk_mul_f32 v[68:69], v[104:105], v[110:111]
	s_nop 0
	v_add_f32_e32 v64, v106, v68
	v_mov_b32_e32 v106, v65
	v_add_f32_e32 v68, v64, v69
	v_pk_mul_f32 v[64:65], v[106:107], v[110:111]
	s_nop 0
	v_add_f32_e32 v64, v113, v64
	v_add_f32_e32 v113, v66, v109
	v_mov_b32_e32 v109, v59
	v_add_f32_e32 v69, v64, v65
	v_pk_mul_f32 v[64:65], v[108:109], v[110:111]
	s_nop 0
	v_add_f32_e32 v64, v112, v64
	v_add_f32_e32 v110, v64, v65
	v_mad_i64_i32 v[64:65], s[50:51], s60, v134, v[42:43]
	flat_load_dwordx4 v[64:67], v[64:65] nt
	s_lshl_b64 s[50:51], s[60:61], 12
	s_waitcnt vmcnt(0) lgkmcnt(0)
	v_lshlrev_b32_e32 v111, 16, v64
	v_and_b32_e32 v64, 0xffff0000, v64
	v_lshlrev_b32_e32 v112, 16, v65
	v_and_b32_e32 v65, 0xffff0000, v65
	v_lshlrev_b32_e32 v116, 16, v66
	v_and_b32_e32 v66, 0xffff0000, v66
	v_lshlrev_b32_e32 v117, 16, v67
	v_and_b32_e32 v67, 0xffff0000, v67
	v_mul_f32_e32 v64, v115, v64
	v_mul_f32_e32 v65, v71, v65
	v_mul_f32_e32 v68, v68, v116
	v_mul_f32_e32 v66, v69, v66
	v_mul_f32_e32 v111, v114, v111
	v_cvt_pk_bf16_f32 v64, v111, v64
	v_mul_f32_e32 v70, v70, v112
	v_cvt_pk_bf16_f32 v65, v70, v65
	v_cvt_pk_bf16_f32 v66, v68, v66
	v_mul_f32_e32 v68, v113, v117
	v_mul_f32_e32 v67, v110, v67
	v_cvt_pk_bf16_f32 v67, v68, v67
	v_lshl_add_u64 v[68:69], v[40:41], 0, s[50:51]
	flat_store_dwordx4 v[68:69], v[64:67]
	global_load_dword v68, v135, s[44:45] offset:12
	s_nop 0
	global_load_dwordx4 v[110:113], v74, s[42:43] offset:1536 nt
	s_waitcnt vmcnt(0)
	v_pk_mul_f32 v[66:67], v[46:47], v[110:111]
	s_nop 0
	v_add_f32_e32 v66, v68, v66
	v_add_f32_e32 v70, v66, v67
	v_pk_mul_f32 v[66:67], v[82:83], v[110:111]
	v_pk_mul_f32 v[64:65], v[44:45], v[110:111]
	v_add_f32_e32 v66, v68, v66
	v_add_f32_e32 v71, v66, v67
	v_pk_mul_f32 v[66:67], v[84:85], v[110:111]
	v_add_f32_e32 v64, v68, v64
	v_add_f32_e32 v66, v68, v66
	v_add_f32_e32 v114, v66, v67
	v_pk_mul_f32 v[66:67], v[86:87], v[110:111]
	s_nop 0
	v_add_f32_e32 v66, v68, v66
	v_add_f32_e32 v115, v66, v67
	v_pk_mul_f32 v[66:67], v[88:89], v[110:111]
	s_nop 0
	v_add_f32_e32 v66, v68, v66
	v_add_f32_e32 v116, v66, v67
	v_pk_mul_f32 v[66:67], v[90:91], v[110:111]
	s_nop 0
	v_add_f32_e32 v66, v68, v66
	v_add_f32_e32 v117, v66, v67
	v_add_f32_e32 v66, v64, v65
	v_pk_mul_f32 v[64:65], v[92:93], v[110:111]
	v_mov_b32_e32 v67, v52
	v_add_f32_e32 v64, v68, v64
	v_add_f32_e32 v118, v64, v65
	v_mov_b32_e32 v64, v58
	v_mov_b32_e32 v65, v50
	v_pk_mul_f32 v[110:111], v[64:65], v[112:113]
	s_nop 0
	v_add_f32_e32 v58, v66, v110
	v_mov_b32_e32 v66, v60
	v_pk_mul_f32 v[68:69], v[66:67], v[112:113]
	s_nop 0
	v_add_f32_e32 v60, v70, v68
	v_add_f32_e32 v119, v60, v69
	v_mov_b32_e32 v60, v61
	v_mov_b32_e32 v61, v53
	v_pk_mul_f32 v[68:69], v[60:61], v[112:113]
	s_nop 0
	v_add_f32_e32 v68, v71, v68
	v_add_f32_e32 v120, v68, v69
	v_mov_b32_e32 v68, v62
	v_mov_b32_e32 v69, v54
	v_pk_mul_f32 v[70:71], v[68:69], v[112:113]
	s_nop 0
	v_add_f32_e32 v62, v114, v70
	v_add_f32_e32 v121, v62, v71
	v_mov_b32_e32 v62, v63
	v_mov_b32_e32 v63, v55
	v_pk_mul_f32 v[70:71], v[62:63], v[112:113]
	s_nop 0
	v_add_f32_e32 v70, v115, v70
	v_add_f32_e32 v122, v70, v71
	v_mov_b32_e32 v70, v56
	v_mov_b32_e32 v71, v48
	v_pk_mul_f32 v[114:115], v[70:71], v[112:113]
	s_nop 0
	v_add_f32_e32 v56, v116, v114
	v_add_f32_e32 v116, v56, v115
	v_mov_b32_e32 v56, v57
	v_mov_b32_e32 v57, v49
	v_pk_mul_f32 v[114:115], v[56:57], v[112:113]
	s_nop 0
	v_add_f32_e32 v110, v117, v114
	v_add_f32_e32 v114, v110, v115
	v_add_f32_e32 v115, v58, v111
	v_mov_b32_e32 v58, v59
	v_mov_b32_e32 v59, v51
	v_pk_mul_f32 v[110:111], v[58:59], v[112:113]
	s_nop 0
	v_add_f32_e32 v110, v118, v110
	v_add_f32_e32 v117, v110, v111
	v_mad_i64_i32 v[110:111], s[50:51], s58, v134, v[42:43]
	flat_load_dwordx4 v[110:113], v[110:111] nt
	s_lshl_b64 s[50:51], s[58:59], 12
	s_waitcnt vmcnt(0) lgkmcnt(0)
	v_lshlrev_b32_e32 v118, 16, v110
	v_and_b32_e32 v110, 0xffff0000, v110
	v_lshlrev_b32_e32 v123, 16, v111
	v_and_b32_e32 v111, 0xffff0000, v111
	v_lshlrev_b32_e32 v124, 16, v112
	v_and_b32_e32 v112, 0xffff0000, v112
	v_lshlrev_b32_e32 v125, 16, v113
	v_and_b32_e32 v113, 0xffff0000, v113
	v_mul_f32_e32 v118, v119, v118
	v_mul_f32_e32 v110, v120, v110
	v_mul_f32_e32 v111, v122, v111
	v_mul_f32_e32 v112, v114, v112
	v_mul_f32_e32 v114, v115, v125
	v_mul_f32_e32 v113, v117, v113
	v_cvt_pk_bf16_f32 v110, v118, v110
	v_mul_f32_e32 v118, v121, v123
	v_cvt_pk_bf16_f32 v111, v118, v111
	v_mul_f32_e32 v116, v116, v124
	v_cvt_pk_bf16_f32 v112, v116, v112
	v_cvt_pk_bf16_f32 v113, v114, v113
	v_lshl_add_u64 v[114:115], v[40:41], 0, s[50:51]
	flat_store_dwordx4 v[114:115], v[110:113]
	global_load_dword v116, v135, s[44:45] offset:16
	s_nop 0
	global_load_dwordx4 v[110:113], v74, s[42:43] offset:2048 nt
	global_load_dword v137, v74, s[42:43] offset:2064
	s_waitcnt vmcnt(0)
	v_mov_b32_e32 v114, v111
	v_mov_b32_e32 v115, v112
	v_fma_f32 v117, v16, v110, v116
	v_fma_f32 v118, v17, v110, v116
	v_fma_f32 v119, v18, v110, v116
	v_fma_f32 v120, v19, v110, v116
	v_fma_f32 v121, v20, v110, v116
	v_fma_f32 v122, v21, v110, v116
	v_fma_f32 v112, v22, v110, v116
	v_fmac_f32_e32 v116, v23, v110
	v_pk_mul_f32 v[110:111], v[94:95], v[114:115]
	v_mov_b32_e32 v136, v113
	v_add_f32_e32 v110, v112, v110
	v_pk_mul_f32 v[112:113], v[96:97], v[114:115]
	s_nop 0
	v_add_f32_e32 v112, v117, v112
	v_add_f32_e32 v117, v112, v113
	v_pk_mul_f32 v[112:113], v[98:99], v[114:115]
	s_nop 0
	v_add_f32_e32 v112, v118, v112
	v_add_f32_e32 v118, v112, v113
	v_pk_mul_f32 v[112:113], v[100:101], v[114:115]
	s_nop 0
	v_add_f32_e32 v112, v119, v112
	v_add_f32_e32 v123, v112, v113
	v_pk_mul_f32 v[112:113], v[102:103], v[114:115]
	s_nop 0
	v_add_f32_e32 v112, v120, v112
	v_add_f32_e32 v120, v112, v113
	v_pk_mul_f32 v[112:113], v[104:105], v[114:115]
	s_nop 0
	v_add_f32_e32 v112, v121, v112
	v_add_f32_e32 v138, v112, v113
	v_pk_mul_f32 v[112:113], v[106:107], v[114:115]
	v_mov_b32_e32 v121, v32
	v_add_f32_e32 v112, v122, v112
	v_add_f32_e32 v140, v112, v113
	v_add_f32_e32 v112, v110, v111
	v_pk_mul_f32 v[110:111], v[108:109], v[114:115]
	v_mov_b32_e32 v113, v36
	v_add_f32_e32 v110, v116, v110
	v_add_f32_e32 v141, v110, v111
	v_mov_b32_e32 v110, v50
	v_mov_b32_e32 v111, v34
	v_pk_mul_f32 v[124:125], v[110:111], v[136:137]
	v_mov_b32_e32 v116, v54
	v_add_f32_e32 v124, v112, v124
	v_mov_b32_e32 v112, v52
	v_pk_mul_f32 v[114:115], v[112:113], v[136:137]
	s_nop 0
	v_add_f32_e32 v50, v117, v114
	v_add_f32_e32 v50, v50, v115
	v_mov_b32_e32 v114, v53
	v_mov_b32_e32 v115, v37
	v_pk_mul_f32 v[52:53], v[114:115], v[136:137]
	v_mov_b32_e32 v117, v38
	v_add_f32_e32 v52, v118, v52
	v_pk_mul_f32 v[118:119], v[116:117], v[136:137]
	v_add_f32_e32 v52, v52, v53
	v_add_f32_e32 v53, v123, v118
	v_add_f32_e32 v53, v53, v119
	v_mov_b32_e32 v118, v55
	v_mov_b32_e32 v119, v39
	v_pk_mul_f32 v[54:55], v[118:119], v[136:137]
	s_nop 0
	v_add_f32_e32 v54, v120, v54
	v_mov_b32_e32 v120, v48
	v_pk_mul_f32 v[122:123], v[120:121], v[136:137]
	v_add_f32_e32 v54, v54, v55
	v_add_f32_e32 v48, v138, v122
	v_add_f32_e32 v48, v48, v123
	v_mov_b32_e32 v122, v49
	v_mov_b32_e32 v123, v33
	v_pk_mul_f32 v[138:139], v[122:123], v[136:137]
	s_nop 0
	v_add_f32_e32 v49, v140, v138
	v_add_f32_e32 v55, v49, v139
	v_add_f32_e32 v49, v124, v125
	v_mov_b32_e32 v124, v51
	v_mov_b32_e32 v125, v35
	v_pk_mul_f32 v[136:137], v[124:125], v[136:137]
	s_nop 0
	v_add_f32_e32 v51, v141, v136
	v_add_f32_e32 v51, v51, v137
	v_mad_i64_i32 v[136:137], s[50:51], s48, v134, v[42:43]
	flat_load_dwordx4 v[136:139], v[136:137] nt
	s_lshl_b64 s[48:49], s[48:49], 12
	s_waitcnt vmcnt(0) lgkmcnt(0)
	v_lshlrev_b32_e32 v140, 16, v136
	v_and_b32_e32 v136, 0xffff0000, v136
	v_lshlrev_b32_e32 v141, 16, v137
	v_and_b32_e32 v137, 0xffff0000, v137
	v_lshlrev_b32_e32 v142, 16, v138
	v_mul_f32_e32 v50, v50, v140
	v_mul_f32_e32 v52, v52, v136
	v_and_b32_e32 v138, 0xffff0000, v138
	v_lshlrev_b32_e32 v143, 16, v139
	v_and_b32_e32 v139, 0xffff0000, v139
	v_cvt_pk_bf16_f32 v52, v50, v52
	v_mul_f32_e32 v50, v53, v141
	v_mul_f32_e32 v53, v54, v137
	v_mul_f32_e32 v48, v48, v142
	v_cvt_pk_bf16_f32 v53, v50, v53
	v_mul_f32_e32 v50, v55, v138
	v_cvt_pk_bf16_f32 v54, v48, v50
	v_mul_f32_e32 v48, v49, v143
	v_mul_f32_e32 v49, v51, v139
	v_cvt_pk_bf16_f32 v55, v48, v49
	v_lshl_add_u64 v[48:49], v[40:41], 0, s[48:49]
	flat_store_dwordx4 v[48:49], v[52:55]
	global_load_dword v136, v135, s[44:45] offset:20
	global_load_dwordx2 v[144:145], v74, s[42:43] offset:2576
	s_nop 0
	global_load_dwordx4 v[48:51], v74, s[42:43] offset:2560 nt
	s_waitcnt vmcnt(0)
	v_pk_mul_f32 v[54:55], v[46:47], v[48:49]
	s_nop 0
	v_add_f32_e32 v54, v136, v54
	v_add_f32_e32 v137, v54, v55
	v_pk_mul_f32 v[54:55], v[82:83], v[48:49]
	v_pk_mul_f32 v[52:53], v[44:45], v[48:49]
	v_add_f32_e32 v54, v136, v54
	v_add_f32_e32 v138, v54, v55
	v_pk_mul_f32 v[54:55], v[84:85], v[48:49]
	v_add_f32_e32 v52, v136, v52
	v_add_f32_e32 v54, v136, v54
	v_add_f32_e32 v139, v54, v55
	v_pk_mul_f32 v[54:55], v[86:87], v[48:49]
	v_add_f32_e32 v52, v52, v53
	v_add_f32_e32 v54, v136, v54
	v_add_f32_e32 v140, v54, v55
	v_pk_mul_f32 v[54:55], v[88:89], v[48:49]
	s_nop 0
	v_add_f32_e32 v54, v136, v54
	v_add_f32_e32 v141, v54, v55
	v_pk_mul_f32 v[54:55], v[90:91], v[48:49]
	v_pk_mul_f32 v[48:49], v[92:93], v[48:49]
	v_add_f32_e32 v54, v136, v54
	v_add_f32_e32 v48, v136, v48
	v_add_f32_e32 v54, v54, v55
	v_add_f32_e32 v55, v48, v49
	v_pk_mul_f32 v[48:49], v[64:65], v[50:51]
	s_nop 0
	v_add_f32_e32 v48, v52, v48
	v_pk_mul_f32 v[52:53], v[66:67], v[50:51]
	s_nop 0
	v_add_f32_e32 v52, v137, v52
	v_add_f32_e32 v136, v52, v53
	v_pk_mul_f32 v[52:53], v[60:61], v[50:51]
	s_nop 0
	v_add_f32_e32 v52, v138, v52
	v_add_f32_e32 v137, v52, v53
	v_pk_mul_f32 v[52:53], v[68:69], v[50:51]
	s_nop 0
	v_add_f32_e32 v52, v139, v52
	v_add_f32_e32 v138, v52, v53
	v_pk_mul_f32 v[52:53], v[62:63], v[50:51]
	s_nop 0
	v_add_f32_e32 v52, v140, v52
	v_add_f32_e32 v139, v52, v53
	v_pk_mul_f32 v[52:53], v[70:71], v[50:51]
	s_nop 0
	v_add_f32_e32 v52, v141, v52
	v_add_f32_e32 v146, v52, v53
	v_pk_mul_f32 v[52:53], v[56:57], v[50:51]
	s_nop 0
	v_add_f32_e32 v52, v54, v52
	v_add_f32_e32 v147, v52, v53
	v_add_f32_e32 v52, v48, v49
	v_pk_mul_f32 v[48:49], v[58:59], v[50:51]
	v_mov_b32_e32 v50, v36
	v_add_f32_e32 v48, v55, v48
	v_add_f32_e32 v148, v48, v49
	v_mov_b32_e32 v48, v34
	v_mov_b32_e32 v49, v26
	v_pk_mul_f32 v[140:141], v[48:49], v[144:145]
	v_mov_b32_e32 v51, v28
	v_add_f32_e32 v34, v52, v140
	v_pk_mul_f32 v[52:53], v[50:51], v[144:145]
	v_add_f32_e32 v141, v34, v141
	v_add_f32_e32 v36, v136, v52
	v_add_f32_e32 v136, v36, v53
	v_mov_b32_e32 v36, v37
	v_mov_b32_e32 v37, v29
	v_pk_mul_f32 v[52:53], v[36:37], v[144:145]
	v_mov_b32_e32 v34, v35
	v_add_f32_e32 v52, v137, v52
	v_add_f32_e32 v137, v52, v53
	v_mov_b32_e32 v52, v38
	v_mov_b32_e32 v53, v30
	v_pk_mul_f32 v[54:55], v[52:53], v[144:145]
	v_mov_b32_e32 v35, v27
	v_add_f32_e32 v38, v138, v54
	v_add_f32_e32 v138, v38, v55
	v_mov_b32_e32 v38, v39
	v_mov_b32_e32 v39, v31
	v_pk_mul_f32 v[54:55], v[38:39], v[144:145]
	s_nop 0
	v_add_f32_e32 v54, v139, v54
	v_add_f32_e32 v139, v54, v55
	v_mov_b32_e32 v54, v32
	v_mov_b32_e32 v55, v24
	v_pk_mul_f32 v[142:143], v[54:55], v[144:145]
	s_nop 0
	v_add_f32_e32 v32, v146, v142
	v_add_f32_e32 v140, v32, v143
	v_mov_b32_e32 v32, v33
	v_mov_b32_e32 v33, v25
	v_pk_mul_f32 v[142:143], v[32:33], v[144:145]
	v_pk_mul_f32 v[144:145], v[34:35], v[144:145]
	v_add_f32_e32 v142, v147, v142
	v_add_f32_e32 v142, v142, v143
	v_add_f32_e32 v143, v148, v144
	v_add_f32_e32 v143, v143, v145
	v_mad_i64_i32 v[144:145], s[48:49], s54, v134, v[42:43]
	flat_load_dwordx4 v[144:147], v[144:145] nt
	s_lshl_b64 s[48:49], s[54:55], 12
	s_waitcnt vmcnt(0) lgkmcnt(0)
	v_lshlrev_b32_e32 v148, 16, v144
	v_and_b32_e32 v144, 0xffff0000, v144
	v_lshlrev_b32_e32 v149, 16, v145
	v_and_b32_e32 v145, 0xffff0000, v145
	v_mul_f32_e32 v136, v136, v148
	v_mul_f32_e32 v137, v137, v144
	v_lshlrev_b32_e32 v150, 16, v146
	v_and_b32_e32 v146, 0xffff0000, v146
	v_cvt_pk_bf16_f32 v136, v136, v137
	v_mul_f32_e32 v137, v138, v149
	v_mul_f32_e32 v138, v139, v145
	v_lshlrev_b32_e32 v151, 16, v147
	v_and_b32_e32 v147, 0xffff0000, v147
	v_cvt_pk_bf16_f32 v137, v137, v138
	v_mul_f32_e32 v138, v140, v150
	v_mul_f32_e32 v139, v142, v146
	v_cvt_pk_bf16_f32 v138, v138, v139
	v_mul_f32_e32 v139, v141, v151
	v_mul_f32_e32 v140, v143, v147
	v_cvt_pk_bf16_f32 v139, v139, v140
	v_lshl_add_u64 v[140:141], v[40:41], 0, s[48:49]
	flat_store_dwordx4 v[140:141], v[136:139]
	global_load_dword v143, v135, s[44:45] offset:24
	s_nop 0
	global_load_dwordx4 v[136:139], v74, s[42:43] offset:3072 nt
	global_load_dwordx3 v[140:142], v74, s[42:43] offset:3088
	s_waitcnt vmcnt(0)
	v_mov_b32_e32 v144, v137
	v_mov_b32_e32 v145, v138
	v_mov_b32_e32 v138, v139
	v_mov_b32_e32 v139, v140
	v_mov_b32_e32 v140, v141
	v_mov_b32_e32 v141, v142
	v_fma_f32 v137, v16, v136, v143
	v_fma_f32 v142, v17, v136, v143
	v_fma_f32 v146, v18, v136, v143
	v_fma_f32 v18, v22, v136, v143
	v_pk_mul_f32 v[16:17], v[94:95], v[144:145]
	v_fma_f32 v147, v19, v136, v143
	v_add_f32_e32 v16, v18, v16
	v_pk_mul_f32 v[18:19], v[96:97], v[144:145]
	v_fma_f32 v20, v20, v136, v143
	v_add_f32_e32 v18, v137, v18
	v_add_f32_e32 v22, v18, v19
	v_pk_mul_f32 v[18:19], v[98:99], v[144:145]
	v_fma_f32 v21, v21, v136, v143
	v_add_f32_e32 v18, v142, v18
	v_fmac_f32_e32 v143, v23, v136
	v_add_f32_e32 v23, v18, v19
	v_pk_mul_f32 v[18:19], v[100:101], v[144:145]
	s_nop 0
	v_add_f32_e32 v18, v146, v18
	v_add_f32_e32 v94, v18, v19
	v_pk_mul_f32 v[18:19], v[102:103], v[144:145]
	s_nop 0
	v_add_f32_e32 v18, v147, v18
	v_add_f32_e32 v95, v18, v19
	v_pk_mul_f32 v[18:19], v[104:105], v[144:145]
	s_nop 0
	v_add_f32_e32 v18, v20, v18
	v_add_f32_e32 v20, v18, v19
	v_pk_mul_f32 v[18:19], v[106:107], v[144:145]
	s_nop 0
	v_add_f32_e32 v18, v21, v18
	v_add_f32_e32 v21, v18, v19
	v_add_f32_e32 v18, v16, v17
	v_pk_mul_f32 v[16:17], v[108:109], v[144:145]
	s_nop 0
	v_add_f32_e32 v16, v143, v16
	v_add_f32_e32 v96, v16, v17
	v_pk_mul_f32 v[16:17], v[110:111], v[138:139]
	s_nop 0
	v_add_f32_e32 v16, v18, v16
	v_pk_mul_f32 v[18:19], v[112:113], v[138:139]
	s_nop 0
	v_add_f32_e32 v18, v22, v18
	v_add_f32_e32 v22, v18, v19
	v_pk_mul_f32 v[18:19], v[114:115], v[138:139]
	s_nop 0
	v_add_f32_e32 v18, v23, v18
	v_add_f32_e32 v23, v18, v19
	v_pk_mul_f32 v[18:19], v[116:117], v[138:139]
	s_nop 0
	v_add_f32_e32 v18, v94, v18
	v_add_f32_e32 v94, v18, v19
	v_pk_mul_f32 v[18:19], v[118:119], v[138:139]
	s_nop 0
	v_add_f32_e32 v18, v95, v18
	v_add_f32_e32 v95, v18, v19
	v_pk_mul_f32 v[18:19], v[120:121], v[138:139]
	s_nop 0
	v_add_f32_e32 v18, v20, v18
	v_add_f32_e32 v97, v18, v19
	v_pk_mul_f32 v[18:19], v[122:123], v[138:139]
	s_nop 0
	v_add_f32_e32 v18, v21, v18
	v_add_f32_e32 v98, v18, v19
	v_add_f32_e32 v18, v16, v17
	v_pk_mul_f32 v[16:17], v[124:125], v[138:139]
	v_mov_b32_e32 v19, v1
	v_add_f32_e32 v16, v96, v16
	v_add_f32_e32 v96, v16, v17
	v_mov_b32_e32 v16, v26
	v_mov_b32_e32 v17, v6
	v_pk_mul_f32 v[20:21], v[16:17], v[140:141]
	v_mov_b32_e32 v16, v28
	v_mov_b32_e32 v17, v0
	v_add_f32_e32 v26, v18, v20
	v_pk_mul_f32 v[16:17], v[16:17], v[140:141]
	v_mov_b32_e32 v18, v29
	v_add_f32_e32 v16, v22, v16
	v_pk_mul_f32 v[18:19], v[18:19], v[140:141]
	v_add_f32_e32 v16, v16, v17
	v_add_f32_e32 v17, v23, v18
	v_add_f32_e32 v17, v17, v19
	v_mov_b32_e32 v18, v30
	v_mov_b32_e32 v19, v2
	v_pk_mul_f32 v[18:19], v[18:19], v[140:141]
	v_mov_b32_e32 v22, v31
	v_mov_b32_e32 v23, v3
	v_add_f32_e32 v18, v94, v18
	v_pk_mul_f32 v[22:23], v[22:23], v[140:141]
	v_add_f32_e32 v18, v18, v19
	v_add_f32_e32 v19, v95, v22
	v_add_f32_e32 v19, v19, v23
	v_mov_b32_e32 v22, v24
	v_mov_b32_e32 v23, v4
	v_pk_mul_f32 v[22:23], v[22:23], v[140:141]
	v_mov_b32_e32 v24, v27
	v_add_f32_e32 v20, v97, v22
	v_add_f32_e32 v20, v20, v23
	v_mov_b32_e32 v22, v25
	v_mov_b32_e32 v23, v5
	v_pk_mul_f32 v[22:23], v[22:23], v[140:141]
	v_mov_b32_e32 v25, v7
	v_add_f32_e32 v22, v98, v22
	v_pk_mul_f32 v[24:25], v[24:25], v[140:141]
	v_add_f32_e32 v22, v22, v23
	v_add_f32_e32 v23, v96, v24
	v_add_f32_e32 v23, v23, v25
	v_mad_i64_i32 v[24:25], s[48:49], s52, v134, v[42:43]
	v_add_f32_e32 v21, v26, v21
	flat_load_dwordx4 v[24:27], v[24:25] nt
	s_lshl_b64 s[48:49], s[52:53], 12
	s_waitcnt vmcnt(0) lgkmcnt(0)
	v_lshlrev_b32_e32 v28, 16, v24
	v_and_b32_e32 v24, 0xffff0000, v24
	v_lshlrev_b32_e32 v29, 16, v25
	v_and_b32_e32 v25, 0xffff0000, v25
	v_mul_f32_e32 v16, v16, v28
	v_mul_f32_e32 v17, v17, v24
	v_lshlrev_b32_e32 v30, 16, v26
	v_and_b32_e32 v26, 0xffff0000, v26
	v_cvt_pk_bf16_f32 v16, v16, v17
	v_mul_f32_e32 v17, v18, v29
	v_mul_f32_e32 v18, v19, v25
	v_lshlrev_b32_e32 v31, 16, v27
	v_and_b32_e32 v27, 0xffff0000, v27
	v_cvt_pk_bf16_f32 v17, v17, v18
	v_mul_f32_e32 v18, v20, v30
	v_mul_f32_e32 v19, v22, v26
	v_cvt_pk_bf16_f32 v18, v18, v19
	v_mul_f32_e32 v19, v21, v31
	v_mul_f32_e32 v20, v23, v27
	v_cvt_pk_bf16_f32 v19, v19, v20
	v_lshl_add_u64 v[20:21], v[40:41], 0, s[48:49]
	flat_store_dwordx4 v[20:21], v[16:19]
	global_load_dword v28, v135, s[44:45] offset:28
	s_nop 0
	global_load_dwordx4 v[16:19], v74, s[42:43] offset:3600 nt
	global_load_dwordx4 v[20:23], v74, s[42:43] offset:3584 nt
	s_waitcnt vmcnt(0)
	v_pk_mul_f32 v[26:27], v[46:47], v[20:21]
	s_nop 0
	v_add_f32_e32 v26, v28, v26
	v_add_f32_e32 v29, v26, v27
	v_pk_mul_f32 v[26:27], v[82:83], v[20:21]
	v_pk_mul_f32 v[24:25], v[44:45], v[20:21]
	v_add_f32_e32 v26, v28, v26
	v_add_f32_e32 v30, v26, v27
	v_pk_mul_f32 v[26:27], v[84:85], v[20:21]
	v_add_f32_e32 v24, v28, v24
	v_add_f32_e32 v26, v28, v26
	v_add_f32_e32 v31, v26, v27
	v_pk_mul_f32 v[26:27], v[86:87], v[20:21]
	v_add_f32_e32 v24, v24, v25
	v_add_f32_e32 v26, v28, v26
	v_add_f32_e32 v44, v26, v27
	v_pk_mul_f32 v[26:27], v[88:89], v[20:21]
	s_nop 0
	v_add_f32_e32 v26, v28, v26
	v_add_f32_e32 v45, v26, v27
	v_pk_mul_f32 v[26:27], v[90:91], v[20:21]
	v_pk_mul_f32 v[20:21], v[92:93], v[20:21]
	v_add_f32_e32 v26, v28, v26
	v_add_f32_e32 v20, v28, v20
	v_add_f32_e32 v26, v26, v27
	v_add_f32_e32 v27, v20, v21
	v_pk_mul_f32 v[20:21], v[64:65], v[22:23]
	s_nop 0
	v_add_f32_e32 v20, v24, v20
	v_pk_mul_f32 v[24:25], v[66:67], v[22:23]
	s_nop 0
	v_add_f32_e32 v24, v29, v24
	v_add_f32_e32 v28, v24, v25
	v_pk_mul_f32 v[24:25], v[60:61], v[22:23]
	s_nop 0
	v_add_f32_e32 v24, v30, v24
	v_add_f32_e32 v29, v24, v25
	v_pk_mul_f32 v[24:25], v[68:69], v[22:23]
	s_nop 0
	v_add_f32_e32 v24, v31, v24
	v_add_f32_e32 v30, v24, v25
	v_pk_mul_f32 v[24:25], v[62:63], v[22:23]
	s_nop 0
	v_add_f32_e32 v24, v44, v24
	v_add_f32_e32 v31, v24, v25
	v_pk_mul_f32 v[24:25], v[70:71], v[22:23]
	s_nop 0
	v_add_f32_e32 v24, v45, v24
	v_add_f32_e32 v44, v24, v25
	v_pk_mul_f32 v[24:25], v[56:57], v[22:23]
	s_nop 0
	v_add_f32_e32 v24, v26, v24
	v_add_f32_e32 v24, v24, v25
	v_add_f32_e32 v25, v20, v21
	v_pk_mul_f32 v[20:21], v[58:59], v[22:23]
	v_pk_mul_f32 v[22:23], v[50:51], v[16:17]
	v_add_f32_e32 v20, v27, v20
	v_add_f32_e32 v26, v20, v21
	v_pk_mul_f32 v[20:21], v[48:49], v[16:17]
	v_add_f32_e32 v22, v28, v22
	v_add_f32_e32 v20, v25, v20
	v_add_f32_e32 v25, v22, v23
	v_pk_mul_f32 v[22:23], v[36:37], v[16:17]
	v_add_f32_e32 v20, v20, v21
	v_add_f32_e32 v22, v29, v22
	v_add_f32_e32 v27, v22, v23
	v_pk_mul_f32 v[22:23], v[52:53], v[16:17]
	s_nop 0
	v_add_f32_e32 v22, v30, v22
	v_add_f32_e32 v28, v22, v23
	v_pk_mul_f32 v[22:23], v[38:39], v[16:17]
	s_nop 0
	v_add_f32_e32 v22, v31, v22
	v_add_f32_e32 v29, v22, v23
	v_pk_mul_f32 v[22:23], v[54:55], v[16:17]
	s_nop 0
	v_add_f32_e32 v22, v44, v22
	v_add_f32_e32 v30, v22, v23
	v_pk_mul_f32 v[22:23], v[32:33], v[16:17]
	v_pk_mul_f32 v[16:17], v[34:35], v[16:17]
	v_add_f32_e32 v22, v24, v22
	v_add_f32_e32 v16, v26, v16
	v_add_f32_e32 v21, v16, v17
	v_mov_b32_e32 v17, v14
	v_mov_b32_e32 v14, v7
	v_mov_b32_e32 v16, v6
	v_pk_mul_f32 v[6:7], v[14:15], v[18:19]
	v_mov_b32_e32 v14, v5
	v_mov_b32_e32 v15, v13
	v_add_f32_e32 v22, v22, v23
	v_pk_mul_f32 v[14:15], v[14:15], v[18:19]
	v_pk_mul_f32 v[16:17], v[16:17], v[18:19]
	v_add_f32_e32 v5, v22, v14
	v_add_f32_e32 v13, v5, v15
	v_mov_b32_e32 v5, v12
	v_pk_mul_f32 v[4:5], v[4:5], v[18:19]
	v_add_f32_e32 v16, v20, v16
	v_add_f32_e32 v4, v30, v4
	v_add_f32_e32 v12, v4, v5
	v_mov_b32_e32 v4, v3
	v_mov_b32_e32 v5, v11
	v_pk_mul_f32 v[4:5], v[4:5], v[18:19]
	v_add_f32_e32 v6, v21, v6
	v_add_f32_e32 v3, v29, v4
	v_add_f32_e32 v4, v3, v5
	v_mov_b32_e32 v3, v10
	v_pk_mul_f32 v[2:3], v[2:3], v[18:19]
	v_add_f32_e32 v6, v6, v7
	v_add_f32_e32 v2, v28, v2
	v_add_f32_e32 v5, v2, v3
	v_mov_b32_e32 v2, v1
	v_mov_b32_e32 v3, v9
	v_pk_mul_f32 v[2:3], v[2:3], v[18:19]
	v_add_f32_e32 v7, v16, v17
	v_add_f32_e32 v1, v27, v2
	v_add_f32_e32 v9, v1, v3
	v_mov_b32_e32 v1, v8
	v_pk_mul_f32 v[0:1], v[0:1], v[18:19]
	s_nop 0
	v_add_f32_e32 v0, v25, v0
	v_add_f32_e32 v8, v0, v1
	v_mad_i64_i32 v[0:1], s[48:49], s4, v134, v[42:43]
	flat_load_dwordx4 v[0:3], v[0:1] nt
	s_lshl_b64 s[4:5], s[4:5], 12
	s_cmpk_gt_i32 s68, 0xff
	s_waitcnt vmcnt(0) lgkmcnt(0)
	v_lshlrev_b32_e32 v10, 16, v0
	v_and_b32_e32 v0, 0xffff0000, v0
	v_lshlrev_b32_e32 v11, 16, v1
	v_and_b32_e32 v1, 0xffff0000, v1
	v_lshlrev_b32_e32 v14, 16, v2
	v_and_b32_e32 v2, 0xffff0000, v2
	v_lshlrev_b32_e32 v15, 16, v3
	v_and_b32_e32 v3, 0xffff0000, v3
	v_mul_f32_e32 v0, v9, v0
	v_mul_f32_e32 v1, v4, v1
	v_mul_f32_e32 v4, v12, v14
	v_mul_f32_e32 v2, v13, v2
	v_mul_f32_e32 v8, v8, v10
	v_cvt_pk_bf16_f32 v0, v8, v0
	v_mul_f32_e32 v5, v5, v11
	v_cvt_pk_bf16_f32 v1, v5, v1
	v_cvt_pk_bf16_f32 v2, v4, v2
	v_mul_f32_e32 v4, v7, v15
	v_mul_f32_e32 v3, v6, v3
	v_cvt_pk_bf16_f32 v3, v4, v3
	v_lshl_add_u64 v[4:5], v[40:41], 0, s[4:5]
	flat_store_dwordx4 v[4:5], v[0:3]
	s_cbranch_scc0 .LBB0_342

.LBB0_365:
	s_ashr_i32 s12, s76, 1
	v_mov_b32_e32 v129, v148
	v_mov_b32_e32 v128, v149
	s_and_b32 s52, s12, 0xffffff80
	s_cmp_lt_i32 s79, 1
	v_add_u32_e32 v155, s58, v129
	v_lshl_add_u32 v156, v128, 3, s59
	s_cbranch_scc1 .LBB0_369
	s_mov_b64 s[48:49], 0
	s_cmp_eq_u32 s79, 1
	s_mov_b64 s[50:51], 0
	s_cbranch_scc0 .LBB0_368
	v_add_u32_e32 v128, s52, v155
	v_ashrrev_i32_e32 v129, 31, v128
	v_add_u32_e32 v144, s76, v156
	v_add_u32_e32 v130, s75, v155
	s_waitcnt lgkmcnt(0)
	v_lshl_add_u64 v[128:129], v[128:129], 2, s[4:5]
	v_mov_b64_e32 v[146:147], s[14:15]
	v_ashrrev_i32_e32 v145, 31, v144
	global_load_dword v157, v[128:129], off
	v_mad_i64_i32 v[162:163], s[50:51], v130, s62, v[146:147]
	v_lshlrev_b64 v[128:129], 1, v[144:145]
	v_lshl_add_u64 v[158:159], v[162:163], 0, v[128:129]
	flat_load_dwordx4 v[158:161], v[158:159] nt
	v_ashrrev_i32_e32 v131, 31, v130
	v_add_u32_e32 v144, 0x80, v144
	v_lshlrev_b64 v[130:131], 12, v[130:131]
	v_ashrrev_i32_e32 v145, 31, v144
	v_lshl_add_u64 v[166:167], s[38:39], 0, v[130:131]
	v_lshlrev_b64 v[130:131], 1, v[144:145]
	v_lshl_add_u64 v[168:169], v[166:167], 0, v[128:129]
	v_lshl_add_u64 v[162:163], v[162:163], 0, v[130:131]
	s_waitcnt vmcnt(0)
	v_add_f32_e32 v123, v123, v157
	v_add_f32_e32 v124, v124, v157
	v_add_f32_e32 v125, v125, v157
	v_add_f32_e32 v126, v126, v157
	v_add_f32_e32 v127, v127, v157
	s_waitcnt lgkmcnt(0)
	v_lshlrev_b32_e32 v173, 16, v161
	v_and_b32_e32 v161, 0xffff0000, v161
	v_add_f32_e32 v120, v120, v157
	v_add_f32_e32 v121, v121, v157
	v_add_f32_e32 v122, v122, v157
	v_lshlrev_b32_e32 v170, 16, v158
	v_and_b32_e32 v158, 0xffff0000, v158
	v_lshlrev_b32_e32 v171, 16, v159
	v_and_b32_e32 v159, 0xffff0000, v159
	v_lshlrev_b32_e32 v172, 16, v160
	v_and_b32_e32 v160, 0xffff0000, v160
	v_mul_f32_e32 v123, v123, v161
	v_mul_f32_e32 v124, v124, v170
	v_mul_f32_e32 v125, v125, v158
	v_mul_f32_e32 v126, v126, v171
	v_mul_f32_e32 v127, v127, v159
	v_mul_f32_e32 v158, v120, v172
	v_mul_f32_e32 v159, v121, v160
	v_mul_f32_e32 v160, v122, v173
	v_cvt_pk_bf16_f32 v120, v124, v125
	v_cvt_pk_bf16_f32 v121, v126, v127
	v_cvt_pk_bf16_f32 v122, v158, v159
	v_cvt_pk_bf16_f32 v123, v160, v123
	flat_store_dwordx4 v[168:169], v[120:123]
	flat_load_dwordx4 v[120:123], v[162:163] nt
	v_add_f32_e32 v116, v116, v157
	v_add_f32_e32 v117, v117, v157
	v_add_f32_e32 v118, v118, v157
	v_add_f32_e32 v119, v119, v157
	v_add_f32_e32 v112, v112, v157
	v_add_f32_e32 v113, v113, v157
	v_add_f32_e32 v114, v114, v157
	v_add_f32_e32 v115, v115, v157
	v_add_u32_e32 v125, 16, v155
	v_add_u32_e32 v124, s75, v125
	v_lshl_add_u64 v[160:161], v[166:167], 0, v[130:131]
	v_mad_i64_i32 v[126:127], s[50:51], v124, s62, v[146:147]
	v_lshl_add_u64 v[158:159], v[126:127], 0, v[128:129]
	s_waitcnt vmcnt(0) lgkmcnt(0)
	v_lshlrev_b32_e32 v157, 16, v120
	v_and_b32_e32 v120, 0xffff0000, v120
	v_lshlrev_b32_e32 v163, 16, v122
	v_mul_f32_e32 v116, v116, v157
	v_lshlrev_b32_e32 v166, 16, v123
	v_and_b32_e32 v123, 0xffff0000, v123
	v_mul_f32_e32 v117, v117, v120
	v_mul_f32_e32 v120, v112, v163
	v_cvt_pk_bf16_f32 v112, v116, v117
	v_add_u32_e32 v116, s52, v125
	v_lshlrev_b32_e32 v162, 16, v121
	v_and_b32_e32 v121, 0xffff0000, v121
	v_and_b32_e32 v122, 0xffff0000, v122
	v_mul_f32_e32 v115, v115, v123
	v_ashrrev_i32_e32 v117, 31, v116
	v_mul_f32_e32 v118, v118, v162
	v_mul_f32_e32 v119, v119, v121
	v_mul_f32_e32 v121, v113, v122
	v_mul_f32_e32 v122, v114, v166
	v_cvt_pk_bf16_f32 v113, v118, v119
	v_cvt_pk_bf16_f32 v114, v120, v121
	v_cvt_pk_bf16_f32 v115, v122, v115
	flat_store_dwordx4 v[160:161], v[112:115]
	v_lshl_add_u64 v[116:117], v[116:117], 2, s[4:5]
	flat_load_dwordx4 v[112:115], v[158:159] nt
	global_load_dword v122, v[116:117], off
	v_ashrrev_i32_e32 v125, 31, v124
	v_lshlrev_b64 v[116:117], 12, v[124:125]
	v_lshl_add_u64 v[116:117], s[38:39], 0, v[116:117]
	v_lshl_add_u64 v[118:119], v[126:127], 0, v[130:131]
	v_lshl_add_u64 v[120:121], v[116:117], 0, v[128:129]
	s_waitcnt vmcnt(0) lgkmcnt(0)
	v_lshlrev_b32_e32 v126, 16, v115
	v_and_b32_e32 v115, 0xffff0000, v115
	v_add_f32_e32 v107, v107, v122
	v_lshlrev_b32_e32 v123, 16, v112
	v_and_b32_e32 v112, 0xffff0000, v112
	v_lshlrev_b32_e32 v124, 16, v113
	v_and_b32_e32 v113, 0xffff0000, v113
	v_lshlrev_b32_e32 v125, 16, v114
	v_and_b32_e32 v114, 0xffff0000, v114
	v_add_f32_e32 v108, v108, v122
	v_add_f32_e32 v109, v109, v122
	v_add_f32_e32 v110, v110, v122
	v_add_f32_e32 v111, v111, v122
	v_add_f32_e32 v104, v104, v122
	v_add_f32_e32 v105, v105, v122
	v_add_f32_e32 v106, v106, v122
	v_mul_f32_e32 v107, v107, v115
	v_mul_f32_e32 v108, v108, v123
	v_mul_f32_e32 v109, v109, v112
	v_mul_f32_e32 v110, v110, v124
	v_mul_f32_e32 v111, v111, v113
	v_mul_f32_e32 v112, v104, v125
	v_mul_f32_e32 v113, v105, v114
	v_mul_f32_e32 v114, v106, v126
	v_cvt_pk_bf16_f32 v104, v108, v109
	v_cvt_pk_bf16_f32 v105, v110, v111
	v_cvt_pk_bf16_f32 v106, v112, v113
	v_cvt_pk_bf16_f32 v107, v114, v107
	flat_store_dwordx4 v[120:121], v[104:107]
	flat_load_dwordx4 v[104:107], v[118:119] nt
	v_lshl_add_u64 v[114:115], v[116:117], 0, v[130:131]
	v_add_f32_e32 v100, v100, v122
	v_add_u32_e32 v109, 32, v155
	v_add_f32_e32 v101, v101, v122
	v_add_f32_e32 v96, v96, v122
	v_add_u32_e32 v108, s75, v109
	v_add_f32_e32 v99, v99, v122
	v_mad_i64_i32 v[110:111], s[50:51], v108, s62, v[146:147]
	v_add_f32_e32 v102, v102, v122
	v_add_f32_e32 v103, v103, v122
	v_add_f32_e32 v97, v97, v122
	v_add_f32_e32 v98, v98, v122
	v_lshl_add_u64 v[112:113], v[110:111], 0, v[128:129]
	s_waitcnt vmcnt(0) lgkmcnt(0)
	v_lshlrev_b32_e32 v116, 16, v104
	v_and_b32_e32 v104, 0xffff0000, v104
	v_lshlrev_b32_e32 v118, 16, v106
	v_mul_f32_e32 v100, v100, v116
	v_lshlrev_b32_e32 v119, 16, v107
	v_and_b32_e32 v107, 0xffff0000, v107
	v_mul_f32_e32 v101, v101, v104
	v_mul_f32_e32 v104, v96, v118
	v_cvt_pk_bf16_f32 v96, v100, v101
	v_add_u32_e32 v100, s52, v109
	v_lshlrev_b32_e32 v117, 16, v105
	v_and_b32_e32 v105, 0xffff0000, v105
	v_and_b32_e32 v106, 0xffff0000, v106
	v_mul_f32_e32 v99, v99, v107
	v_ashrrev_i32_e32 v101, 31, v100
	v_mul_f32_e32 v102, v102, v117
	v_mul_f32_e32 v103, v103, v105
	v_mul_f32_e32 v105, v97, v106
	v_mul_f32_e32 v106, v98, v119
	v_cvt_pk_bf16_f32 v97, v102, v103
	v_cvt_pk_bf16_f32 v98, v104, v105
	v_cvt_pk_bf16_f32 v99, v106, v99
	flat_store_dwordx4 v[114:115], v[96:99]
	v_lshl_add_u64 v[100:101], v[100:101], 2, s[4:5]
	flat_load_dwordx4 v[96:99], v[112:113] nt
	global_load_dword v106, v[100:101], off
	v_ashrrev_i32_e32 v109, 31, v108
	v_lshlrev_b64 v[100:101], 12, v[108:109]
	v_lshl_add_u64 v[100:101], s[38:39], 0, v[100:101]
	v_lshl_add_u64 v[102:103], v[110:111], 0, v[130:131]
	v_lshl_add_u64 v[104:105], v[100:101], 0, v[128:129]
	s_waitcnt vmcnt(0) lgkmcnt(0)
	v_lshlrev_b32_e32 v110, 16, v99
	v_and_b32_e32 v99, 0xffff0000, v99
	v_add_f32_e32 v91, v91, v106
	v_lshlrev_b32_e32 v107, 16, v96
	v_and_b32_e32 v96, 0xffff0000, v96
	v_lshlrev_b32_e32 v108, 16, v97
	v_and_b32_e32 v97, 0xffff0000, v97
	v_lshlrev_b32_e32 v109, 16, v98
	v_and_b32_e32 v98, 0xffff0000, v98
	v_add_f32_e32 v92, v92, v106
	v_add_f32_e32 v93, v93, v106
	v_add_f32_e32 v94, v94, v106
	v_add_f32_e32 v95, v95, v106
	v_add_f32_e32 v88, v88, v106
	v_add_f32_e32 v89, v89, v106
	v_add_f32_e32 v90, v90, v106
	v_mul_f32_e32 v91, v91, v99
	v_mul_f32_e32 v92, v92, v107
	v_mul_f32_e32 v93, v93, v96
	v_mul_f32_e32 v94, v94, v108
	v_mul_f32_e32 v95, v95, v97
	v_mul_f32_e32 v96, v88, v109
	v_mul_f32_e32 v97, v89, v98
	v_mul_f32_e32 v98, v90, v110
	v_cvt_pk_bf16_f32 v88, v92, v93
	v_cvt_pk_bf16_f32 v89, v94, v95
	v_cvt_pk_bf16_f32 v90, v96, v97
	v_cvt_pk_bf16_f32 v91, v98, v91
	flat_store_dwordx4 v[104:105], v[88:91]
	flat_load_dwordx4 v[88:91], v[102:103] nt
	v_lshl_add_u64 v[98:99], v[100:101], 0, v[130:131]
	v_add_f32_e32 v84, v84, v106
	v_add_u32_e32 v93, 48, v155
	v_add_f32_e32 v85, v85, v106
	v_add_f32_e32 v80, v80, v106
	v_add_u32_e32 v92, s75, v93
	v_add_f32_e32 v83, v83, v106
	v_mad_i64_i32 v[94:95], s[50:51], v92, s62, v[146:147]
	v_add_f32_e32 v86, v86, v106
	v_add_f32_e32 v87, v87, v106
	v_add_f32_e32 v81, v81, v106
	v_add_f32_e32 v82, v82, v106
	v_lshl_add_u64 v[96:97], v[94:95], 0, v[128:129]
	s_mov_b64 s[50:51], -1
	s_waitcnt vmcnt(0) lgkmcnt(0)
	v_lshlrev_b32_e32 v100, 16, v88
	v_and_b32_e32 v88, 0xffff0000, v88
	v_lshlrev_b32_e32 v102, 16, v90
	v_mul_f32_e32 v84, v84, v100
	v_lshlrev_b32_e32 v103, 16, v91
	v_and_b32_e32 v91, 0xffff0000, v91
	v_mul_f32_e32 v85, v85, v88
	v_mul_f32_e32 v88, v80, v102
	v_cvt_pk_bf16_f32 v80, v84, v85
	v_add_u32_e32 v84, s52, v93
	v_lshlrev_b32_e32 v101, 16, v89
	v_and_b32_e32 v89, 0xffff0000, v89
	v_and_b32_e32 v90, 0xffff0000, v90
	v_mul_f32_e32 v83, v83, v91
	v_ashrrev_i32_e32 v85, 31, v84
	v_mul_f32_e32 v86, v86, v101
	v_mul_f32_e32 v87, v87, v89
	v_mul_f32_e32 v89, v81, v90
	v_mul_f32_e32 v90, v82, v103
	v_cvt_pk_bf16_f32 v81, v86, v87
	v_cvt_pk_bf16_f32 v82, v88, v89
	v_cvt_pk_bf16_f32 v83, v90, v83
	flat_store_dwordx4 v[98:99], v[80:83]
	v_lshl_add_u64 v[84:85], v[84:85], 2, s[4:5]
	flat_load_dwordx4 v[80:83], v[96:97] nt
	global_load_dword v88, v[84:85], off
	v_ashrrev_i32_e32 v93, 31, v92
	v_lshlrev_b64 v[146:147], 12, v[92:93]
	v_lshl_add_u64 v[84:85], s[38:39], 0, v[146:147]
	v_lshl_add_u64 v[84:85], v[84:85], 0, v[128:129]
	v_lshl_add_u64 v[86:87], v[94:95], 0, v[130:131]
	s_waitcnt vmcnt(0) lgkmcnt(0)
	v_lshlrev_b32_e32 v92, 16, v83
	v_and_b32_e32 v83, 0xffff0000, v83
	v_add_f32_e32 v75, v75, v88
	v_lshlrev_b32_e32 v89, 16, v80
	v_and_b32_e32 v80, 0xffff0000, v80
	v_lshlrev_b32_e32 v90, 16, v81
	v_and_b32_e32 v81, 0xffff0000, v81
	v_lshlrev_b32_e32 v91, 16, v82
	v_and_b32_e32 v82, 0xffff0000, v82
	v_add_f32_e32 v76, v76, v88
	v_add_f32_e32 v77, v77, v88
	v_add_f32_e32 v78, v78, v88
	v_add_f32_e32 v79, v79, v88
	v_add_f32_e32 v72, v72, v88
	v_add_f32_e32 v73, v73, v88
	v_add_f32_e32 v74, v74, v88
	v_mul_f32_e32 v75, v75, v83
	v_mul_f32_e32 v76, v76, v89
	v_mul_f32_e32 v77, v77, v80
	v_mul_f32_e32 v78, v78, v90
	v_mul_f32_e32 v79, v79, v81
	v_mul_f32_e32 v80, v72, v91
	v_mul_f32_e32 v81, v73, v82
	v_mul_f32_e32 v82, v74, v92
	v_cvt_pk_bf16_f32 v72, v76, v77
	v_cvt_pk_bf16_f32 v73, v78, v79
	v_cvt_pk_bf16_f32 v74, v80, v81
	v_cvt_pk_bf16_f32 v75, v82, v75
	flat_store_dwordx4 v[84:85], v[72:75]
	flat_load_dwordx4 v[72:75], v[86:87] nt
	v_add_f32_e32 v68, v68, v88
	v_add_f32_e32 v69, v69, v88
	v_add_f32_e32 v70, v70, v88
	v_add_f32_e32 v71, v71, v88
	v_add_f32_e32 v64, v64, v88
	v_add_f32_e32 v65, v65, v88
	v_add_f32_e32 v66, v66, v88
	v_add_f32_e32 v67, v67, v88
	s_waitcnt vmcnt(0) lgkmcnt(0)
	v_lshlrev_b32_e32 v76, 16, v72
	v_and_b32_e32 v72, 0xffff0000, v72
	v_lshlrev_b32_e32 v77, 16, v73
	v_and_b32_e32 v73, 0xffff0000, v73
	v_lshlrev_b32_e32 v78, 16, v74
	v_and_b32_e32 v74, 0xffff0000, v74
	v_lshlrev_b32_e32 v79, 16, v75
	v_and_b32_e32 v75, 0xffff0000, v75
	v_mul_f32_e32 v68, v68, v76
	v_mul_f32_e32 v69, v69, v72
	v_mul_f32_e32 v70, v70, v77
	v_mul_f32_e32 v71, v71, v73
	v_mul_f32_e32 v64, v64, v78
	v_mul_f32_e32 v65, v65, v74
	v_mul_f32_e32 v66, v66, v79
	v_mul_f32_e32 v67, v67, v75
	v_cvt_pk_bf16_f32 v128, v68, v69
	v_cvt_pk_bf16_f32 v129, v70, v71
	v_cvt_pk_bf16_f32 v130, v64, v65
	v_cvt_pk_bf16_f32 v131, v66, v67

.LBB0_377:
	v_add_u32_e32 v64, s52, v155
	v_ashrrev_i32_e32 v65, 31, v64
	v_add_u32_e32 v74, s76, v156
	v_add_u32_e32 v66, s75, v155
	s_waitcnt lgkmcnt(0)
	v_lshl_add_u64 v[64:65], v[64:65], 2, s[4:5]
	v_mov_b64_e32 v[68:69], s[14:15]
	v_ashrrev_i32_e32 v75, 31, v74
	global_load_dword v80, v[64:65], off
	v_mad_i64_i32 v[76:77], s[48:49], v66, s62, v[68:69]
	v_lshlrev_b64 v[64:65], 1, v[74:75]
	v_lshl_add_u64 v[70:71], v[76:77], 0, v[64:65]
	flat_load_dwordx4 v[70:73], v[70:71] nt
	v_ashrrev_i32_e32 v67, 31, v66
	v_add_u32_e32 v144, 0x80, v74
	v_lshlrev_b64 v[66:67], 12, v[66:67]
	v_ashrrev_i32_e32 v145, 31, v144
	v_lshl_add_u64 v[74:75], s[38:39], 0, v[66:67]
	v_lshlrev_b64 v[66:67], 1, v[144:145]
	v_lshl_add_u64 v[78:79], v[74:75], 0, v[64:65]
	v_lshl_add_u64 v[76:77], v[76:77], 0, v[66:67]
	s_waitcnt vmcnt(0)
	v_add_f32_e32 v59, v59, v80
	v_add_f32_e32 v60, v60, v80
	v_add_f32_e32 v61, v61, v80
	v_add_f32_e32 v62, v62, v80
	v_add_f32_e32 v63, v63, v80
	s_waitcnt lgkmcnt(0)
	v_lshlrev_b32_e32 v84, 16, v73
	v_and_b32_e32 v73, 0xffff0000, v73
	v_add_f32_e32 v56, v56, v80
	v_add_f32_e32 v57, v57, v80
	v_add_f32_e32 v58, v58, v80
	v_lshlrev_b32_e32 v81, 16, v70
	v_and_b32_e32 v70, 0xffff0000, v70
	v_lshlrev_b32_e32 v82, 16, v71
	v_and_b32_e32 v71, 0xffff0000, v71
	v_lshlrev_b32_e32 v83, 16, v72
	v_and_b32_e32 v72, 0xffff0000, v72
	v_mul_f32_e32 v59, v59, v73
	v_mul_f32_e32 v60, v60, v81
	v_mul_f32_e32 v61, v61, v70
	v_mul_f32_e32 v62, v62, v82
	v_mul_f32_e32 v63, v63, v71
	v_mul_f32_e32 v70, v56, v83
	v_mul_f32_e32 v71, v57, v72
	v_mul_f32_e32 v72, v58, v84
	v_cvt_pk_bf16_f32 v56, v60, v61
	v_cvt_pk_bf16_f32 v57, v62, v63
	v_cvt_pk_bf16_f32 v58, v70, v71
	v_cvt_pk_bf16_f32 v59, v72, v59
	flat_store_dwordx4 v[78:79], v[56:59]
	flat_load_dwordx4 v[56:59], v[76:77] nt
	v_lshl_add_u64 v[72:73], v[74:75], 0, v[66:67]
	v_add_f32_e32 v52, v52, v80
	v_add_u32_e32 v61, 16, v155
	v_add_f32_e32 v53, v53, v80
	v_add_f32_e32 v48, v48, v80
	v_add_u32_e32 v60, s75, v61
	v_add_f32_e32 v51, v51, v80
	v_mad_i64_i32 v[62:63], s[48:49], v60, s62, v[68:69]
	v_add_f32_e32 v54, v54, v80
	v_add_f32_e32 v55, v55, v80
	v_add_f32_e32 v49, v49, v80
	v_add_f32_e32 v50, v50, v80
	v_lshl_add_u64 v[70:71], v[62:63], 0, v[64:65]
	s_waitcnt vmcnt(0) lgkmcnt(0)
	v_lshlrev_b32_e32 v74, 16, v56
	v_and_b32_e32 v56, 0xffff0000, v56
	v_lshlrev_b32_e32 v76, 16, v58
	v_mul_f32_e32 v52, v52, v74
	v_lshlrev_b32_e32 v77, 16, v59
	v_and_b32_e32 v59, 0xffff0000, v59
	v_mul_f32_e32 v53, v53, v56
	v_mul_f32_e32 v56, v48, v76
	v_cvt_pk_bf16_f32 v48, v52, v53
	v_add_u32_e32 v52, s52, v61
	v_lshlrev_b32_e32 v75, 16, v57
	v_and_b32_e32 v57, 0xffff0000, v57
	v_and_b32_e32 v58, 0xffff0000, v58
	v_mul_f32_e32 v51, v51, v59
	v_ashrrev_i32_e32 v53, 31, v52
	v_mul_f32_e32 v54, v54, v75
	v_mul_f32_e32 v55, v55, v57
	v_mul_f32_e32 v57, v49, v58
	v_mul_f32_e32 v58, v50, v77
	v_cvt_pk_bf16_f32 v49, v54, v55
	v_cvt_pk_bf16_f32 v50, v56, v57
	v_cvt_pk_bf16_f32 v51, v58, v51
	flat_store_dwordx4 v[72:73], v[48:51]
	v_lshl_add_u64 v[52:53], v[52:53], 2, s[4:5]
	flat_load_dwordx4 v[48:51], v[70:71] nt
	global_load_dword v58, v[52:53], off
	v_ashrrev_i32_e32 v61, 31, v60
	v_lshlrev_b64 v[52:53], 12, v[60:61]
	v_lshl_add_u64 v[52:53], s[38:39], 0, v[52:53]
	v_lshl_add_u64 v[54:55], v[62:63], 0, v[66:67]
	v_lshl_add_u64 v[56:57], v[52:53], 0, v[64:65]
	s_waitcnt vmcnt(0) lgkmcnt(0)
	v_lshlrev_b32_e32 v62, 16, v51
	v_and_b32_e32 v51, 0xffff0000, v51
	v_add_f32_e32 v43, v43, v58
	v_lshlrev_b32_e32 v59, 16, v48
	v_and_b32_e32 v48, 0xffff0000, v48
	v_lshlrev_b32_e32 v60, 16, v49
	v_and_b32_e32 v49, 0xffff0000, v49
	v_lshlrev_b32_e32 v61, 16, v50
	v_and_b32_e32 v50, 0xffff0000, v50
	v_add_f32_e32 v44, v44, v58
	v_add_f32_e32 v45, v45, v58
	v_add_f32_e32 v46, v46, v58
	v_add_f32_e32 v47, v47, v58
	v_add_f32_e32 v40, v40, v58
	v_add_f32_e32 v41, v41, v58
	v_add_f32_e32 v42, v42, v58
	v_mul_f32_e32 v43, v43, v51
	v_mul_f32_e32 v44, v44, v59
	v_mul_f32_e32 v45, v45, v48
	v_mul_f32_e32 v46, v46, v60
	v_mul_f32_e32 v47, v47, v49
	v_mul_f32_e32 v48, v40, v61
	v_mul_f32_e32 v49, v41, v50
	v_mul_f32_e32 v50, v42, v62
	v_cvt_pk_bf16_f32 v40, v44, v45
	v_cvt_pk_bf16_f32 v41, v46, v47
	v_cvt_pk_bf16_f32 v42, v48, v49
	v_cvt_pk_bf16_f32 v43, v50, v43
	flat_store_dwordx4 v[56:57], v[40:43]
	flat_load_dwordx4 v[40:43], v[54:55] nt
	v_lshl_add_u64 v[50:51], v[52:53], 0, v[66:67]
	v_add_f32_e32 v36, v36, v58
	v_add_u32_e32 v45, 32, v155
	v_add_f32_e32 v37, v37, v58
	v_add_f32_e32 v32, v32, v58
	v_add_u32_e32 v44, s75, v45
	v_add_f32_e32 v35, v35, v58
	v_mad_i64_i32 v[46:47], s[48:49], v44, s62, v[68:69]
	v_add_f32_e32 v38, v38, v58
	v_add_f32_e32 v39, v39, v58
	v_add_f32_e32 v33, v33, v58
	v_add_f32_e32 v34, v34, v58
	v_lshl_add_u64 v[48:49], v[46:47], 0, v[64:65]
	s_waitcnt vmcnt(0) lgkmcnt(0)
	v_lshlrev_b32_e32 v52, 16, v40
	v_and_b32_e32 v40, 0xffff0000, v40
	v_lshlrev_b32_e32 v54, 16, v42
	v_mul_f32_e32 v36, v36, v52
	v_lshlrev_b32_e32 v55, 16, v43
	v_and_b32_e32 v43, 0xffff0000, v43
	v_mul_f32_e32 v37, v37, v40
	v_mul_f32_e32 v40, v32, v54
	v_cvt_pk_bf16_f32 v32, v36, v37
	v_add_u32_e32 v36, s52, v45
	v_lshlrev_b32_e32 v53, 16, v41
	v_and_b32_e32 v41, 0xffff0000, v41
	v_and_b32_e32 v42, 0xffff0000, v42
	v_mul_f32_e32 v35, v35, v43
	v_ashrrev_i32_e32 v37, 31, v36
	v_mul_f32_e32 v38, v38, v53
	v_mul_f32_e32 v39, v39, v41
	v_mul_f32_e32 v41, v33, v42
	v_mul_f32_e32 v42, v34, v55
	v_cvt_pk_bf16_f32 v33, v38, v39
	v_cvt_pk_bf16_f32 v34, v40, v41
	v_cvt_pk_bf16_f32 v35, v42, v35
	flat_store_dwordx4 v[50:51], v[32:35]
	v_lshl_add_u64 v[36:37], v[36:37], 2, s[4:5]
	flat_load_dwordx4 v[32:35], v[48:49] nt
	global_load_dword v42, v[36:37], off
	v_ashrrev_i32_e32 v45, 31, v44
	v_lshlrev_b64 v[36:37], 12, v[44:45]
	v_lshl_add_u64 v[36:37], s[38:39], 0, v[36:37]
	v_lshl_add_u64 v[38:39], v[46:47], 0, v[66:67]
	v_lshl_add_u64 v[40:41], v[36:37], 0, v[64:65]
	s_waitcnt vmcnt(0) lgkmcnt(0)
	v_lshlrev_b32_e32 v46, 16, v35
	v_and_b32_e32 v35, 0xffff0000, v35
	v_add_f32_e32 v27, v27, v42
	v_lshlrev_b32_e32 v43, 16, v32
	v_and_b32_e32 v32, 0xffff0000, v32
	v_lshlrev_b32_e32 v44, 16, v33
	v_and_b32_e32 v33, 0xffff0000, v33
	v_lshlrev_b32_e32 v45, 16, v34
	v_and_b32_e32 v34, 0xffff0000, v34
	v_add_f32_e32 v28, v28, v42
	v_add_f32_e32 v29, v29, v42
	v_add_f32_e32 v30, v30, v42
	v_add_f32_e32 v31, v31, v42
	v_add_f32_e32 v24, v24, v42
	v_add_f32_e32 v25, v25, v42
	v_add_f32_e32 v26, v26, v42
	v_mul_f32_e32 v27, v27, v35
	v_mul_f32_e32 v28, v28, v43
	v_mul_f32_e32 v29, v29, v32
	v_mul_f32_e32 v30, v30, v44
	v_mul_f32_e32 v31, v31, v33
	v_mul_f32_e32 v32, v24, v45
	v_mul_f32_e32 v33, v25, v34
	v_mul_f32_e32 v34, v26, v46
	v_cvt_pk_bf16_f32 v24, v28, v29
	v_cvt_pk_bf16_f32 v25, v30, v31
	v_cvt_pk_bf16_f32 v26, v32, v33
	v_cvt_pk_bf16_f32 v27, v34, v27
	flat_store_dwordx4 v[40:41], v[24:27]
	flat_load_dwordx4 v[24:27], v[38:39] nt
	v_lshl_add_u64 v[34:35], v[36:37], 0, v[66:67]
	v_add_f32_e32 v20, v20, v42
	v_add_u32_e32 v29, 48, v155
	v_add_f32_e32 v21, v21, v42
	v_add_f32_e32 v16, v16, v42
	v_add_u32_e32 v28, s75, v29
	v_add_f32_e32 v19, v19, v42
	v_mad_i64_i32 v[30:31], s[48:49], v28, s62, v[68:69]
	v_add_f32_e32 v22, v22, v42
	v_add_f32_e32 v23, v23, v42
	v_add_f32_e32 v17, v17, v42
	v_add_f32_e32 v18, v18, v42
	v_lshl_add_u64 v[32:33], v[30:31], 0, v[64:65]
	s_waitcnt vmcnt(0) lgkmcnt(0)
	v_lshlrev_b32_e32 v36, 16, v24
	v_and_b32_e32 v24, 0xffff0000, v24
	v_lshlrev_b32_e32 v38, 16, v26
	v_mul_f32_e32 v20, v20, v36
	v_lshlrev_b32_e32 v39, 16, v27
	v_and_b32_e32 v27, 0xffff0000, v27
	v_mul_f32_e32 v21, v21, v24
	v_mul_f32_e32 v24, v16, v38
	v_cvt_pk_bf16_f32 v16, v20, v21
	v_add_u32_e32 v20, s52, v29
	v_lshlrev_b32_e32 v37, 16, v25
	v_and_b32_e32 v25, 0xffff0000, v25
	v_and_b32_e32 v26, 0xffff0000, v26
	v_mul_f32_e32 v19, v19, v27
	v_ashrrev_i32_e32 v21, 31, v20
	v_mul_f32_e32 v22, v22, v37
	v_mul_f32_e32 v23, v23, v25
	v_mul_f32_e32 v25, v17, v26
	v_mul_f32_e32 v26, v18, v39
	v_cvt_pk_bf16_f32 v17, v22, v23
	v_cvt_pk_bf16_f32 v18, v24, v25
	v_cvt_pk_bf16_f32 v19, v26, v19
	flat_store_dwordx4 v[34:35], v[16:19]
	v_lshl_add_u64 v[20:21], v[20:21], 2, s[4:5]
	flat_load_dwordx4 v[16:19], v[32:33] nt
	global_load_dword v24, v[20:21], off
	v_ashrrev_i32_e32 v29, 31, v28
	v_lshlrev_b64 v[146:147], 12, v[28:29]
	v_lshl_add_u64 v[20:21], s[38:39], 0, v[146:147]
	v_lshl_add_u64 v[20:21], v[20:21], 0, v[64:65]
	v_lshl_add_u64 v[22:23], v[30:31], 0, v[66:67]
	s_waitcnt vmcnt(0) lgkmcnt(0)
	v_lshlrev_b32_e32 v28, 16, v19
	v_and_b32_e32 v19, 0xffff0000, v19
	v_add_f32_e32 v11, v11, v24
	v_lshlrev_b32_e32 v25, 16, v16
	v_and_b32_e32 v16, 0xffff0000, v16
	v_lshlrev_b32_e32 v26, 16, v17
	v_and_b32_e32 v17, 0xffff0000, v17
	v_lshlrev_b32_e32 v27, 16, v18
	v_and_b32_e32 v18, 0xffff0000, v18
	v_add_f32_e32 v12, v12, v24
	v_add_f32_e32 v13, v13, v24
	v_add_f32_e32 v14, v14, v24
	v_add_f32_e32 v15, v15, v24
	v_add_f32_e32 v8, v8, v24
	v_add_f32_e32 v9, v9, v24
	v_add_f32_e32 v10, v10, v24
	v_mul_f32_e32 v11, v11, v19
	v_mul_f32_e32 v12, v12, v25
	v_mul_f32_e32 v13, v13, v16
	v_mul_f32_e32 v14, v14, v26
	v_mul_f32_e32 v15, v15, v17
	v_mul_f32_e32 v16, v8, v27
	v_mul_f32_e32 v17, v9, v18
	v_mul_f32_e32 v18, v10, v28
	v_cvt_pk_bf16_f32 v8, v12, v13
	v_cvt_pk_bf16_f32 v9, v14, v15
	v_cvt_pk_bf16_f32 v10, v16, v17
	v_cvt_pk_bf16_f32 v11, v18, v11
	flat_store_dwordx4 v[20:21], v[8:11]
	flat_load_dwordx4 v[8:11], v[22:23] nt
	v_add_f32_e32 v4, v4, v24
	v_add_f32_e32 v5, v5, v24
	v_add_f32_e32 v6, v6, v24
	v_add_f32_e32 v7, v7, v24
	v_add_f32_e32 v0, v0, v24
	v_add_f32_e32 v1, v1, v24
	v_add_f32_e32 v2, v2, v24
	v_add_f32_e32 v3, v3, v24
	s_waitcnt vmcnt(0) lgkmcnt(0)
	v_lshlrev_b32_e32 v12, 16, v8
	v_and_b32_e32 v8, 0xffff0000, v8
	v_lshlrev_b32_e32 v13, 16, v9
	v_and_b32_e32 v9, 0xffff0000, v9
	v_lshlrev_b32_e32 v14, 16, v10
	v_and_b32_e32 v10, 0xffff0000, v10
	v_lshlrev_b32_e32 v15, 16, v11
	v_and_b32_e32 v11, 0xffff0000, v11
	v_mul_f32_e32 v4, v4, v12
	v_mul_f32_e32 v5, v5, v8
	v_mul_f32_e32 v6, v6, v13
	v_mul_f32_e32 v7, v7, v9
	v_mul_f32_e32 v0, v0, v14
	v_mul_f32_e32 v1, v1, v10
	v_mul_f32_e32 v2, v2, v15
	v_mul_f32_e32 v3, v3, v11
	v_cvt_pk_bf16_f32 v128, v4, v5
	v_cvt_pk_bf16_f32 v129, v6, v7
	v_cvt_pk_bf16_f32 v130, v0, v1
	v_cvt_pk_bf16_f32 v131, v2, v3
	s_cbranch_execnz .LBB0_372
	s_branch .LBB0_373

.LBB0_442:
	v_mov_b32_e32 v128, v155
	v_mov_b32_e32 v130, v156
	s_nop 0
	v_add_u32_e32 v131, s92, v128
	v_mov_b64_e32 v[128:129], s[8:9]
	v_mad_i64_i32 v[128:129], s[40:41], v131, s70, v[128:129]
	v_lshl_add_u64 v[128:129], s[52:53], 1, v[128:129]
	v_lshlrev_b32_e32 v130, 3, v130
	v_lshl_add_u64 v[128:129], v[128:129], 0, s[4:5]
	v_ashrrev_i32_e32 v131, 31, v130
	v_lshl_add_u64 v[152:153], v[130:131], 1, v[128:129]
	v_add_co_u32_e32 v128, vcc, 0x2000, v152
	s_nop 1
	v_addc_co_u32_e32 v129, vcc, 0, v153, vcc
	flat_load_dwordx4 v[160:163], v[128:129] offset:2048 nt
	v_lshl_add_u64 v[128:129], v[152:153], 0, s[42:43]
	flat_load_dwordx4 v[166:169], v[128:129] offset:512 nt
	v_add_co_u32_e32 v128, vcc, 0x4a000, v152
	s_waitcnt vmcnt(0) lgkmcnt(0)
	v_lshlrev_b32_e32 v188, 16, v160
	v_addc_co_u32_e32 v129, vcc, 0, v153, vcc
	flat_load_dwordx4 v[170:173], v[128:129] offset:2048 nt
	flat_load_dwordx4 v[136:139], v[128:129] offset:2560 nt
	v_add_co_u32_e32 v128, vcc, 0x92000, v152
	v_and_b32_e32 v189, 0xffff0000, v160
	s_nop 0
	v_addc_co_u32_e32 v129, vcc, 0, v153, vcc
	flat_load_dwordx4 v[132:135], v[128:129] offset:2048 nt
	s_nop 0
	flat_load_dwordx4 v[128:131], v[128:129] offset:2560 nt
	v_add_co_u32_e32 v186, vcc, s74, v152
	v_lshlrev_b32_e32 v160, 16, v161
	s_nop 0
	v_addc_co_u32_e32 v187, vcc, 0, v153, vcc
	v_add_co_u32_e32 v178, vcc, 0xda000, v152
	v_and_b32_e32 v161, 0xffff0000, v161
	s_nop 0
	v_addc_co_u32_e32 v179, vcc, 0, v153, vcc
	flat_load_dwordx4 v[174:177], v[178:179] offset:2048 nt
	s_nop 0
	flat_load_dwordx4 v[178:181], v[178:179] offset:2560 nt
	flat_load_dwordx4 v[182:185], v[186:187] offset:2048 nt
	v_lshlrev_b32_e32 v192, 16, v166
	v_and_b32_e32 v193, 0xffff0000, v166
	v_lshlrev_b32_e32 v166, 16, v167
	v_and_b32_e32 v167, 0xffff0000, v167
	v_pk_mul_f32 v[126:127], v[126:127], v[160:161]
	v_lshlrev_b32_e32 v190, 16, v162
	v_and_b32_e32 v191, 0xffff0000, v162
	v_lshlrev_b32_e32 v162, 16, v163
	v_and_b32_e32 v163, 0xffff0000, v163
	v_lshlrev_b32_e32 v194, 16, v168
	v_and_b32_e32 v195, 0xffff0000, v168
	v_lshlrev_b32_e32 v168, 16, v169
	v_and_b32_e32 v169, 0xffff0000, v169
	v_pk_mul_f32 v[118:119], v[118:119], v[166:167]
	v_pk_mul_f32 v[122:123], v[122:123], v[162:163]
	v_pk_mul_f32 v[114:115], v[114:115], v[168:169]
	v_pk_mul_f32 v[124:125], v[124:125], v[188:189]
	v_pk_mul_f32 v[120:121], v[120:121], v[190:191]
	v_pk_mul_f32 v[116:117], v[116:117], v[192:193]
	v_pk_mul_f32 v[112:113], v[112:113], v[194:195]
	s_waitcnt vmcnt(0) lgkmcnt(0)
	v_lshlrev_b32_e32 v160, 16, v170
	v_and_b32_e32 v161, 0xffff0000, v170
	v_lshlrev_b32_e32 v166, 16, v171
	v_and_b32_e32 v167, 0xffff0000, v171
	v_lshlrev_b32_e32 v170, 16, v136
	v_and_b32_e32 v171, 0xffff0000, v136
	v_lshlrev_b32_e32 v136, 16, v137
	v_and_b32_e32 v137, 0xffff0000, v137
	v_pk_mul_f32 v[108:109], v[108:109], v[160:161]
	v_lshlrev_b32_e32 v160, 16, v139
	v_and_b32_e32 v161, 0xffff0000, v139
	v_lshlrev_b32_e32 v162, 16, v172
	v_and_b32_e32 v163, 0xffff0000, v172
	v_lshlrev_b32_e32 v168, 16, v173
	v_and_b32_e32 v169, 0xffff0000, v173
	v_lshlrev_b32_e32 v172, 16, v138
	v_and_b32_e32 v173, 0xffff0000, v138
	v_pk_mul_f32 v[110:111], v[110:111], v[166:167]
	v_pk_mul_f32 v[102:103], v[102:103], v[136:137]
	flat_load_dwordx4 v[136:139], v[186:187] offset:2560 nt
	v_pk_mul_f32 v[98:99], v[98:99], v[160:161]
	v_lshlrev_b32_e32 v160, 16, v132
	v_and_b32_e32 v161, 0xffff0000, v132
	v_add_co_u32_e32 v166, vcc, s75, v152
	v_pk_mul_f32 v[92:93], v[92:93], v[160:161]
	v_lshlrev_b32_e32 v160, 16, v134
	v_and_b32_e32 v161, 0xffff0000, v134
	v_addc_co_u32_e32 v167, vcc, 0, v153, vcc
	v_pk_mul_f32 v[104:105], v[104:105], v[162:163]
	v_pk_mul_f32 v[88:89], v[88:89], v[160:161]
	flat_load_dwordx4 v[160:163], v[166:167] offset:2048 nt
	v_lshlrev_b32_e32 v132, 16, v133
	v_and_b32_e32 v133, 0xffff0000, v133
	v_pk_mul_f32 v[94:95], v[94:95], v[132:133]
	v_lshlrev_b32_e32 v132, 16, v135
	v_and_b32_e32 v133, 0xffff0000, v135
	v_pk_mul_f32 v[90:91], v[90:91], v[132:133]
	v_lshlrev_b32_e32 v132, 16, v128
	v_and_b32_e32 v133, 0xffff0000, v128
	v_pk_mul_f32 v[106:107], v[106:107], v[168:169]
	v_pk_mul_f32 v[84:85], v[84:85], v[132:133]
	v_lshlrev_b32_e32 v168, 16, v130
	v_and_b32_e32 v169, 0xffff0000, v130
	flat_load_dwordx4 v[132:135], v[166:167] offset:2560 nt
	v_lshlrev_b32_e32 v128, 16, v129
	v_and_b32_e32 v129, 0xffff0000, v129
	v_add_co_u32_e32 v166, vcc, s76, v152
	v_pk_mul_f32 v[80:81], v[80:81], v[168:169]
	v_pk_mul_f32 v[86:87], v[86:87], v[128:129]
	v_lshlrev_b32_e32 v128, 16, v131
	v_and_b32_e32 v129, 0xffff0000, v131
	v_addc_co_u32_e32 v167, vcc, 0, v153, vcc
	v_lshlrev_b32_e32 v168, 16, v174
	v_and_b32_e32 v169, 0xffff0000, v174
	v_pk_mul_f32 v[82:83], v[82:83], v[128:129]
	flat_load_dwordx4 v[128:131], v[166:167] offset:2048 nt
	v_pk_mul_f32 v[76:77], v[76:77], v[168:169]
	v_lshlrev_b32_e32 v168, 16, v176
	v_and_b32_e32 v169, 0xffff0000, v176
	v_pk_mul_f32 v[72:73], v[72:73], v[168:169]
	v_lshlrev_b32_e32 v168, 16, v175
	v_and_b32_e32 v169, 0xffff0000, v175
	v_pk_mul_f32 v[78:79], v[78:79], v[168:169]
	flat_load_dwordx4 v[166:169], v[166:167] offset:2560 nt
	v_pk_mul_f32 v[100:101], v[100:101], v[170:171]
	v_lshlrev_b32_e32 v170, 16, v177
	v_and_b32_e32 v171, 0xffff0000, v177
	v_pk_mul_f32 v[74:75], v[74:75], v[170:171]
	v_lshlrev_b32_e32 v170, 16, v178
	v_and_b32_e32 v171, 0xffff0000, v178
	v_add_co_u32_e32 v152, vcc, s79, v152
	v_pk_mul_f32 v[68:69], v[68:69], v[170:171]
	v_lshlrev_b32_e32 v170, 16, v180
	v_and_b32_e32 v171, 0xffff0000, v180
	v_addc_co_u32_e32 v153, vcc, 0, v153, vcc
	v_pk_mul_f32 v[96:97], v[96:97], v[172:173]
	v_pk_mul_f32 v[64:65], v[64:65], v[170:171]
	flat_load_dwordx4 v[170:173], v[152:153] offset:2048 nt
	v_lshlrev_b32_e32 v174, 16, v179
	v_and_b32_e32 v175, 0xffff0000, v179
	v_pk_mul_f32 v[70:71], v[70:71], v[174:175]
	v_lshlrev_b32_e32 v174, 16, v181
	v_and_b32_e32 v175, 0xffff0000, v181
	v_pk_mul_f32 v[66:67], v[66:67], v[174:175]
	flat_load_dwordx4 v[174:177], v[152:153] offset:2560 nt
	v_lshlrev_b32_e32 v152, 16, v182
	v_and_b32_e32 v153, 0xffff0000, v182
	v_pk_mul_f32 v[60:61], v[60:61], v[152:153]
	v_lshlrev_b32_e32 v152, 16, v184
	v_and_b32_e32 v153, 0xffff0000, v184
	v_pk_mul_f32 v[56:57], v[56:57], v[152:153]
	v_lshlrev_b32_e32 v152, 16, v183
	v_and_b32_e32 v153, 0xffff0000, v183
	v_pk_mul_f32 v[62:63], v[62:63], v[152:153]
	v_lshlrev_b32_e32 v152, 16, v185
	v_and_b32_e32 v153, 0xffff0000, v185
	v_pk_mul_f32 v[58:59], v[58:59], v[152:153]
	s_waitcnt vmcnt(0) lgkmcnt(0)
	v_lshlrev_b32_e32 v152, 16, v136
	v_and_b32_e32 v153, 0xffff0000, v136
	v_lshlrev_b32_e32 v136, 16, v137
	v_and_b32_e32 v137, 0xffff0000, v137
	v_pk_mul_f32 v[54:55], v[54:55], v[136:137]
	v_lshlrev_b32_e32 v136, 16, v139
	v_and_b32_e32 v137, 0xffff0000, v139
	v_pk_mul_f32 v[50:51], v[50:51], v[136:137]
	v_lshlrev_b32_e32 v136, 16, v160
	v_and_b32_e32 v137, 0xffff0000, v160
	v_pk_mul_f32 v[44:45], v[44:45], v[136:137]
	v_lshlrev_b32_e32 v136, 16, v162
	v_and_b32_e32 v137, 0xffff0000, v162
	v_pk_mul_f32 v[40:41], v[40:41], v[136:137]
	v_lshlrev_b32_e32 v136, 16, v161
	v_and_b32_e32 v137, 0xffff0000, v161
	v_pk_mul_f32 v[46:47], v[46:47], v[136:137]
	v_lshlrev_b32_e32 v136, 16, v163
	v_and_b32_e32 v137, 0xffff0000, v163
	v_pk_mul_f32 v[42:43], v[42:43], v[136:137]
	v_pk_mul_f32 v[52:53], v[52:53], v[152:153]
	v_lshlrev_b32_e32 v136, 16, v132
	v_and_b32_e32 v137, 0xffff0000, v132
	v_lshlrev_b32_e32 v132, 16, v133
	v_and_b32_e32 v133, 0xffff0000, v133
	v_pk_mul_f32 v[38:39], v[38:39], v[132:133]
	v_lshlrev_b32_e32 v132, 16, v135
	v_and_b32_e32 v133, 0xffff0000, v135
	v_pk_mul_f32 v[34:35], v[34:35], v[132:133]
	v_lshlrev_b32_e32 v152, 16, v138
	v_and_b32_e32 v153, 0xffff0000, v138
	v_pk_mul_f32 v[36:37], v[36:37], v[136:137]
	v_lshlrev_b32_e32 v136, 16, v134
	v_and_b32_e32 v137, 0xffff0000, v134
	v_pk_mul_f32 v[48:49], v[48:49], v[152:153]
	v_lshlrev_b32_e32 v132, 16, v128
	v_and_b32_e32 v133, 0xffff0000, v128
	v_lshlrev_b32_e32 v128, 16, v129
	v_and_b32_e32 v129, 0xffff0000, v129
	v_pk_mul_f32 v[30:31], v[30:31], v[128:129]
	v_lshlrev_b32_e32 v128, 16, v131
	v_and_b32_e32 v129, 0xffff0000, v131
	v_pk_mul_f32 v[26:27], v[26:27], v[128:129]
	v_lshlrev_b32_e32 v128, 16, v166
	v_and_b32_e32 v129, 0xffff0000, v166
	v_pk_mul_f32 v[20:21], v[20:21], v[128:129]
	v_lshlrev_b32_e32 v128, 16, v168
	v_and_b32_e32 v129, 0xffff0000, v168
	v_pk_mul_f32 v[16:17], v[16:17], v[128:129]
	v_lshlrev_b32_e32 v128, 16, v167
	v_and_b32_e32 v129, 0xffff0000, v167
	v_pk_mul_f32 v[22:23], v[22:23], v[128:129]
	v_lshlrev_b32_e32 v128, 16, v169
	v_and_b32_e32 v129, 0xffff0000, v169
	v_pk_mul_f32 v[18:19], v[18:19], v[128:129]
	v_pk_mul_f32 v[28:29], v[28:29], v[132:133]
	v_lshlrev_b32_e32 v132, 16, v130
	v_and_b32_e32 v133, 0xffff0000, v130
	v_pk_mul_f32 v[32:33], v[32:33], v[136:137]
	v_lshlrev_b32_e32 v128, 16, v170
	v_and_b32_e32 v129, 0xffff0000, v170
	v_pk_mul_f32 v[12:13], v[12:13], v[128:129]
	v_lshlrev_b32_e32 v128, 16, v172
	v_and_b32_e32 v129, 0xffff0000, v172
	v_pk_mul_f32 v[8:9], v[8:9], v[128:129]
	v_lshlrev_b32_e32 v128, 16, v171
	v_and_b32_e32 v129, 0xffff0000, v171
	v_pk_mul_f32 v[14:15], v[14:15], v[128:129]
	v_lshlrev_b32_e32 v128, 16, v173
	v_and_b32_e32 v129, 0xffff0000, v173
	v_pk_mul_f32 v[10:11], v[10:11], v[128:129]
	v_lshlrev_b32_e32 v128, 16, v174
	v_and_b32_e32 v129, 0xffff0000, v174
	v_pk_mul_f32 v[4:5], v[4:5], v[128:129]
	v_lshlrev_b32_e32 v128, 16, v176
	v_and_b32_e32 v129, 0xffff0000, v176
	v_pk_mul_f32 v[0:1], v[0:1], v[128:129]
	v_lshlrev_b32_e32 v128, 16, v175
	v_and_b32_e32 v129, 0xffff0000, v175
	v_pk_mul_f32 v[6:7], v[6:7], v[128:129]
	v_lshlrev_b32_e32 v128, 16, v177
	v_and_b32_e32 v129, 0xffff0000, v177
	v_pk_mul_f32 v[24:25], v[24:25], v[132:133]
	v_pk_mul_f32 v[2:3], v[2:3], v[128:129]

.LBB0_630:
	s_or_b64 exec, exec, s[4:5]
	s_waitcnt lgkmcnt(0)
	v_mov_b32_e32 v0, v164
	s_barrier
	s_add_u32 s8, s34, 0x20200000
	s_mov_b32 s4, 16
	s_addc_u32 s9, s35, 0
	s_ashr_i32 s5, s4, 31
	s_lshl_b64 s[4:5], s[4:5], 3
	s_add_u32 s4, s0, s4
	s_addc_u32 s5, s1, s5
	s_load_dwordx2 s[14:15], s[4:5], 0x0
	s_add_u32 s6, s34, 0x9800000
	s_mov_b32 s4, 1
	s_addc_u32 s7, s35, 0
	s_ashr_i32 s5, s4, 31
	s_lshl_b64 s[4:5], s[4:5], 3
	s_add_u32 s4, s0, s4
	s_addc_u32 s5, s1, s5
	s_load_dwordx2 s[10:11], s[4:5], 0x0
	v_readlane_b32 s12, v226, 3
	v_readlane_b32 s13, v226, 4
	v_and_b32_e32 v45, 63, v0
	s_andn2_b64 vcc, exec, s[12:13]
	v_cndmask_b32_e64 v0, 0, 1, s[12:13]
	v_cmp_ne_u32_e64 s[4:5], 1, v0
	v_lshlrev_b32_e32 v40, 4, v45
	v_lshlrev_b32_e32 v44, 5, v45
	s_mov_b32 s52, s24
	s_cbranch_vccnz .LBB0_632
	v_mov_b32_e32 v41, 0
	s_ashr_i32 s25, s24, 31
	v_lshl_add_u64 v[0:1], s[8:9], 0, v[40:41]
	s_lshl_b64 s[50:51], s[24:25], 12
	v_lshl_add_u64 v[2:3], v[0:1], 0, s[50:51]
	s_add_i32 s12, s24, s18
	flat_load_dwordx4 v[28:31], v[2:3] offset:1024 nt
	flat_load_dwordx4 v[32:35], v[2:3] offset:2048 nt
	flat_load_dwordx4 v[24:27], v[2:3] offset:3072 nt
	flat_load_dwordx4 v[36:39], v[2:3] nt
	s_ashr_i32 s13, s12, 31
	s_lshl_b64 s[46:47], s[12:13], 12
	v_lshl_add_u64 v[2:3], v[0:1], 0, s[46:47]
	flat_load_dwordx4 v[46:49], v[2:3] nt
	flat_load_dwordx4 v[50:53], v[2:3] offset:1024 nt
	flat_load_dwordx4 v[108:111], v[2:3] offset:2048 nt
	flat_load_dwordx4 v[12:15], v[2:3] offset:3072 nt
	v_readlane_b32 s28, v226, 1
	v_readlane_b32 s29, v226, 2
	s_add_i32 s40, s12, s18
	s_mov_b32 s12, s28
	s_ashr_i32 s29, s28, 31
	v_writelane_b32 v226, s12, 1
	s_ashr_i32 s41, s40, 31
	s_lshl_b64 s[44:45], s[40:41], 12
	v_writelane_b32 v226, s13, 2
	s_lshl_b64 s[12:13], s[28:29], 12
	v_lshl_add_u64 v[4:5], v[0:1], 0, s[12:13]
	v_lshl_add_u64 v[0:1], v[0:1], 0, s[44:45]
	flat_load_dwordx4 v[20:23], v[0:1] nt
	flat_load_dwordx4 v[16:19], v[0:1] offset:1024 nt
	flat_load_dwordx4 v[8:11], v[0:1] offset:2048 nt
	s_nop 0
	flat_load_dwordx4 v[0:3], v[0:1] offset:3072 nt
	s_waitcnt lgkmcnt(0)
	v_add_u32_e32 v204, 0x1000, v44
	global_load_dwordx4 v[166:169], v44, s[14:15]
	global_load_dwordx4 v[170:173], v44, s[14:15] offset:16
	global_load_dwordx4 v[174:177], v44, s[14:15] offset:2048
	global_load_dwordx4 v[178:181], v44, s[14:15] offset:2064
	global_load_dwordx4 v[182:185], v204, s[14:15]
	global_load_dwordx4 v[186:189], v204, s[14:15] offset:16
	global_load_dwordx4 v[190:193], v204, s[14:15] offset:2048
	global_load_dwordx4 v[200:203], v204, s[14:15] offset:2064
	s_mov_b32 s40, 0x358637bd
	s_mov_b32 s48, 0x3a000000
	s_mov_b32 s3, 0x800000
	v_mov_b32_e32 v105, v41
	s_waitcnt vmcnt(0)
	v_mov_b32_e32 v112, v170
	v_mov_b32_e32 v113, v171
	v_mov_b32_e32 v114, v172
	v_mov_b32_e32 v115, v173
	v_mov_b32_e32 v122, v166
	v_mov_b32_e32 v123, v167
	v_mov_b32_e32 v124, v168
	v_mov_b32_e32 v125, v169
	v_lshlrev_b32_e32 v87, 16, v30
	v_and_b32_e32 v93, 0xffff0000, v30
	v_lshlrev_b32_e32 v89, 16, v31
	v_and_b32_e32 v71, 0xffff0000, v36
	v_and_b32_e32 v70, 0xffff0000, v46
	v_lshlrev_b32_e32 v63, 16, v36
	v_and_b32_e32 v97, 0xffff0000, v31
	v_lshlrev_b32_e32 v62, 16, v46
	v_pk_mul_f32 v[30:31], v[70:71], v[70:71]
	v_lshlrev_b32_e32 v65, 16, v37
	v_and_b32_e32 v55, 0xffff0000, v33
	v_lshlrev_b32_e32 v59, 16, v32
	v_and_b32_e32 v67, 0xffff0000, v32
	v_lshlrev_b32_e32 v61, 16, v33
	v_lshlrev_b32_e32 v64, 16, v47
	v_pk_fma_f32 v[32:33], v[62:63], v[62:63], v[30:31]
	v_and_b32_e32 v77, 0xffff0000, v37
	v_and_b32_e32 v76, 0xffff0000, v47
	v_pk_fma_f32 v[32:33], v[64:65], v[64:65], v[32:33]
	v_lshlrev_b32_e32 v73, 16, v38
	v_lshlrev_b32_e32 v72, 16, v48
	v_pk_fma_f32 v[32:33], v[76:77], v[76:77], v[32:33]
	v_and_b32_e32 v85, 0xffff0000, v38
	v_and_b32_e32 v84, 0xffff0000, v48
	v_pk_fma_f32 v[32:33], v[72:73], v[72:73], v[32:33]
	v_lshlrev_b32_e32 v83, 16, v39
	v_lshlrev_b32_e32 v82, 16, v49
	v_pk_fma_f32 v[32:33], v[84:85], v[84:85], v[32:33]
	v_and_b32_e32 v95, 0xffff0000, v39
	v_and_b32_e32 v94, 0xffff0000, v49
	v_pk_fma_f32 v[32:33], v[82:83], v[82:83], v[32:33]
	v_lshlrev_b32_e32 v69, 16, v28
	v_lshlrev_b32_e32 v68, 16, v50
	v_pk_fma_f32 v[32:33], v[94:95], v[94:95], v[32:33]
	v_and_b32_e32 v57, 0xffff0000, v28
	v_and_b32_e32 v56, 0xffff0000, v50
	v_pk_fma_f32 v[32:33], v[68:69], v[68:69], v[32:33]
	v_lshlrev_b32_e32 v81, 16, v29
	v_lshlrev_b32_e32 v80, 16, v51
	v_pk_fma_f32 v[32:33], v[56:57], v[56:57], v[32:33]
	v_and_b32_e32 v91, 0xffff0000, v29
	v_and_b32_e32 v90, 0xffff0000, v51
	v_pk_fma_f32 v[32:33], v[80:81], v[80:81], v[32:33]
	v_lshlrev_b32_e32 v86, 16, v52
	v_pk_fma_f32 v[32:33], v[90:91], v[90:91], v[32:33]
	v_and_b32_e32 v92, 0xffff0000, v52
	v_pk_fma_f32 v[32:33], v[86:87], v[86:87], v[32:33]
	v_lshlrev_b32_e32 v88, 16, v53
	v_pk_fma_f32 v[32:33], v[92:93], v[92:93], v[32:33]
	v_and_b32_e32 v96, 0xffff0000, v53
	v_pk_fma_f32 v[32:33], v[88:89], v[88:89], v[32:33]
	v_lshlrev_b32_e32 v58, 16, v108
	v_pk_fma_f32 v[32:33], v[96:97], v[96:97], v[32:33]
	v_and_b32_e32 v66, 0xffff0000, v108
	v_pk_fma_f32 v[32:33], v[58:59], v[58:59], v[32:33]
	v_lshlrev_b32_e32 v60, 16, v109
	v_pk_fma_f32 v[32:33], v[66:67], v[66:67], v[32:33]
	v_and_b32_e32 v54, 0xffff0000, v109
	v_pk_fma_f32 v[32:33], v[60:61], v[60:61], v[32:33]
	v_lshlrev_b32_e32 v43, 16, v34
	v_lshlrev_b32_e32 v42, 16, v110
	v_pk_fma_f32 v[32:33], v[54:55], v[54:55], v[32:33]
	v_and_b32_e32 v79, 0xffff0000, v34
	v_and_b32_e32 v78, 0xffff0000, v110
	v_pk_fma_f32 v[32:33], v[42:43], v[42:43], v[32:33]
	v_lshlrev_b32_e32 v75, 16, v35
	v_lshlrev_b32_e32 v74, 16, v111
	v_pk_fma_f32 v[32:33], v[78:79], v[78:79], v[32:33]
	v_and_b32_e32 v99, 0xffff0000, v35
	v_and_b32_e32 v98, 0xffff0000, v111
	v_pk_fma_f32 v[32:33], v[74:75], v[74:75], v[32:33]
	v_lshlrev_b32_e32 v47, 16, v24
	v_pk_fma_f32 v[32:33], v[98:99], v[98:99], v[32:33]
	v_lshlrev_b32_e32 v46, 16, v12
	v_and_b32_e32 v100, 0xffff0000, v26
	v_lshlrev_b32_e32 v103, 16, v26
	v_and_b32_e32 v26, 0xffff0000, v14
	v_and_b32_e32 v49, 0xffff0000, v24
	v_and_b32_e32 v48, 0xffff0000, v12
	v_lshlrev_b32_e32 v50, 16, v13
	v_and_b32_e32 v24, 0xffff0000, v13
	v_pk_fma_f32 v[12:13], v[46:47], v[46:47], v[32:33]
	v_mov_b32_e32 v102, v100
	v_lshlrev_b32_e32 v53, 16, v14
	v_mov_b32_e32 v52, v26
	v_lshlrev_b32_e32 v51, 16, v25
	v_pk_fma_f32 v[12:13], v[48:49], v[48:49], v[12:13]
	v_pk_mul_f32 v[28:29], v[102:103], v[102:103]
	v_pk_mul_f32 v[30:31], v[52:53], v[52:53]
	v_and_b32_e32 v25, 0xffff0000, v25
	v_pk_fma_f32 v[12:13], v[50:51], v[50:51], v[12:13]
	v_mov_b32_e32 v32, v31
	v_pk_fma_f32 v[12:13], v[24:25], v[24:25], v[12:13]
	v_mov_b32_e32 v33, v29
	v_pk_add_f32 v[32:33], v[32:33], v[12:13]
	v_mbcnt_hi_u32_b32 v13, -1, v165
	v_and_b32_e32 v14, 64, v13
	v_and_b32_e32 v104, 0xffff0000, v27
	v_and_b32_e32 v12, 0xffff0000, v15
	v_add_u32_e32 v14, 64, v14
	v_xor_b32_e32 v29, 1, v13
	v_lshlrev_b32_e32 v107, 16, v27
	v_mov_b32_e32 v106, v104
	v_lshlrev_b32_e32 v111, 16, v15
	v_mov_b32_e32 v110, v12
	v_cmp_lt_i32_e32 vcc, v29, v14
	v_pk_mul_f32 v[6:7], v[106:107], v[106:107]
	v_pk_mul_f32 v[34:35], v[110:111], v[110:111]
	v_cndmask_b32_e32 v29, v13, v29, vcc
	v_mov_b32_e32 v31, v28
	v_lshlrev_b32_e32 v116, 2, v29
	v_pk_add_f32 v[28:29], v[30:31], v[32:33]
	v_mov_b32_e32 v30, v35
	v_mov_b32_e32 v31, v7
	v_pk_add_f32 v[28:29], v[30:31], v[28:29]
	v_mov_b32_e32 v35, v6
	v_pk_add_f32 v[6:7], v[34:35], v[28:29]
	ds_bpermute_b32 v29, v116, v7
	ds_bpermute_b32 v28, v116, v6
	v_xor_b32_e32 v30, 2, v13
	v_cmp_lt_i32_e32 vcc, v30, v14
	v_mov_b32_e32 v128, v65
	v_mov_b32_e32 v129, v77
	v_cndmask_b32_e32 v30, v13, v30, vcc
	v_lshlrev_b32_e32 v118, 2, v30
	s_waitcnt lgkmcnt(0)
	v_pk_add_f32 v[6:7], v[6:7], v[28:29]
	ds_bpermute_b32 v29, v118, v7
	ds_bpermute_b32 v28, v118, v6
	v_xor_b32_e32 v30, 4, v13
	v_cmp_lt_i32_e32 vcc, v30, v14
	v_mov_b32_e32 v134, v81
	v_mov_b32_e32 v135, v91
	v_cndmask_b32_e32 v30, v13, v30, vcc
	v_lshlrev_b32_e32 v119, 2, v30
	s_waitcnt lgkmcnt(0)
	v_pk_add_f32 v[6:7], v[6:7], v[28:29]
	ds_bpermute_b32 v29, v119, v7
	ds_bpermute_b32 v28, v119, v6
	v_xor_b32_e32 v30, 8, v13
	v_cmp_lt_i32_e32 vcc, v30, v14
	v_mov_b32_e32 v136, v87
	v_mov_b32_e32 v137, v93
	v_cndmask_b32_e32 v30, v13, v30, vcc
	v_lshlrev_b32_e32 v120, 2, v30
	s_waitcnt lgkmcnt(0)
	v_pk_add_f32 v[6:7], v[6:7], v[28:29]
	ds_bpermute_b32 v29, v120, v7
	ds_bpermute_b32 v28, v120, v6
	v_xor_b32_e32 v30, 16, v13
	v_cmp_lt_i32_e32 vcc, v30, v14
	v_mov_b32_e32 v138, v89
	v_mov_b32_e32 v139, v97
	v_cndmask_b32_e32 v30, v13, v30, vcc
	v_lshlrev_b32_e32 v121, 2, v30
	s_waitcnt lgkmcnt(0)
	v_pk_add_f32 v[6:7], v[6:7], v[28:29]
	ds_bpermute_b32 v29, v121, v7
	ds_bpermute_b32 v28, v121, v6
	v_xor_b32_e32 v30, 32, v13
	v_cmp_lt_i32_e32 vcc, v30, v14
	v_and_b32_e32 v101, s0, v27
	v_pk_mov_b32 v[100:101], v[102:103], v[100:101] op_sel:[1,0]
	v_cndmask_b32_e32 v13, v13, v30, vcc
	v_lshlrev_b32_e32 v117, 2, v13
	s_waitcnt lgkmcnt(0)
	v_pk_add_f32 v[108:109], v[6:7], v[28:29]
	ds_bpermute_b32 v127, v117, v109
	ds_bpermute_b32 v126, v117, v108
	flat_load_dwordx4 v[36:39], v[4:5] nt
	flat_load_dwordx4 v[32:35], v[4:5] offset:1024 nt
	flat_load_dwordx4 v[28:31], v[4:5] offset:2048 nt
	s_nop 0
	flat_load_dwordx4 v[4:7], v[4:5] offset:3072 nt
	v_pk_mov_b32 v[102:103], v[106:107], v[104:105] op_sel:[1,0]
	v_mov_b32_e32 v65, v76
	v_mov_b32_e32 v81, v90
	s_waitcnt lgkmcnt(0)
	v_pk_add_f32 v[126:127], v[108:109], v[126:127]
	v_mov_b64_e32 v[108:109], s[40:41]
	v_pk_fma_f32 v[130:131], v[126:127], s[48:49], v[108:109] op_sel_hi:[1,0,0]
	v_mov_b32_e32 v126, v63
	v_mul_f32_e32 v13, 0x4b800000, v131
	v_cmp_gt_f32_e32 vcc, s3, v131
	v_mov_b32_e32 v127, v71
	s_add_u32 s40, s6, s50
	v_cndmask_b32_e32 v13, v131, v13, vcc
	v_rsq_f32_e32 v13, v13
	s_addc_u32 s41, s7, s51
	v_lshl_add_u64 v[132:133], s[40:41], 0, v[40:41]
	s_add_u32 s40, s6, s46
	v_mul_f32_e32 v14, 0x45800000, v13
	v_cndmask_b32_e32 v14, v13, v14, vcc
	v_pk_mul_f32 v[126:127], v[126:127], v[14:15] op_sel_hi:[1,0]
	v_pk_mul_f32 v[128:129], v[128:129], v[14:15] op_sel_hi:[1,0]
	v_pk_mul_f32 v[122:123], v[122:123], v[126:127]
	v_pk_mul_f32 v[124:125], v[124:125], v[128:129]
	v_mov_b32_e32 v126, v73
	v_mov_b32_e32 v127, v85
	v_mov_b32_e32 v128, v83
	v_mov_b32_e32 v129, v95
	v_pk_mul_f32 v[126:127], v[126:127], v[14:15] op_sel_hi:[1,0]
	v_pk_mul_f32 v[128:129], v[128:129], v[14:15] op_sel_hi:[1,0]
	v_pk_mul_f32 v[134:135], v[134:135], v[14:15] op_sel_hi:[1,0]
	v_pk_mul_f32 v[128:129], v[114:115], v[128:129]
	v_pk_mul_f32 v[114:115], v[112:113], v[126:127]
	v_cvt_pk_bf16_f32 v112, v122, v123
	v_cvt_pk_bf16_f32 v113, v124, v125
	v_pk_mul_f32 v[136:137], v[136:137], v[14:15] op_sel_hi:[1,0]
	v_cvt_pk_bf16_f32 v114, v114, v115
	v_cvt_pk_bf16_f32 v115, v128, v129
	global_store_dwordx4 v[132:133], v[112:115], off
	s_nop 1
	v_mov_b32_e32 v112, v69
	v_mov_b32_e32 v113, v57
	v_pk_mul_f32 v[112:113], v[112:113], v[14:15] op_sel_hi:[1,0]
	v_pk_mul_f32 v[138:139], v[138:139], v[14:15] op_sel_hi:[1,0]
	v_or_b32_e32 v114, 0x1000, v44
	v_or_b32_e32 v115, 0x1800, v44
	v_pk_mul_f32 v[100:101], v[14:15], v[100:101] op_sel_hi:[0,1]
	v_pk_mul_f32 v[102:103], v[14:15], v[102:103] op_sel_hi:[0,1]
	v_mul_f32_e32 v13, 0x4b800000, v130
	v_cmp_gt_f32_e32 vcc, s3, v130
	v_mov_b32_e32 v63, v70
	s_addc_u32 s41, s7, s47
	v_cndmask_b32_e32 v13, v130, v13, vcc
	v_rsq_f32_e32 v13, v13
	v_mov_b32_e32 v73, v84
	v_mov_b32_e32 v83, v94
	v_mov_b32_e32 v69, v56
	v_mov_b32_e32 v87, v92
	v_mov_b32_e32 v89, v96
	v_lshlrev_b32_e32 v85, 16, v20
	v_and_b32_e32 v93, 0xffff0000, v21
	v_and_b32_e32 v95, 0xffff0000, v22
	v_lshlrev_b32_e32 v91, 16, v23
	v_and_b32_e32 v27, s0, v15
	v_and_b32_e32 v97, 0xffff0000, v23
	s_waitcnt vmcnt(1)
	v_mov_b32_e32 v122, v174
	v_mov_b32_e32 v123, v175
	v_mov_b32_e32 v124, v176
	v_mov_b32_e32 v125, v177
	v_mov_b32_e32 v126, v178
	v_mov_b32_e32 v127, v179
	v_mov_b32_e32 v128, v180
	v_mov_b32_e32 v129, v181
	v_and_b32_e32 v94, 0xffff0000, v38
	v_lshlrev_b32_e32 v90, 16, v39
	v_and_b32_e32 v96, 0xffff0000, v39
	v_lshlrev_b32_e32 v84, 16, v36
	v_and_b32_e32 v92, 0xffff0000, v37
	v_pk_mul_f32 v[124:125], v[124:125], v[134:135]
	v_pk_mul_f32 v[112:113], v[122:123], v[112:113]
	v_pk_mul_f32 v[128:129], v[128:129], v[138:139]
	v_pk_mul_f32 v[126:127], v[126:127], v[136:137]
	v_cvt_pk_bf16_f32 v122, v112, v113
	v_cvt_pk_bf16_f32 v123, v124, v125
	v_mov_b32_e32 v134, v61
	v_cvt_pk_bf16_f32 v124, v126, v127
	v_cvt_pk_bf16_f32 v125, v128, v129
	global_store_dwordx4 v[132:133], v[122:125], off offset:1024
	s_nop 1
	s_nop 0
	v_mov_b32_e32 v135, v55
	v_mov_b32_e32 v112, v59
	v_mov_b32_e32 v113, v67
	v_mov_b32_e32 v136, v43
	v_mov_b32_e32 v137, v79
	v_mov_b32_e32 v138, v75
	v_mov_b32_e32 v139, v99
	v_pk_mul_f32 v[134:135], v[134:135], v[14:15] op_sel_hi:[1,0]
	v_pk_mul_f32 v[112:113], v[112:113], v[14:15] op_sel_hi:[1,0]
	v_pk_mul_f32 v[136:137], v[136:137], v[14:15] op_sel_hi:[1,0]
	v_pk_mul_f32 v[138:139], v[138:139], v[14:15] op_sel_hi:[1,0]
	v_mov_b32_e32 v43, v78
	v_mov_b32_e32 v59, v66
	v_mov_b32_e32 v61, v54
	v_mov_b32_e32 v75, v98
	v_and_b32_e32 v98, 0xffff0000, v2
	v_and_b32_e32 v67, 0xffff0000, v10
	v_and_b32_e32 v78, 0xffff0000, v35
	v_and_b32_e32 v66, 0xffff0000, v30
	v_and_b32_e32 v79, 0xffff0000, v19
	v_and_b32_e32 v99, s0, v3
	v_mov_b32_e32 v122, v182
	v_mov_b32_e32 v123, v183
	v_mov_b32_e32 v124, v184
	v_mov_b32_e32 v125, v185
	v_mov_b32_e32 v126, v186
	v_mov_b32_e32 v127, v187
	v_mov_b32_e32 v128, v188
	v_mov_b32_e32 v129, v189
	v_pk_mul_f32 v[124:125], v[134:135], v[124:125]
	v_pk_mul_f32 v[112:113], v[112:113], v[122:123]
	v_pk_mul_f32 v[128:129], v[138:139], v[128:129]
	v_pk_mul_f32 v[126:127], v[136:137], v[126:127]
	v_cvt_pk_bf16_f32 v122, v112, v113
	v_cvt_pk_bf16_f32 v123, v124, v125
	v_mov_b32_e32 v112, v47
	v_cvt_pk_bf16_f32 v124, v126, v127
	v_cvt_pk_bf16_f32 v125, v128, v129
	global_store_dwordx4 v[132:133], v[122:125], off offset:2048
	s_nop 1
	s_nop 0
	v_mov_b32_e32 v113, v49
	v_mov_b32_e32 v134, v51
	v_mov_b32_e32 v135, v25
	v_pk_mul_f32 v[104:105], v[112:113], v[14:15] op_sel_hi:[1,0]
	v_pk_mul_f32 v[106:107], v[134:135], v[14:15] op_sel_hi:[1,0]
	v_mul_f32_e32 v14, 0x45800000, v13
	v_cndmask_b32_e32 v130, v13, v14, vcc
	v_pk_mul_f32 v[62:63], v[62:63], v[130:131] op_sel_hi:[1,0]
	v_pk_mul_f32 v[64:65], v[64:65], v[130:131] op_sel_hi:[1,0]
	v_pk_mul_f32 v[70:71], v[72:73], v[130:131] op_sel_hi:[1,0]
	v_pk_mul_f32 v[72:73], v[82:83], v[130:131] op_sel_hi:[1,0]
	v_pk_mul_f32 v[56:57], v[68:69], v[130:131] op_sel_hi:[1,0]
	v_pk_mul_f32 v[68:69], v[80:81], v[130:131] op_sel_hi:[1,0]
	v_pk_mul_f32 v[76:77], v[86:87], v[130:131] op_sel_hi:[1,0]
	v_pk_mul_f32 v[80:81], v[88:89], v[130:131] op_sel_hi:[1,0]
	v_lshlrev_b32_e32 v88, 16, v38
	v_pk_mul_f32 v[38:39], v[42:43], v[130:131] op_sel_hi:[1,0]
	v_lshlrev_b32_e32 v86, 16, v37
	v_and_b32_e32 v82, 0xffff0000, v33
	v_pk_mul_f32 v[42:43], v[74:75], v[130:131] op_sel_hi:[1,0]
	v_and_b32_e32 v75, 0xffff0000, v8
	v_lshlrev_b32_e32 v87, 16, v21
	v_lshlrev_b32_e32 v89, 16, v22
	v_and_b32_e32 v14, 0xffff0000, v6
	v_mov_b32_e32 v13, v41
	v_mov_b32_e32 v47, v48
	v_and_b32_e32 v83, 0xffff0000, v17
	v_pk_mov_b32 v[12:13], v[110:111], v[12:13] op_sel:[1,0]
	v_mov_b32_e32 v51, v24
	v_pk_mul_f32 v[12:13], v[130:131], v[12:13] op_sel_hi:[0,1]
	v_and_b32_e32 v74, 0xffff0000, v28
	v_mov_b32_e32 v24, v87
	v_mov_b32_e32 v25, v93
	v_and_b32_e32 v15, s0, v7
	v_mov_b32_e32 v122, v190
	v_mov_b32_e32 v123, v191
	v_mov_b32_e32 v124, v192
	v_mov_b32_e32 v125, v193
	v_mov_b32_e32 v126, v200
	v_mov_b32_e32 v127, v201
	v_mov_b32_e32 v128, v202
	v_mov_b32_e32 v129, v203
	v_pk_mul_f32 v[106:107], v[106:107], v[124:125]
	v_pk_mul_f32 v[112:113], v[102:103], v[128:129]
	v_pk_mul_f32 v[102:103], v[100:101], v[126:127]
	v_pk_mul_f32 v[104:105], v[104:105], v[122:123]
	s_nop 0
	v_cvt_pk_bf16_f32 v100, v104, v105
	v_cvt_pk_bf16_f32 v101, v106, v107
	v_cvt_pk_bf16_f32 v102, v102, v103
	v_cvt_pk_bf16_f32 v103, v112, v113
	global_store_dwordx4 v[132:133], v[100:103], off offset:3072
	s_nop 1
	s_nop 0
	v_lshl_add_u64 v[112:113], s[40:41], 0, v[40:41]
	s_add_u32 s40, s6, s44
	s_addc_u32 s41, s7, s45
	s_add_u32 s12, s6, s12
	s_addc_u32 s13, s7, s13
	v_mov_b32_e32 v100, v166
	v_mov_b32_e32 v101, v167
	v_mov_b32_e32 v102, v168
	v_mov_b32_e32 v103, v169
	v_mov_b32_e32 v104, v170
	v_mov_b32_e32 v105, v171
	v_mov_b32_e32 v106, v172
	v_mov_b32_e32 v107, v173
	v_pk_mul_f32 v[64:65], v[64:65], v[102:103]
	v_pk_mul_f32 v[62:63], v[62:63], v[100:101]
	v_pk_mul_f32 v[72:73], v[72:73], v[106:107]
	v_pk_mul_f32 v[70:71], v[70:71], v[104:105]
	v_cvt_pk_bf16_f32 v62, v62, v63
	v_cvt_pk_bf16_f32 v63, v64, v65
	v_and_b32_e32 v100, 0xffff0000, v36
	v_cvt_pk_bf16_f32 v64, v70, v71
	v_cvt_pk_bf16_f32 v65, v72, v73
	global_store_dwordx4 v[112:113], v[62:65], off
	s_nop 1
	s_nop 0
	v_pk_mul_f32 v[36:37], v[60:61], v[130:131] op_sel_hi:[1,0]
	v_and_b32_e32 v101, 0xffff0000, v20
	v_lshlrev_b32_e32 v107, 16, v2
	v_and_b32_e32 v61, 0xffff0000, v11
	v_mov_b32_e32 v106, v98
	v_and_b32_e32 v60, 0xffff0000, v31
	v_mov_b32_e32 v62, v174
	v_mov_b32_e32 v63, v175
	v_mov_b32_e32 v64, v176
	v_mov_b32_e32 v65, v177
	v_mov_b32_e32 v70, v178
	v_mov_b32_e32 v71, v179
	v_mov_b32_e32 v72, v180
	v_mov_b32_e32 v73, v181
	v_pk_mul_f32 v[64:65], v[68:69], v[64:65]
	v_pk_mul_f32 v[56:57], v[56:57], v[62:63]
	v_pk_mul_f32 v[68:69], v[80:81], v[72:73]
	v_pk_mul_f32 v[70:71], v[76:77], v[70:71]
	v_cvt_pk_bf16_f32 v62, v56, v57
	v_cvt_pk_bf16_f32 v63, v64, v65
	v_and_b32_e32 v80, 0xffff0000, v32
	v_cvt_pk_bf16_f32 v64, v70, v71
	v_cvt_pk_bf16_f32 v65, v68, v69
	global_store_dwordx4 v[112:113], v[62:65], off offset:1024
	s_nop 1
	v_lshlrev_b32_e32 v64, 16, v32
	v_lshlrev_b32_e32 v68, 16, v33
	v_pk_mul_f32 v[32:33], v[58:59], v[130:131] op_sel_hi:[1,0]
	v_and_b32_e32 v63, 0xffff0000, v9
	v_lshlrev_b32_e32 v57, 16, v10
	v_lshlrev_b32_e32 v65, 16, v16
	v_lshlrev_b32_e32 v59, 16, v11
	v_pk_mov_b32 v[10:11], v[52:53], v[26:27] op_sel:[1,0]
	v_and_b32_e32 v81, 0xffff0000, v16
	v_lshlrev_b32_e32 v69, 16, v17
	v_pk_mul_f32 v[16:17], v[106:107], v[106:107]
	v_pk_mul_f32 v[10:11], v[130:131], v[10:11] op_sel_hi:[0,1]
	v_mov_b32_e32 v23, v17
	v_and_b32_e32 v62, 0xffff0000, v29
	v_lshlrev_b32_e32 v56, 16, v30
	v_lshlrev_b32_e32 v70, 16, v34
	v_and_b32_e32 v76, 0xffff0000, v34
	v_lshlrev_b32_e32 v72, 16, v35
	v_lshlrev_b32_e32 v58, 16, v31
	v_and_b32_e32 v30, 0xffff0000, v4
	v_and_b32_e32 v34, 0xffff0000, v5
	v_lshlrev_b32_e32 v71, 16, v18
	v_and_b32_e32 v77, 0xffff0000, v18
	v_lshlrev_b32_e32 v73, 16, v19
	v_and_b32_e32 v31, 0xffff0000, v0
	v_and_b32_e32 v35, 0xffff0000, v1
	v_mov_b32_e32 v102, v182
	v_mov_b32_e32 v103, v183
	v_mov_b32_e32 v104, v184
	v_mov_b32_e32 v105, v185
	v_mov_b32_e32 v122, v186
	v_mov_b32_e32 v123, v187
	v_mov_b32_e32 v124, v188
	v_mov_b32_e32 v125, v189
	v_pk_mul_f32 v[54:55], v[36:37], v[104:105]
	v_pk_mul_f32 v[38:39], v[38:39], v[122:123]
	v_pk_mul_f32 v[32:33], v[32:33], v[102:103]
	v_pk_mul_f32 v[42:43], v[42:43], v[124:125]
	v_cvt_pk_bf16_f32 v36, v32, v33
	v_cvt_pk_bf16_f32 v37, v54, v55
	v_cvt_pk_bf16_f32 v38, v38, v39
	v_lshlrev_b32_e32 v55, 16, v9
	v_cvt_pk_bf16_f32 v39, v42, v43
	global_store_dwordx4 v[112:113], v[36:39], off offset:2048
	s_nop 1
	v_lshlrev_b32_e32 v43, 16, v8
	v_pk_mul_f32 v[8:9], v[100:101], v[100:101]
	v_lshlrev_b32_e32 v33, 16, v6
	v_pk_fma_f32 v[8:9], v[84:85], v[84:85], v[8:9]
	v_mov_b32_e32 v32, v14
	v_pk_fma_f32 v[8:9], v[86:87], v[86:87], v[8:9]
	v_and_b32_e32 v36, 0xffff0000, v7
	v_pk_fma_f32 v[8:9], v[92:93], v[92:93], v[8:9]
	v_and_b32_e32 v102, 0xffff0000, v3
	v_pk_fma_f32 v[8:9], v[88:89], v[88:89], v[8:9]
	v_pk_mul_f32 v[20:21], v[32:33], v[32:33]
	v_pk_fma_f32 v[8:9], v[94:95], v[94:95], v[8:9]
	v_lshlrev_b32_e32 v39, 16, v7
	v_pk_fma_f32 v[8:9], v[90:91], v[90:91], v[8:9]
	v_mov_b32_e32 v38, v36
	v_pk_fma_f32 v[8:9], v[96:97], v[96:97], v[8:9]
	v_lshlrev_b32_e32 v105, 16, v3
	v_pk_fma_f32 v[52:53], v[64:65], v[64:65], v[8:9]
	v_pk_mul_f32 v[8:9], v[46:47], v[130:131] op_sel_hi:[1,0]
	v_mov_b32_e32 v104, v102
	v_mov_b32_e32 v22, v21
	v_mov_b32_e32 v21, v16
	v_pk_mul_f32 v[16:17], v[50:51], v[130:131] op_sel_hi:[1,0]
	v_lshlrev_b32_e32 v42, 16, v28
	v_lshlrev_b32_e32 v54, 16, v29
	v_lshlrev_b32_e32 v28, 16, v4
	v_lshlrev_b32_e32 v4, 16, v5
	v_lshlrev_b32_e32 v29, 16, v0
	v_lshlrev_b32_e32 v5, 16, v1
	v_pk_mul_f32 v[0:1], v[38:39], v[38:39]
	v_pk_mul_f32 v[18:19], v[104:105], v[104:105]
	v_mov_b32_e32 v26, v1
	v_mov_b32_e32 v27, v19
	v_mov_b32_e32 v1, v18
	v_mov_b32_e32 v103, v41
	v_mov_b32_e32 v87, v92
	v_mov_b32_e32 v37, v41
	v_mov_b32_e32 v122, v200
	v_mov_b32_e32 v123, v201
	v_mov_b32_e32 v124, v202
	v_mov_b32_e32 v125, v203
	v_mov_b32_e32 v126, v190
	v_mov_b32_e32 v127, v191
	v_mov_b32_e32 v128, v192
	v_mov_b32_e32 v129, v193
	v_pk_mul_f32 v[10:11], v[10:11], v[122:123]
	v_pk_mul_f32 v[8:9], v[8:9], v[126:127]
	v_pk_mul_f32 v[16:17], v[16:17], v[128:129]
	v_pk_mul_f32 v[12:13], v[12:13], v[124:125]
	v_cvt_pk_bf16_f32 v8, v8, v9
	v_cvt_pk_bf16_f32 v9, v16, v17
	v_cvt_pk_bf16_f32 v10, v10, v11
	s_nop 0
	v_cvt_pk_bf16_f32 v11, v12, v13
	global_store_dwordx4 v[112:113], v[8:11], off offset:3072
	s_nop 1
	s_nop 0
	v_pk_fma_f32 v[12:13], v[80:81], v[80:81], v[52:53]
	s_nop 0
	v_pk_fma_f32 v[12:13], v[68:69], v[68:69], v[12:13]
	s_nop 0
	v_pk_fma_f32 v[12:13], v[82:83], v[82:83], v[12:13]
	s_nop 0
	v_pk_fma_f32 v[12:13], v[70:71], v[70:71], v[12:13]
	s_nop 0
	v_pk_fma_f32 v[12:13], v[76:77], v[76:77], v[12:13]
	s_nop 0
	v_pk_fma_f32 v[12:13], v[72:73], v[72:73], v[12:13]
	s_nop 0
	v_pk_fma_f32 v[12:13], v[78:79], v[78:79], v[12:13]
	s_nop 0
	v_pk_fma_f32 v[12:13], v[42:43], v[42:43], v[12:13]
	s_nop 0
	v_pk_fma_f32 v[12:13], v[74:75], v[74:75], v[12:13]
	s_nop 0
	v_pk_fma_f32 v[12:13], v[54:55], v[54:55], v[12:13]
	s_nop 0
	v_pk_fma_f32 v[12:13], v[62:63], v[62:63], v[12:13]
	s_nop 0
	v_pk_fma_f32 v[12:13], v[56:57], v[56:57], v[12:13]
	s_nop 0
	v_pk_fma_f32 v[12:13], v[66:67], v[66:67], v[12:13]
	s_nop 0
	v_pk_fma_f32 v[12:13], v[58:59], v[58:59], v[12:13]
	s_nop 0
	v_pk_fma_f32 v[12:13], v[60:61], v[60:61], v[12:13]
	s_nop 0
	v_pk_fma_f32 v[12:13], v[28:29], v[28:29], v[12:13]
	s_nop 0
	v_pk_fma_f32 v[12:13], v[30:31], v[30:31], v[12:13]
	s_nop 0
	v_pk_fma_f32 v[12:13], v[4:5], v[4:5], v[12:13]
	s_nop 0
	v_pk_fma_f32 v[12:13], v[34:35], v[34:35], v[12:13]
	s_nop 0
	v_pk_add_f32 v[12:13], v[22:23], v[12:13]
	v_mov_b32_e32 v22, v85
	v_pk_add_f32 v[12:13], v[20:21], v[12:13]
	v_mov_b32_e32 v23, v101
	v_pk_add_f32 v[12:13], v[26:27], v[12:13]
	v_mov_b32_e32 v26, v89
	v_pk_add_f32 v[0:1], v[0:1], v[12:13]
	ds_bpermute_b32 v13, v116, v1
	ds_bpermute_b32 v12, v116, v0
	v_mov_b32_e32 v27, v95
	v_lshl_add_u64 v[20:21], s[40:41], 0, v[40:41]
	v_mov_b32_e32 v85, v100
	v_mov_b32_e32 v89, v94
	s_waitcnt lgkmcnt(0)
	v_pk_add_f32 v[0:1], v[0:1], v[12:13]
	ds_bpermute_b32 v13, v118, v1
	ds_bpermute_b32 v12, v118, v0
	s_waitcnt lgkmcnt(0)
	v_pk_add_f32 v[0:1], v[0:1], v[12:13]
	ds_bpermute_b32 v13, v119, v1
	ds_bpermute_b32 v12, v119, v0
	s_waitcnt lgkmcnt(0)
	v_pk_add_f32 v[0:1], v[0:1], v[12:13]
	ds_bpermute_b32 v13, v120, v1
	ds_bpermute_b32 v12, v120, v0
	s_waitcnt lgkmcnt(0)
	v_pk_add_f32 v[0:1], v[0:1], v[12:13]
	ds_bpermute_b32 v13, v121, v1
	ds_bpermute_b32 v12, v121, v0
	s_waitcnt lgkmcnt(0)
	v_pk_add_f32 v[0:1], v[0:1], v[12:13]
	ds_bpermute_b32 v13, v117, v1
	ds_bpermute_b32 v12, v117, v0
	s_waitcnt lgkmcnt(0)
	v_pk_add_f32 v[0:1], v[0:1], v[12:13]
	s_nop 0
	v_pk_fma_f32 v[12:13], v[0:1], s[48:49], v[108:109] op_sel_hi:[1,0,0]
	v_mov_b32_e32 v1, v97
	v_mul_f32_e32 v0, 0x4b800000, v13
	v_cmp_gt_f32_e32 vcc, s3, v13
	s_nop 1
	v_cndmask_b32_e32 v0, v13, v0, vcc
	v_rsq_f32_e32 v2, v0
	v_mov_b32_e32 v0, v91
	v_mov_b32_e32 v91, v96
	v_mul_f32_e32 v6, 0x45800000, v2
	v_cndmask_b32_e32 v2, v2, v6, vcc
	v_pk_mul_f32 v[26:27], v[26:27], v[2:3] op_sel_hi:[1,0]
	v_pk_mul_f32 v[0:1], v[0:1], v[2:3] op_sel_hi:[1,0]
	v_pk_mul_f32 v[22:23], v[22:23], v[2:3] op_sel_hi:[1,0]
	v_pk_mul_f32 v[24:25], v[24:25], v[2:3] op_sel_hi:[1,0]
	v_mov_b32_e32 v8, v170
	v_mov_b32_e32 v9, v171
	v_mov_b32_e32 v10, v172
	v_mov_b32_e32 v11, v173
	v_mov_b32_e32 v16, v166
	v_mov_b32_e32 v17, v167
	v_mov_b32_e32 v18, v168
	v_mov_b32_e32 v19, v169
	v_pk_mul_f32 v[0:1], v[0:1], v[10:11]
	v_pk_mul_f32 v[10:11], v[26:27], v[8:9]
	v_pk_mul_f32 v[18:19], v[24:25], v[18:19]
	v_pk_mul_f32 v[16:17], v[22:23], v[16:17]
	v_mov_b32_e32 v22, v69
	v_cvt_pk_bf16_f32 v8, v16, v17
	v_cvt_pk_bf16_f32 v9, v18, v19
	v_cvt_pk_bf16_f32 v10, v10, v11
	v_cvt_pk_bf16_f32 v11, v0, v1
	global_store_dwordx4 v[20:21], v[8:11], off
	s_nop 1
	s_nop 0
	v_mov_b32_e32 v23, v83
	v_mov_b32_e32 v0, v65
	v_mov_b32_e32 v1, v81
	v_mov_b32_e32 v24, v71
	v_mov_b32_e32 v25, v77
	v_mov_b32_e32 v26, v73
	v_mov_b32_e32 v27, v79
	v_pk_mul_f32 v[22:23], v[22:23], v[2:3] op_sel_hi:[1,0]
	v_pk_mul_f32 v[0:1], v[0:1], v[2:3] op_sel_hi:[1,0]
	v_pk_mul_f32 v[24:25], v[24:25], v[2:3] op_sel_hi:[1,0]
	v_pk_mul_f32 v[26:27], v[26:27], v[2:3] op_sel_hi:[1,0]
	v_cmp_gt_f32_e32 vcc, s3, v12
	v_mov_b32_e32 v65, v80
	v_mov_b32_e32 v69, v82
	v_mov_b32_e32 v71, v76
	v_mov_b32_e32 v73, v78
	s_lshl_b32 s3, s26, 5
	s_add_i32 s52, s24, s3
	v_mov_b32_e32 v8, v174
	v_mov_b32_e32 v9, v175
	v_mov_b32_e32 v10, v176
	v_mov_b32_e32 v11, v177
	v_mov_b32_e32 v16, v178
	v_mov_b32_e32 v17, v179
	v_mov_b32_e32 v18, v180
	v_mov_b32_e32 v19, v181
	v_pk_mul_f32 v[10:11], v[22:23], v[10:11]
	v_pk_mul_f32 v[0:1], v[0:1], v[8:9]
	v_pk_mul_f32 v[18:19], v[26:27], v[18:19]
	v_pk_mul_f32 v[16:17], v[24:25], v[16:17]
	v_cvt_pk_bf16_f32 v8, v0, v1
	v_cvt_pk_bf16_f32 v9, v10, v11
	v_mov_b32_e32 v22, v55
	v_cvt_pk_bf16_f32 v10, v16, v17
	v_cvt_pk_bf16_f32 v11, v18, v19
	global_store_dwordx4 v[20:21], v[8:11], off offset:1024
	s_nop 1
	s_nop 0
	v_mov_b32_e32 v23, v63
	v_mov_b32_e32 v0, v43
	v_mov_b32_e32 v1, v75
	v_mov_b32_e32 v24, v57
	v_mov_b32_e32 v25, v67
	v_mov_b32_e32 v26, v59
	v_mov_b32_e32 v27, v61
	v_pk_mul_f32 v[22:23], v[22:23], v[2:3] op_sel_hi:[1,0]
	v_pk_mul_f32 v[0:1], v[0:1], v[2:3] op_sel_hi:[1,0]
	v_pk_mul_f32 v[24:25], v[24:25], v[2:3] op_sel_hi:[1,0]
	v_pk_mul_f32 v[26:27], v[26:27], v[2:3] op_sel_hi:[1,0]
	v_mov_b32_e32 v43, v74
	v_mov_b32_e32 v55, v62
	v_mov_b32_e32 v57, v66
	v_mov_b32_e32 v59, v60
	v_mov_b32_e32 v8, v182
	v_mov_b32_e32 v9, v183
	v_mov_b32_e32 v10, v184
	v_mov_b32_e32 v11, v185
	v_mov_b32_e32 v16, v186
	v_mov_b32_e32 v17, v187
	v_mov_b32_e32 v18, v188
	v_mov_b32_e32 v19, v189
	v_pk_mul_f32 v[10:11], v[22:23], v[10:11]
	v_pk_mul_f32 v[0:1], v[0:1], v[8:9]
	v_pk_mul_f32 v[18:19], v[26:27], v[18:19]
	v_pk_mul_f32 v[16:17], v[24:25], v[16:17]
	v_cvt_pk_bf16_f32 v8, v0, v1
	v_cvt_pk_bf16_f32 v9, v10, v11
	v_mov_b32_e32 v0, v29
	v_cvt_pk_bf16_f32 v10, v16, v17
	v_cvt_pk_bf16_f32 v11, v18, v19
	global_store_dwordx4 v[20:21], v[8:11], off offset:2048
	s_nop 1
	s_nop 0
	v_mov_b32_e32 v1, v31
	v_mov_b32_e32 v22, v5
	v_mov_b32_e32 v23, v35
	v_pk_mov_b32 v[24:25], v[106:107], v[98:99] op_sel:[1,0]
	v_pk_mov_b32 v[26:27], v[104:105], v[102:103] op_sel:[1,0]
	v_pk_mul_f32 v[0:1], v[0:1], v[2:3] op_sel_hi:[1,0]
	v_pk_mul_f32 v[22:23], v[22:23], v[2:3] op_sel_hi:[1,0]
	v_pk_mul_f32 v[24:25], v[2:3], v[24:25] op_sel_hi:[0,1]
	v_pk_mul_f32 v[2:3], v[2:3], v[26:27] op_sel_hi:[0,1]
	v_mul_f32_e32 v5, 0x4b800000, v12
	v_cndmask_b32_e32 v5, v12, v5, vcc
	v_rsq_f32_e32 v5, v5
	v_mov_b32_e32 v29, v30
	v_mul_f32_e32 v6, 0x45800000, v5
	v_cndmask_b32_e32 v6, v5, v6, vcc
	v_pk_mul_f32 v[12:13], v[84:85], v[6:7] op_sel_hi:[1,0]
	v_mov_b32_e32 v5, v34
	v_pk_mul_f32 v[4:5], v[4:5], v[6:7] op_sel_hi:[1,0]
	v_mov_b32_e32 v8, v190
	v_mov_b32_e32 v9, v191
	v_mov_b32_e32 v10, v192
	v_mov_b32_e32 v11, v193
	v_mov_b32_e32 v16, v200
	v_mov_b32_e32 v17, v201
	v_mov_b32_e32 v18, v202
	v_mov_b32_e32 v19, v203
	v_pk_mul_f32 v[0:1], v[0:1], v[8:9]
	v_pk_mul_f32 v[8:9], v[2:3], v[18:19]
	v_pk_mul_f32 v[2:3], v[24:25], v[16:17]
	v_pk_mul_f32 v[10:11], v[22:23], v[10:11]
	v_cvt_pk_bf16_f32 v0, v0, v1
	v_pk_mul_f32 v[18:19], v[86:87], v[6:7] op_sel_hi:[1,0]
	v_cvt_pk_bf16_f32 v1, v10, v11
	v_cvt_pk_bf16_f32 v2, v2, v3
	v_cvt_pk_bf16_f32 v3, v8, v9
	global_store_dwordx4 v[20:21], v[0:3], off offset:3072
	s_nop 1
	s_nop 0
	v_lshl_add_u64 v[16:17], s[12:13], 0, v[40:41]
	v_pk_mul_f32 v[20:21], v[88:89], v[6:7] op_sel_hi:[1,0]
	v_pk_mul_f32 v[22:23], v[90:91], v[6:7] op_sel_hi:[1,0]
	v_mov_b32_e32 v0, v166
	v_mov_b32_e32 v1, v167
	v_mov_b32_e32 v2, v168
	v_mov_b32_e32 v3, v169
	v_mov_b32_e32 v8, v170
	v_mov_b32_e32 v9, v171
	v_mov_b32_e32 v10, v172
	v_mov_b32_e32 v11, v173
	v_pk_mul_f32 v[2:3], v[18:19], v[2:3]
	v_pk_mul_f32 v[0:1], v[12:13], v[0:1]
	v_pk_mul_f32 v[10:11], v[22:23], v[10:11]
	v_pk_mul_f32 v[8:9], v[20:21], v[8:9]
	v_cvt_pk_bf16_f32 v0, v0, v1
	v_cvt_pk_bf16_f32 v1, v2, v3
	v_pk_mul_f32 v[12:13], v[64:65], v[6:7] op_sel_hi:[1,0]
	v_cvt_pk_bf16_f32 v2, v8, v9
	v_cvt_pk_bf16_f32 v3, v10, v11
	global_store_dwordx4 v[16:17], v[0:3], off
	s_nop 1
	s_nop 0
	v_pk_mul_f32 v[18:19], v[68:69], v[6:7] op_sel_hi:[1,0]
	v_pk_mul_f32 v[20:21], v[70:71], v[6:7] op_sel_hi:[1,0]
	v_pk_mul_f32 v[22:23], v[72:73], v[6:7] op_sel_hi:[1,0]
	v_mov_b32_e32 v0, v174
	v_mov_b32_e32 v1, v175
	v_mov_b32_e32 v2, v176
	v_mov_b32_e32 v3, v177
	v_mov_b32_e32 v8, v178
	v_mov_b32_e32 v9, v179
	v_mov_b32_e32 v10, v180
	v_mov_b32_e32 v11, v181
	v_pk_mul_f32 v[2:3], v[18:19], v[2:3]
	v_pk_mul_f32 v[0:1], v[12:13], v[0:1]
	v_pk_mul_f32 v[10:11], v[22:23], v[10:11]
	v_pk_mul_f32 v[8:9], v[20:21], v[8:9]
	v_cvt_pk_bf16_f32 v0, v0, v1
	v_cvt_pk_bf16_f32 v1, v2, v3
	v_pk_mul_f32 v[12:13], v[42:43], v[6:7] op_sel_hi:[1,0]
	v_cvt_pk_bf16_f32 v2, v8, v9
	v_cvt_pk_bf16_f32 v3, v10, v11
	global_store_dwordx4 v[16:17], v[0:3], off offset:1024
	s_nop 1
	s_nop 0
	v_pk_mul_f32 v[18:19], v[54:55], v[6:7] op_sel_hi:[1,0]
	v_pk_mul_f32 v[20:21], v[56:57], v[6:7] op_sel_hi:[1,0]
	v_pk_mul_f32 v[22:23], v[58:59], v[6:7] op_sel_hi:[1,0]
	v_mov_b32_e32 v0, v182
	v_mov_b32_e32 v1, v183
	v_mov_b32_e32 v2, v184
	v_mov_b32_e32 v3, v185
	v_mov_b32_e32 v8, v186
	v_mov_b32_e32 v9, v187
	v_mov_b32_e32 v10, v188
	v_mov_b32_e32 v11, v189
	v_pk_mul_f32 v[2:3], v[18:19], v[2:3]
	v_pk_mul_f32 v[0:1], v[12:13], v[0:1]
	v_pk_mul_f32 v[10:11], v[22:23], v[10:11]
	v_pk_mul_f32 v[8:9], v[20:21], v[8:9]
	v_cvt_pk_bf16_f32 v0, v0, v1
	v_cvt_pk_bf16_f32 v1, v2, v3
	v_pk_mov_b32 v[12:13], v[32:33], v[14:15] op_sel:[1,0]
	v_cvt_pk_bf16_f32 v2, v8, v9
	v_cvt_pk_bf16_f32 v3, v10, v11
	global_store_dwordx4 v[16:17], v[0:3], off offset:2048
	s_nop 1
	s_nop 0
	v_pk_mov_b32 v[14:15], v[38:39], v[36:37] op_sel:[1,0]
	v_pk_mul_f32 v[18:19], v[28:29], v[6:7] op_sel_hi:[1,0]
	v_pk_mul_f32 v[12:13], v[6:7], v[12:13] op_sel_hi:[0,1]
	v_pk_mul_f32 v[6:7], v[6:7], v[14:15] op_sel_hi:[0,1]
	v_mov_b32_e32 v0, v190
	v_mov_b32_e32 v1, v191
	v_mov_b32_e32 v2, v192
	v_mov_b32_e32 v3, v193
	v_mov_b32_e32 v8, v200
	v_mov_b32_e32 v9, v201
	v_mov_b32_e32 v10, v202
	v_mov_b32_e32 v11, v203
	v_pk_mul_f32 v[2:3], v[4:5], v[2:3]
	v_pk_mul_f32 v[0:1], v[18:19], v[0:1]
	v_pk_mul_f32 v[4:5], v[6:7], v[10:11]
	v_pk_mul_f32 v[6:7], v[12:13], v[8:9]
	v_cvt_pk_bf16_f32 v0, v0, v1
	v_cvt_pk_bf16_f32 v1, v2, v3
	s_nop 0
	v_cvt_pk_bf16_f32 v2, v6, v7
	v_cvt_pk_bf16_f32 v3, v4, v5
	global_store_dwordx4 v[16:17], v[0:3], off offset:3072
	s_nop 1

.LBB0_846:
	s_or_b64 exec, exec, s[58:59]
	s_waitcnt lgkmcnt(0)
	s_barrier
	ds_read_b32 v0, v92
	s_movk_i32 s40, 0x1ff
	s_mov_b64 s[58:59], -1
	s_waitcnt lgkmcnt(0)
	v_cmp_lt_i32_e32 vcc, s40, v0
	v_readfirstlane_b32 s66, v0
	s_cbranch_vccnz .LBB0_843
	s_mov_b32 s40, 3
	s_ashr_i32 s41, s40, 31
	s_ashr_i32 s58, s66, 2
	s_lshl_b64 s[40:41], s[40:41], 3
	s_add_u32 s40, s0, s40
	s_addc_u32 s41, s1, s41
	s_load_dwordx2 s[64:65], s[40:41], 0x0
	s_lshl_b32 s40, s66, 9
	s_and_b32 s48, s40, 0x600
	s_mov_b32 s40, 4
	s_ashr_i32 s41, s40, 31
	s_lshl_b64 s[40:41], s[40:41], 3
	s_add_u32 s40, s0, s40
	s_addc_u32 s41, s1, s41
	s_load_dwordx2 s[60:61], s[40:41], 0x0
	s_and_b64 vcc, exec, s[14:15]
	s_lshl_b32 s67, s58, 3
	s_cbranch_vccnz .LBB0_849
	v_add_u32_e32 v0, s67, v85
	v_ashrrev_i32_e32 v1, 31, v0
	v_lshlrev_b64 v[0:1], 12, v[0:1]
	v_lshl_add_u64 v[0:1], s[50:51], 0, v[0:1]
	s_lshl_b32 s40, s48, 1
	s_mov_b32 s41, s49
	v_lshl_add_u64 v[0:1], v[0:1], 0, s[40:41]
	v_mov_b32_e32 v73, v65
	v_lshl_add_u64 v[8:9], v[0:1], 0, v[72:73]
	s_mov_b32 s40, 0x400000
	v_add_co_u32_e32 v4, vcc, s40, v8
	s_mov_b32 s40, 0x800000
	s_nop 0
	v_addc_co_u32_e32 v5, vcc, 0, v9, vcc
	v_add_co_u32_e32 v10, vcc, s40, v8
	s_mov_b32 s40, 0xc00000
	s_nop 0
	v_addc_co_u32_e32 v11, vcc, 0, v9, vcc
	flat_load_dwordx4 v[12:15], v[10:11] nt
	v_add_co_u32_e32 v10, vcc, s40, v8
	s_mov_b32 s40, 0x1000000
	s_nop 0
	v_addc_co_u32_e32 v11, vcc, 0, v9, vcc
	flat_load_dwordx4 v[16:19], v[10:11] nt
	v_add_co_u32_e32 v10, vcc, s40, v8
	flat_load_dwordx4 v[0:3], v[8:9] nt
	s_nop 0
	v_addc_co_u32_e32 v11, vcc, 0, v9, vcc
	s_mov_b32 s40, 0x1400000
	flat_load_dwordx4 v[4:7], v[4:5] nt
	s_waitcnt vmcnt(0) lgkmcnt(0)
	v_lshlrev_b32_e32 v40, 16, v12
	flat_load_dwordx4 v[20:23], v[10:11] nt
	v_add_co_u32_e32 v10, vcc, s40, v8
	s_mov_b32 s40, 0x1800000
	s_nop 0
	v_addc_co_u32_e32 v11, vcc, 0, v9, vcc
	flat_load_dwordx4 v[24:27], v[10:11] nt
	v_add_co_u32_e32 v10, vcc, s40, v8
	s_mov_b32 s40, 0x1c00000
	s_nop 0
	v_addc_co_u32_e32 v11, vcc, 0, v9, vcc
	v_add_co_u32_e32 v8, vcc, s40, v8
	flat_load_dwordx4 v[28:31], v[10:11] nt
	s_nop 0
	v_addc_co_u32_e32 v9, vcc, 0, v9, vcc
	flat_load_dwordx4 v[8:11], v[8:9] nt
	v_lshlrev_b32_e32 v32, 16, v0
	v_and_b32_e32 v33, 0xffff0000, v0
	v_lshlrev_b32_e32 v0, 16, v1
	v_and_b32_e32 v1, 0xffff0000, v1
	v_lshlrev_b32_e32 v34, 16, v2
	v_and_b32_e32 v35, 0xffff0000, v2
	v_lshlrev_b32_e32 v2, 16, v3
	v_and_b32_e32 v3, 0xffff0000, v3
	v_pk_add_f32 v[0:1], v[0:1], 0 op_sel_hi:[1,0]
	v_pk_add_f32 v[32:33], v[32:33], 0 op_sel_hi:[1,0]
	v_pk_add_f32 v[2:3], v[2:3], 0 op_sel_hi:[1,0]
	v_pk_add_f32 v[34:35], v[34:35], 0 op_sel_hi:[1,0]
	v_lshlrev_b32_e32 v36, 16, v4
	v_and_b32_e32 v37, 0xffff0000, v4
	v_lshlrev_b32_e32 v4, 16, v5
	v_and_b32_e32 v5, 0xffff0000, v5
	v_lshlrev_b32_e32 v38, 16, v6
	v_and_b32_e32 v39, 0xffff0000, v6
	v_lshlrev_b32_e32 v6, 16, v7
	v_and_b32_e32 v7, 0xffff0000, v7
	v_and_b32_e32 v41, 0xffff0000, v12
	v_lshlrev_b32_e32 v12, 16, v13
	v_and_b32_e32 v13, 0xffff0000, v13
	v_lshlrev_b32_e32 v42, 16, v14
	v_and_b32_e32 v43, 0xffff0000, v14
	v_lshlrev_b32_e32 v14, 16, v15
	v_and_b32_e32 v15, 0xffff0000, v15
	v_pk_add_f32 v[32:33], v[32:33], v[36:37]
	v_pk_add_f32 v[0:1], v[0:1], v[4:5]
	v_pk_add_f32 v[4:5], v[34:35], v[38:39]
	v_pk_add_f32 v[2:3], v[2:3], v[6:7]
	v_lshlrev_b32_e32 v44, 16, v16
	v_and_b32_e32 v45, 0xffff0000, v16
	v_pk_add_f32 v[0:1], v[0:1], v[12:13]
	v_pk_add_f32 v[6:7], v[32:33], v[40:41]
	v_pk_add_f32 v[2:3], v[2:3], v[14:15]
	v_pk_add_f32 v[4:5], v[4:5], v[42:43]
	v_lshlrev_b32_e32 v12, 16, v17
	v_and_b32_e32 v13, 0xffff0000, v17
	v_lshlrev_b32_e32 v14, 16, v18
	v_and_b32_e32 v15, 0xffff0000, v18
	v_lshlrev_b32_e32 v16, 16, v19
	v_and_b32_e32 v17, 0xffff0000, v19
	v_pk_add_f32 v[6:7], v[6:7], v[44:45]
	v_pk_add_f32 v[0:1], v[0:1], v[12:13]
	v_pk_add_f32 v[4:5], v[4:5], v[14:15]
	v_pk_add_f32 v[2:3], v[2:3], v[16:17]
	s_waitcnt vmcnt(0) lgkmcnt(0)
	v_lshlrev_b32_e32 v12, 16, v20
	v_and_b32_e32 v13, 0xffff0000, v20
	v_lshlrev_b32_e32 v14, 16, v21
	v_and_b32_e32 v15, 0xffff0000, v21
	v_lshlrev_b32_e32 v18, 16, v23
	v_and_b32_e32 v19, 0xffff0000, v23
	v_lshlrev_b32_e32 v16, 16, v22
	v_and_b32_e32 v17, 0xffff0000, v22
	v_pk_add_f32 v[0:1], v[0:1], v[14:15]
	v_pk_add_f32 v[6:7], v[6:7], v[12:13]
	v_pk_add_f32 v[2:3], v[2:3], v[18:19]
	v_lshlrev_b32_e32 v12, 16, v24
	v_and_b32_e32 v13, 0xffff0000, v24
	v_lshlrev_b32_e32 v14, 16, v25
	v_and_b32_e32 v15, 0xffff0000, v25
	v_lshlrev_b32_e32 v18, 16, v27
	v_and_b32_e32 v19, 0xffff0000, v27
	v_pk_add_f32 v[4:5], v[4:5], v[16:17]
	v_lshlrev_b32_e32 v16, 16, v26
	v_and_b32_e32 v17, 0xffff0000, v26
	v_pk_add_f32 v[6:7], v[6:7], v[12:13]
	v_pk_add_f32 v[0:1], v[0:1], v[14:15]
	v_pk_add_f32 v[12:13], v[2:3], v[18:19]
	v_lshlrev_b32_e32 v2, 16, v29
	v_and_b32_e32 v3, 0xffff0000, v29
	v_lshlrev_b32_e32 v18, 16, v31
	v_and_b32_e32 v19, 0xffff0000, v31
	v_pk_add_f32 v[4:5], v[4:5], v[16:17]
	v_lshlrev_b32_e32 v14, 16, v28
	v_and_b32_e32 v15, 0xffff0000, v28
	v_lshlrev_b32_e32 v16, 16, v30
	v_and_b32_e32 v17, 0xffff0000, v30
	v_pk_add_f32 v[2:3], v[0:1], v[2:3]
	v_pk_add_f32 v[0:1], v[12:13], v[18:19]
	v_lshlrev_b32_e32 v12, 16, v8
	v_and_b32_e32 v13, 0xffff0000, v8
	v_lshlrev_b32_e32 v8, 16, v9
	v_and_b32_e32 v9, 0xffff0000, v9
	v_pk_add_f32 v[6:7], v[6:7], v[14:15]
	v_pk_add_f32 v[4:5], v[4:5], v[16:17]
	v_lshlrev_b32_e32 v14, 16, v10
	v_and_b32_e32 v15, 0xffff0000, v10
	v_lshlrev_b32_e32 v10, 16, v11
	v_and_b32_e32 v11, 0xffff0000, v11
	v_pk_add_f32 v[2:3], v[2:3], v[8:9]
	v_pk_add_f32 v[6:7], v[6:7], v[12:13]
	v_pk_add_f32 v[4:5], v[4:5], v[14:15]
	v_pk_add_f32 v[0:1], v[0:1], v[10:11]
	v_pk_mul_f32 v[2:3], v[2:3], s[54:55] op_sel_hi:[1,0]
	v_pk_mul_f32 v[6:7], v[6:7], s[54:55] op_sel_hi:[1,0]
	v_pk_mul_f32 v[8:9], v[0:1], s[54:55] op_sel_hi:[1,0]
	v_pk_mul_f32 v[4:5], v[4:5], s[54:55] op_sel_hi:[1,0]
	v_cvt_pk_bf16_f32 v0, v6, v7
	v_cvt_pk_bf16_f32 v1, v2, v3
	s_nop 0
	v_cvt_pk_bf16_f32 v2, v4, v5
	v_cvt_pk_bf16_f32 v3, v8, v9
	ds_write_b128 v86, v[0:3] offset:9472
	s_waitcnt lgkmcnt(0)
	s_barrier

.LBB0_1026:
	s_or_b64 exec, exec, s[6:7]
	s_waitcnt lgkmcnt(0)
	v_mov_b32_e32 v0, v164
	s_barrier
	s_add_u32 s6, s34, 0x2aa00000
	s_mov_b32 s8, 22
	s_addc_u32 s7, s35, 0
	s_ashr_i32 s9, s8, 31
	s_lshl_b64 s[8:9], s[8:9], 3
	s_add_u32 s8, s0, s8
	s_addc_u32 s9, s1, s9
	s_load_dwordx2 s[12:13], s[8:9], 0x0
	v_and_b32_e32 v0, 63, v0
	s_add_u32 s10, s34, 0x9800000
	s_addc_u32 s11, s35, 0
	s_and_b64 vcc, exec, s[4:5]
	v_lshlrev_b32_e32 v40, 4, v0
	v_lshlrev_b32_e32 v48, 5, v0
	s_mov_b32 s48, s24
	s_cbranch_vccnz .LBB0_1028
	v_mov_b32_e32 v41, 0
	s_ashr_i32 s25, s24, 31
	v_lshl_add_u64 v[0:1], s[6:7], 0, v[40:41]
	s_lshl_b64 s[48:49], s[24:25], 12
	v_lshl_add_u64 v[2:3], v[0:1], 0, s[48:49]
	s_add_i32 s8, s24, s18
	flat_load_dwordx4 v[4:7], v[2:3] offset:1024 nt
	flat_load_dwordx4 v[28:31], v[2:3] offset:2048 nt
	flat_load_dwordx4 v[24:27], v[2:3] offset:3072 nt
	flat_load_dwordx4 v[32:35], v[2:3] nt
	s_ashr_i32 s9, s8, 31
	s_lshl_b64 s[44:45], s[8:9], 12
	v_lshl_add_u64 v[2:3], v[0:1], 0, s[44:45]
	flat_load_dwordx4 v[36:39], v[2:3] nt
	flat_load_dwordx4 v[44:47], v[2:3] offset:1024 nt
	flat_load_dwordx4 v[110:113], v[2:3] offset:2048 nt
	flat_load_dwordx4 v[12:15], v[2:3] offset:3072 nt
	v_readlane_b32 s14, v226, 1
	v_readlane_b32 s15, v226, 2
	s_mov_b32 s28, s14
	s_ashr_i32 s29, s14, 31
	s_add_i32 s14, s8, s18
	s_mov_b32 s8, s28
	s_ashr_i32 s15, s14, 31
	v_writelane_b32 v226, s8, 1
	s_lshl_b64 s[14:15], s[14:15], 12
	v_lshl_add_u64 v[42:43], v[0:1], 0, s[14:15]
	v_writelane_b32 v226, s9, 2
	s_lshl_b64 s[8:9], s[28:29], 12
	v_lshl_add_u64 v[108:109], v[0:1], 0, s[8:9]
	flat_load_dwordx4 v[20:23], v[42:43] nt
	flat_load_dwordx4 v[16:19], v[42:43] offset:1024 nt
	flat_load_dwordx4 v[8:11], v[42:43] offset:2048 nt
	flat_load_dwordx4 v[0:3], v[42:43] offset:3072 nt
	s_waitcnt lgkmcnt(0)
	v_add_u32_e32 v204, 0x1000, v48
	global_load_dwordx4 v[166:169], v48, s[12:13]
	global_load_dwordx4 v[170:173], v48, s[12:13] offset:16
	global_load_dwordx4 v[174:177], v48, s[12:13] offset:2048
	global_load_dwordx4 v[178:181], v48, s[12:13] offset:2064
	global_load_dwordx4 v[182:185], v204, s[12:13]
	global_load_dwordx4 v[186:189], v204, s[12:13] offset:16
	global_load_dwordx4 v[190:193], v204, s[12:13] offset:2048
	global_load_dwordx4 v[200:203], v204, s[12:13] offset:2064
	s_mov_b32 s40, 0x358637bd
	s_mov_b32 s46, 0x3a000000
	s_mov_b32 s3, 0x800000
	v_or_b32_e32 v49, 0x1800, v48
	v_mov_b32_e32 v105, v41
	s_waitcnt vmcnt(0)
	v_mov_b32_e32 v120, v170
	v_mov_b32_e32 v121, v171
	v_mov_b32_e32 v122, v172
	v_mov_b32_e32 v123, v173
	v_mov_b32_e32 v124, v166
	v_mov_b32_e32 v125, v167
	v_mov_b32_e32 v126, v168
	v_mov_b32_e32 v127, v169
	v_lshlrev_b32_e32 v69, 16, v4
	v_and_b32_e32 v55, 0xffff0000, v29
	v_lshlrev_b32_e32 v59, 16, v28
	v_and_b32_e32 v71, 0xffff0000, v32
	v_and_b32_e32 v70, 0xffff0000, v36
	v_lshlrev_b32_e32 v63, 16, v32
	v_and_b32_e32 v67, 0xffff0000, v28
	v_lshlrev_b32_e32 v61, 16, v29
	v_lshlrev_b32_e32 v62, 16, v36
	v_pk_mul_f32 v[28:29], v[70:71], v[70:71]
	v_lshlrev_b32_e32 v65, 16, v33
	v_and_b32_e32 v77, 0xffff0000, v33
	v_lshlrev_b32_e32 v64, 16, v37
	v_pk_fma_f32 v[32:33], v[62:63], v[62:63], v[28:29]
	v_and_b32_e32 v76, 0xffff0000, v37
	v_pk_fma_f32 v[32:33], v[64:65], v[64:65], v[32:33]
	v_lshlrev_b32_e32 v73, 16, v34
	v_lshlrev_b32_e32 v72, 16, v38
	v_pk_fma_f32 v[32:33], v[76:77], v[76:77], v[32:33]
	v_and_b32_e32 v85, 0xffff0000, v34
	v_and_b32_e32 v84, 0xffff0000, v38
	v_pk_fma_f32 v[32:33], v[72:73], v[72:73], v[32:33]
	v_lshlrev_b32_e32 v83, 16, v35
	v_lshlrev_b32_e32 v82, 16, v39
	v_pk_fma_f32 v[32:33], v[84:85], v[84:85], v[32:33]
	v_and_b32_e32 v95, 0xffff0000, v35
	v_and_b32_e32 v94, 0xffff0000, v39
	v_pk_fma_f32 v[32:33], v[82:83], v[82:83], v[32:33]
	v_lshlrev_b32_e32 v68, 16, v44
	v_pk_fma_f32 v[32:33], v[94:95], v[94:95], v[32:33]
	v_and_b32_e32 v57, 0xffff0000, v4
	v_and_b32_e32 v56, 0xffff0000, v44
	v_pk_fma_f32 v[32:33], v[68:69], v[68:69], v[32:33]
	v_lshlrev_b32_e32 v81, 16, v5
	v_lshlrev_b32_e32 v80, 16, v45
	v_pk_fma_f32 v[32:33], v[56:57], v[56:57], v[32:33]
	v_and_b32_e32 v91, 0xffff0000, v5
	v_and_b32_e32 v90, 0xffff0000, v45
	v_pk_fma_f32 v[32:33], v[80:81], v[80:81], v[32:33]
	v_lshlrev_b32_e32 v87, 16, v6
	v_lshlrev_b32_e32 v86, 16, v46
	v_pk_fma_f32 v[32:33], v[90:91], v[90:91], v[32:33]
	v_and_b32_e32 v93, 0xffff0000, v6
	v_and_b32_e32 v92, 0xffff0000, v46
	v_pk_fma_f32 v[32:33], v[86:87], v[86:87], v[32:33]
	v_lshlrev_b32_e32 v89, 16, v7
	v_lshlrev_b32_e32 v88, 16, v47
	v_pk_fma_f32 v[32:33], v[92:93], v[92:93], v[32:33]
	v_and_b32_e32 v97, 0xffff0000, v7
	v_and_b32_e32 v96, 0xffff0000, v47
	v_pk_fma_f32 v[32:33], v[88:89], v[88:89], v[32:33]
	v_lshlrev_b32_e32 v58, 16, v110
	v_pk_fma_f32 v[32:33], v[96:97], v[96:97], v[32:33]
	v_and_b32_e32 v66, 0xffff0000, v110
	v_pk_fma_f32 v[32:33], v[58:59], v[58:59], v[32:33]
	v_lshlrev_b32_e32 v60, 16, v111
	v_pk_fma_f32 v[32:33], v[66:67], v[66:67], v[32:33]
	v_lshlrev_b32_e32 v43, 16, v30
	v_and_b32_e32 v79, 0xffff0000, v30
	v_lshlrev_b32_e32 v75, 16, v31
	v_and_b32_e32 v54, 0xffff0000, v111
	v_and_b32_e32 v99, 0xffff0000, v31
	v_pk_fma_f32 v[30:31], v[60:61], v[60:61], v[32:33]
	v_lshlrev_b32_e32 v42, 16, v112
	v_pk_fma_f32 v[30:31], v[54:55], v[54:55], v[30:31]
	v_and_b32_e32 v78, 0xffff0000, v112
	v_pk_fma_f32 v[30:31], v[42:43], v[42:43], v[30:31]
	v_lshlrev_b32_e32 v74, 16, v113
	v_pk_fma_f32 v[30:31], v[78:79], v[78:79], v[30:31]
	v_and_b32_e32 v100, 0xffff0000, v26
	v_and_b32_e32 v98, 0xffff0000, v113
	v_pk_fma_f32 v[30:31], v[74:75], v[74:75], v[30:31]
	v_lshlrev_b32_e32 v103, 16, v26
	v_mov_b32_e32 v102, v100
	v_pk_fma_f32 v[30:31], v[98:99], v[98:99], v[30:31]
	v_lshlrev_b32_e32 v45, 16, v24
	v_lshlrev_b32_e32 v44, 16, v12
	v_and_b32_e32 v26, 0xffff0000, v14
	v_pk_mul_f32 v[6:7], v[102:103], v[102:103]
	v_and_b32_e32 v47, 0xffff0000, v24
	v_and_b32_e32 v46, 0xffff0000, v12
	v_lshlrev_b32_e32 v50, 16, v13
	v_and_b32_e32 v24, 0xffff0000, v13
	v_pk_fma_f32 v[12:13], v[44:45], v[44:45], v[30:31]
	v_lshlrev_b32_e32 v53, 16, v14
	v_mov_b32_e32 v52, v26
	v_lshlrev_b32_e32 v51, 16, v25
	v_pk_fma_f32 v[12:13], v[46:47], v[46:47], v[12:13]
	v_mov_b32_e32 v31, v7
	v_and_b32_e32 v7, 64, v196
	v_and_b32_e32 v104, 0xffff0000, v27
	v_pk_mul_f32 v[28:29], v[52:53], v[52:53]
	v_and_b32_e32 v25, 0xffff0000, v25
	v_pk_fma_f32 v[12:13], v[50:51], v[50:51], v[12:13]
	v_and_b32_e32 v110, 0xffff0000, v15
	v_add_u32_e32 v14, 64, v7
	v_xor_b32_e32 v7, 1, v196
	v_lshlrev_b32_e32 v107, 16, v27
	v_mov_b32_e32 v106, v104
	v_pk_fma_f32 v[12:13], v[24:25], v[24:25], v[12:13]
	v_mov_b32_e32 v30, v29
	v_lshlrev_b32_e32 v113, 16, v15
	v_mov_b32_e32 v112, v110
	v_cmp_lt_i32_e32 vcc, v7, v14
	v_pk_mul_f32 v[4:5], v[106:107], v[106:107]
	v_pk_add_f32 v[12:13], v[30:31], v[12:13]
	v_pk_mul_f32 v[30:31], v[112:113], v[112:113]
	v_cndmask_b32_e32 v7, v196, v7, vcc
	v_mov_b32_e32 v29, v6
	v_lshlrev_b32_e32 v114, 2, v7
	v_pk_add_f32 v[6:7], v[28:29], v[12:13]
	v_mov_b32_e32 v12, v31
	v_mov_b32_e32 v13, v5
	v_pk_add_f32 v[6:7], v[12:13], v[6:7]
	v_mov_b32_e32 v31, v4
	v_pk_add_f32 v[4:5], v[30:31], v[6:7]
	ds_bpermute_b32 v7, v114, v5
	ds_bpermute_b32 v6, v114, v4
	v_xor_b32_e32 v12, 2, v196
	v_cmp_lt_i32_e32 vcc, v12, v14
	v_mov_b32_e32 v130, v63
	v_mov_b32_e32 v131, v71
	v_cndmask_b32_e32 v12, v196, v12, vcc
	v_lshlrev_b32_e32 v116, 2, v12
	s_waitcnt lgkmcnt(0)
	v_pk_add_f32 v[4:5], v[4:5], v[6:7]
	ds_bpermute_b32 v7, v116, v5
	ds_bpermute_b32 v6, v116, v4
	v_xor_b32_e32 v12, 4, v196
	v_cmp_lt_i32_e32 vcc, v12, v14
	v_mov_b32_e32 v132, v65
	v_mov_b32_e32 v133, v77
	v_cndmask_b32_e32 v12, v196, v12, vcc
	v_lshlrev_b32_e32 v117, 2, v12
	s_waitcnt lgkmcnt(0)
	v_pk_add_f32 v[4:5], v[4:5], v[6:7]
	ds_bpermute_b32 v7, v117, v5
	ds_bpermute_b32 v6, v117, v4
	v_xor_b32_e32 v12, 8, v196
	v_cmp_lt_i32_e32 vcc, v12, v14
	v_mov_b32_e32 v134, v87
	v_mov_b32_e32 v135, v93
	v_cndmask_b32_e32 v12, v196, v12, vcc
	v_lshlrev_b32_e32 v118, 2, v12
	s_waitcnt lgkmcnt(0)
	v_pk_add_f32 v[4:5], v[4:5], v[6:7]
	ds_bpermute_b32 v7, v118, v5
	ds_bpermute_b32 v6, v118, v4
	v_xor_b32_e32 v12, 16, v196
	v_cmp_lt_i32_e32 vcc, v12, v14
	v_mov_b32_e32 v136, v89
	v_mov_b32_e32 v137, v97
	v_cndmask_b32_e32 v12, v196, v12, vcc
	v_lshlrev_b32_e32 v119, 2, v12
	s_waitcnt lgkmcnt(0)
	v_pk_add_f32 v[4:5], v[4:5], v[6:7]
	ds_bpermute_b32 v7, v119, v5
	ds_bpermute_b32 v6, v119, v4
	v_xor_b32_e32 v12, 32, v196
	v_cmp_lt_i32_e32 vcc, v12, v14
	v_and_b32_e32 v101, s0, v27
	v_pk_mov_b32 v[100:101], v[102:103], v[100:101] op_sel:[1,0]
	v_cndmask_b32_e32 v12, v196, v12, vcc
	v_lshlrev_b32_e32 v115, 2, v12
	s_waitcnt lgkmcnt(0)
	v_pk_add_f32 v[12:13], v[4:5], v[6:7]
	ds_bpermute_b32 v129, v115, v13
	ds_bpermute_b32 v128, v115, v12
	flat_load_dwordx4 v[36:39], v[108:109] nt
	flat_load_dwordx4 v[32:35], v[108:109] offset:1024 nt
	flat_load_dwordx4 v[28:31], v[108:109] offset:2048 nt
	flat_load_dwordx4 v[4:7], v[108:109] offset:3072 nt
	v_mov_b64_e32 v[108:109], s[40:41]
	s_add_u32 s40, s10, s48
	s_addc_u32 s41, s11, s49
	s_waitcnt lgkmcnt(0)
	v_pk_add_f32 v[12:13], v[12:13], v[128:129]
	v_lshl_add_u64 v[128:129], s[40:41], 0, v[40:41]
	v_pk_fma_f32 v[12:13], v[12:13], s[46:47], v[108:109] op_sel_hi:[1,0,0]
	v_pk_mov_b32 v[102:103], v[106:107], v[104:105] op_sel:[1,0]
	v_mul_f32_e32 v14, 0x4b800000, v13
	v_cmp_gt_f32_e32 vcc, s3, v13
	s_add_u32 s40, s10, s44
	v_mov_b32_e32 v63, v70
	v_cndmask_b32_e32 v13, v13, v14, vcc
	v_rsq_f32_e32 v13, v13
	v_mov_b32_e32 v65, v76
	s_addc_u32 s41, s11, s45
	v_mov_b32_e32 v87, v92
	v_mul_f32_e32 v14, 0x45800000, v13
	v_cndmask_b32_e32 v14, v13, v14, vcc
	v_pk_mul_f32 v[130:131], v[130:131], v[14:15] op_sel_hi:[1,0]
	v_pk_mul_f32 v[132:133], v[132:133], v[14:15] op_sel_hi:[1,0]
	v_pk_mul_f32 v[124:125], v[124:125], v[130:131]
	v_pk_mul_f32 v[126:127], v[126:127], v[132:133]
	v_mov_b32_e32 v130, v73
	v_mov_b32_e32 v131, v85
	v_mov_b32_e32 v132, v83
	v_mov_b32_e32 v133, v95
	v_pk_mul_f32 v[130:131], v[130:131], v[14:15] op_sel_hi:[1,0]
	v_pk_mul_f32 v[132:133], v[132:133], v[14:15] op_sel_hi:[1,0]
	v_pk_mul_f32 v[134:135], v[134:135], v[14:15] op_sel_hi:[1,0]
	v_pk_mul_f32 v[132:133], v[122:123], v[132:133]
	v_pk_mul_f32 v[122:123], v[120:121], v[130:131]
	v_cvt_pk_bf16_f32 v120, v124, v125
	v_cvt_pk_bf16_f32 v121, v126, v127
	v_mov_b32_e32 v130, v69
	v_cvt_pk_bf16_f32 v122, v122, v123
	v_cvt_pk_bf16_f32 v123, v132, v133
	global_store_dwordx4 v[128:129], v[120:123], off
	s_nop 1
	s_nop 0
	v_mov_b32_e32 v131, v57
	v_mov_b32_e32 v132, v81
	v_mov_b32_e32 v133, v91
	v_pk_mul_f32 v[130:131], v[130:131], v[14:15] op_sel_hi:[1,0]
	v_pk_mul_f32 v[132:133], v[132:133], v[14:15] op_sel_hi:[1,0]
	v_pk_mul_f32 v[136:137], v[136:137], v[14:15] op_sel_hi:[1,0]
	v_or_b32_e32 v13, 0x1000, v48
	v_pk_mul_f32 v[100:101], v[14:15], v[100:101] op_sel_hi:[0,1]
	v_pk_mul_f32 v[102:103], v[14:15], v[102:103] op_sel_hi:[0,1]
	v_cmp_gt_f32_e32 vcc, s3, v12
	v_mov_b32_e32 v73, v84
	v_mov_b32_e32 v83, v94
	v_mov_b32_e32 v69, v56
	v_mov_b32_e32 v81, v90
	v_mov_b32_e32 v89, v96
	v_and_b32_e32 v97, 0xffff0000, v20
	v_lshlrev_b32_e32 v85, 16, v21
	v_and_b32_e32 v91, 0xffff0000, v21
	v_and_b32_e32 v93, 0xffff0000, v22
	v_and_b32_e32 v27, s0, v15
	v_and_b32_e32 v95, 0xffff0000, v23
	v_mov_b32_e32 v111, v41
	s_add_u32 s14, s10, s14
	s_addc_u32 s15, s11, s15
	s_add_u32 s8, s10, s8
	s_addc_u32 s9, s11, s9
	s_waitcnt vmcnt(1)
	v_mov_b32_e32 v120, v174
	v_mov_b32_e32 v121, v175
	v_mov_b32_e32 v122, v176
	v_mov_b32_e32 v123, v177
	v_mov_b32_e32 v124, v178
	v_mov_b32_e32 v125, v179
	v_mov_b32_e32 v126, v180
	v_mov_b32_e32 v127, v181
	v_and_b32_e32 v96, 0xffff0000, v36
	v_lshlrev_b32_e32 v84, 16, v37
	v_and_b32_e32 v90, 0xffff0000, v37
	v_and_b32_e32 v92, 0xffff0000, v38
	v_and_b32_e32 v94, 0xffff0000, v39
	v_pk_mul_f32 v[122:123], v[122:123], v[132:133]
	v_pk_mul_f32 v[120:121], v[120:121], v[130:131]
	v_pk_mul_f32 v[126:127], v[126:127], v[136:137]
	v_pk_mul_f32 v[124:125], v[124:125], v[134:135]
	v_cvt_pk_bf16_f32 v120, v120, v121
	v_cvt_pk_bf16_f32 v121, v122, v123
	v_mov_b32_e32 v130, v59
	v_cvt_pk_bf16_f32 v122, v124, v125
	v_cvt_pk_bf16_f32 v123, v126, v127
	global_store_dwordx4 v[128:129], v[120:123], off offset:1024
	s_nop 1
	s_nop 0
	v_mov_b32_e32 v131, v67
	v_mov_b32_e32 v132, v61
	v_mov_b32_e32 v133, v55
	v_mov_b32_e32 v134, v43
	v_mov_b32_e32 v135, v79
	v_mov_b32_e32 v136, v75
	v_mov_b32_e32 v137, v99
	v_pk_mul_f32 v[130:131], v[130:131], v[14:15] op_sel_hi:[1,0]
	v_pk_mul_f32 v[132:133], v[132:133], v[14:15] op_sel_hi:[1,0]
	v_pk_mul_f32 v[134:135], v[134:135], v[14:15] op_sel_hi:[1,0]
	v_pk_mul_f32 v[136:137], v[136:137], v[14:15] op_sel_hi:[1,0]
	v_mov_b32_e32 v59, v66
	v_mov_b32_e32 v61, v54
	v_mov_b32_e32 v43, v78
	v_mov_b32_e32 v75, v98
	v_and_b32_e32 v98, 0xffff0000, v2
	v_and_b32_e32 v66, 0xffff0000, v30
	v_and_b32_e32 v67, 0xffff0000, v10
	v_and_b32_e32 v79, 0xffff0000, v19
	v_and_b32_e32 v78, 0xffff0000, v35
	v_and_b32_e32 v99, s0, v3
	v_mov_b32_e32 v120, v182
	v_mov_b32_e32 v121, v183
	v_mov_b32_e32 v122, v184
	v_mov_b32_e32 v123, v185
	v_mov_b32_e32 v124, v186
	v_mov_b32_e32 v125, v187
	v_mov_b32_e32 v126, v188
	v_mov_b32_e32 v127, v189
	v_pk_mul_f32 v[122:123], v[132:133], v[122:123]
	v_pk_mul_f32 v[120:121], v[130:131], v[120:121]
	v_pk_mul_f32 v[126:127], v[136:137], v[126:127]
	v_pk_mul_f32 v[124:125], v[134:135], v[124:125]
	v_cvt_pk_bf16_f32 v120, v120, v121
	v_cvt_pk_bf16_f32 v121, v122, v123
	v_mov_b32_e32 v130, v45
	v_cvt_pk_bf16_f32 v122, v124, v125
	v_cvt_pk_bf16_f32 v123, v126, v127
	global_store_dwordx4 v[128:129], v[120:123], off offset:2048
	s_nop 1
	s_nop 0
	v_mov_b32_e32 v131, v47
	v_mov_b32_e32 v132, v51
	v_mov_b32_e32 v133, v25
	v_pk_mul_f32 v[104:105], v[130:131], v[14:15] op_sel_hi:[1,0]
	v_pk_mul_f32 v[106:107], v[132:133], v[14:15] op_sel_hi:[1,0]
	v_mul_f32_e32 v14, 0x4b800000, v12
	v_cndmask_b32_e32 v12, v12, v14, vcc
	v_rsq_f32_e32 v12, v12
	v_lshlrev_b32_e32 v15, 16, v0
	v_mov_b32_e32 v45, v46
	v_mov_b32_e32 v51, v24
	v_mul_f32_e32 v14, 0x45800000, v12
	v_mov_b32_e32 v120, v190
	v_mov_b32_e32 v121, v191
	v_mov_b32_e32 v122, v192
	v_mov_b32_e32 v123, v193
	v_mov_b32_e32 v124, v200
	v_mov_b32_e32 v125, v201
	v_mov_b32_e32 v126, v202
	v_mov_b32_e32 v127, v203
	v_pk_mul_f32 v[104:105], v[104:105], v[120:121]
	v_pk_mul_f32 v[120:121], v[102:103], v[126:127]
	v_pk_mul_f32 v[102:103], v[100:101], v[124:125]
	v_pk_mul_f32 v[106:107], v[106:107], v[122:123]
	v_cvt_pk_bf16_f32 v100, v104, v105
	v_lshlrev_b32_e32 v105, 16, v2
	v_cvt_pk_bf16_f32 v101, v106, v107
	v_cvt_pk_bf16_f32 v102, v102, v103
	v_cvt_pk_bf16_f32 v103, v120, v121
	global_store_dwordx4 v[128:129], v[100:103], off offset:3072
	s_nop 1
	s_nop 0
	v_cndmask_b32_e32 v128, v12, v14, vcc
	v_pk_mul_f32 v[62:63], v[62:63], v[128:129] op_sel_hi:[1,0]
	v_pk_mul_f32 v[64:65], v[64:65], v[128:129] op_sel_hi:[1,0]
	v_lshl_add_u64 v[106:107], s[40:41], 0, v[40:41]
	v_pk_mul_f32 v[70:71], v[72:73], v[128:129] op_sel_hi:[1,0]
	v_pk_mul_f32 v[72:73], v[82:83], v[128:129] op_sel_hi:[1,0]
	v_pk_mul_f32 v[56:57], v[68:69], v[128:129] op_sel_hi:[1,0]
	v_pk_mul_f32 v[68:69], v[80:81], v[128:129] op_sel_hi:[1,0]
	v_pk_mul_f32 v[76:77], v[86:87], v[128:129] op_sel_hi:[1,0]
	v_pk_mul_f32 v[80:81], v[88:89], v[128:129] op_sel_hi:[1,0]
	v_lshlrev_b32_e32 v82, 16, v36
	v_pk_mul_f32 v[36:37], v[60:61], v[128:129] op_sel_hi:[1,0]
	v_pk_mul_f32 v[42:43], v[42:43], v[128:129] op_sel_hi:[1,0]
	v_pk_mul_f32 v[54:55], v[74:75], v[128:129] op_sel_hi:[1,0]
	v_lshlrev_b32_e32 v83, 16, v20
	v_and_b32_e32 v75, 0xffff0000, v8
	v_lshlrev_b32_e32 v86, 16, v38
	v_lshlrev_b32_e32 v87, 16, v22
	v_lshlrev_b32_e32 v88, 16, v39
	v_lshlrev_b32_e32 v89, 16, v23
	v_and_b32_e32 v12, 0xffff0000, v6
	v_lshlrev_b32_e32 v38, 16, v30
	v_and_b32_e32 v74, 0xffff0000, v28
	v_lshlrev_b32_e32 v14, 16, v4
	v_and_b32_e32 v30, 0xffff0000, v4
	v_lshlrev_b32_e32 v4, 16, v5
	v_lshlrev_b32_e32 v39, 16, v10
	v_mov_b32_e32 v104, v98
	v_mov_b32_e32 v100, v166
	v_mov_b32_e32 v101, v167
	v_mov_b32_e32 v102, v168
	v_mov_b32_e32 v103, v169
	v_mov_b32_e32 v120, v170
	v_mov_b32_e32 v121, v171
	v_mov_b32_e32 v122, v172
	v_mov_b32_e32 v123, v173
	v_pk_mul_f32 v[64:65], v[64:65], v[102:103]
	v_pk_mul_f32 v[62:63], v[62:63], v[100:101]
	v_pk_mul_f32 v[72:73], v[72:73], v[122:123]
	v_pk_mul_f32 v[70:71], v[70:71], v[120:121]
	v_cvt_pk_bf16_f32 v62, v62, v63
	v_cvt_pk_bf16_f32 v63, v64, v65
	s_nop 0
	v_cvt_pk_bf16_f32 v64, v70, v71
	v_cvt_pk_bf16_f32 v65, v72, v73
	global_store_dwordx4 v[106:107], v[62:65], off
	s_nop 1
	s_nop 0
	v_mov_b32_e32 v62, v174
	v_mov_b32_e32 v63, v175
	v_mov_b32_e32 v64, v176
	v_mov_b32_e32 v65, v177
	v_mov_b32_e32 v70, v178
	v_mov_b32_e32 v71, v179
	v_mov_b32_e32 v72, v180
	v_mov_b32_e32 v73, v181
	v_pk_mul_f32 v[64:65], v[68:69], v[64:65]
	v_pk_mul_f32 v[56:57], v[56:57], v[62:63]
	v_pk_mul_f32 v[68:69], v[80:81], v[72:73]
	v_pk_mul_f32 v[70:71], v[76:77], v[70:71]
	v_cvt_pk_bf16_f32 v62, v56, v57
	v_cvt_pk_bf16_f32 v63, v64, v65
	v_and_b32_e32 v76, 0xffff0000, v32
	v_cvt_pk_bf16_f32 v64, v70, v71
	v_cvt_pk_bf16_f32 v65, v68, v69
	global_store_dwordx4 v[106:107], v[62:65], off offset:1024
	s_nop 1
	v_lshlrev_b32_e32 v62, 16, v32
	v_lshlrev_b32_e32 v64, 16, v33
	v_and_b32_e32 v80, 0xffff0000, v33
	v_pk_mul_f32 v[32:33], v[58:59], v[128:129] op_sel_hi:[1,0]
	v_and_b32_e32 v57, 0xffff0000, v9
	v_lshlrev_b32_e32 v68, 16, v34
	v_and_b32_e32 v72, 0xffff0000, v34
	v_and_b32_e32 v34, 0xffff0000, v7
	v_and_b32_e32 v56, 0xffff0000, v29
	v_lshlrev_b32_e32 v63, 16, v16
	v_and_b32_e32 v77, 0xffff0000, v16
	v_lshlrev_b32_e32 v65, 16, v17
	v_and_b32_e32 v81, 0xffff0000, v17
	v_lshlrev_b32_e32 v69, 16, v18
	v_and_b32_e32 v73, 0xffff0000, v18
	v_lshlrev_b32_e32 v71, 16, v19
	v_pk_mov_b32 v[16:17], v[112:113], v[110:111] op_sel:[1,0]
	v_pk_mul_f32 v[18:19], v[104:105], v[104:105]
	v_pk_mul_f32 v[16:17], v[128:129], v[16:17] op_sel_hi:[0,1]
	v_mov_b32_e32 v23, v19
	v_lshlrev_b32_e32 v70, 16, v35
	v_mov_b32_e32 v35, v41
	v_mov_b32_e32 v100, v182
	v_mov_b32_e32 v101, v183
	v_mov_b32_e32 v102, v184
	v_mov_b32_e32 v103, v185
	v_mov_b32_e32 v120, v186
	v_mov_b32_e32 v121, v187
	v_mov_b32_e32 v122, v188
	v_mov_b32_e32 v123, v189
	v_pk_mul_f32 v[36:37], v[36:37], v[102:103]
	v_pk_mul_f32 v[32:33], v[32:33], v[100:101]
	v_pk_mul_f32 v[54:55], v[54:55], v[122:123]
	v_pk_mul_f32 v[42:43], v[42:43], v[120:121]
	v_cvt_pk_bf16_f32 v58, v32, v33
	v_cvt_pk_bf16_f32 v59, v36, v37
	v_and_b32_e32 v100, 0xffff0000, v3
	v_cvt_pk_bf16_f32 v60, v42, v43
	v_cvt_pk_bf16_f32 v61, v54, v55
	global_store_dwordx4 v[106:107], v[58:61], off offset:2048
	s_nop 1
	v_lshlrev_b32_e32 v43, 16, v8
	v_lshlrev_b32_e32 v55, 16, v9
	v_pk_mul_f32 v[8:9], v[96:97], v[96:97]
	v_lshlrev_b32_e32 v37, 16, v7
	v_pk_fma_f32 v[8:9], v[82:83], v[82:83], v[8:9]
	v_mov_b32_e32 v36, v34
	v_pk_fma_f32 v[8:9], v[84:85], v[84:85], v[8:9]
	v_lshlrev_b32_e32 v103, 16, v3
	v_pk_fma_f32 v[8:9], v[90:91], v[90:91], v[8:9]
	v_mov_b32_e32 v102, v100
	v_pk_fma_f32 v[8:9], v[86:87], v[86:87], v[8:9]
	v_lshlrev_b32_e32 v42, 16, v28
	v_pk_fma_f32 v[8:9], v[92:93], v[92:93], v[8:9]
	v_lshlrev_b32_e32 v54, 16, v29
	v_pk_fma_f32 v[8:9], v[88:89], v[88:89], v[8:9]
	v_lshlrev_b32_e32 v29, 16, v6
	v_lshlrev_b32_e32 v58, 16, v31
	v_and_b32_e32 v60, 0xffff0000, v31
	v_and_b32_e32 v32, 0xffff0000, v5
	v_mov_b32_e32 v28, v12
	v_lshlrev_b32_e32 v59, 16, v11
	v_and_b32_e32 v61, 0xffff0000, v11
	v_and_b32_e32 v31, 0xffff0000, v0
	v_lshlrev_b32_e32 v5, 16, v1
	v_and_b32_e32 v33, 0xffff0000, v1
	v_pk_mul_f32 v[0:1], v[36:37], v[36:37]
	v_pk_mov_b32 v[10:11], v[52:53], v[26:27] op_sel:[1,0]
	v_pk_mul_f32 v[52:53], v[102:103], v[102:103]
	v_pk_fma_f32 v[8:9], v[94:95], v[94:95], v[8:9]
	v_pk_mul_f32 v[20:21], v[28:29], v[28:29]
	v_mov_b32_e32 v26, v1
	v_mov_b32_e32 v27, v53
	v_mov_b32_e32 v1, v52
	v_pk_fma_f32 v[52:53], v[62:63], v[62:63], v[8:9]
	v_pk_mul_f32 v[8:9], v[44:45], v[128:129] op_sel_hi:[1,0]
	v_pk_mul_f32 v[10:11], v[128:129], v[10:11] op_sel_hi:[0,1]
	v_mov_b32_e32 v22, v21
	v_mov_b32_e32 v21, v18
	v_pk_mul_f32 v[18:19], v[50:51], v[128:129] op_sel_hi:[1,0]
	v_pk_fma_f32 v[24:25], v[76:77], v[76:77], v[52:53]
	v_mov_b32_e32 v44, v87
	v_pk_fma_f32 v[24:25], v[64:65], v[64:65], v[24:25]
	v_mov_b32_e32 v45, v93
	v_pk_fma_f32 v[24:25], v[80:81], v[80:81], v[24:25]
	v_mov_b32_e32 v101, v41
	v_pk_fma_f32 v[24:25], v[68:69], v[68:69], v[24:25]
	v_mov_b32_e32 v87, v92
	v_pk_fma_f32 v[24:25], v[72:73], v[72:73], v[24:25]
	v_mov_b32_e32 v120, v200
	v_mov_b32_e32 v121, v201
	v_mov_b32_e32 v122, v202
	v_mov_b32_e32 v123, v203
	v_mov_b32_e32 v124, v190
	v_mov_b32_e32 v125, v191
	v_mov_b32_e32 v126, v192
	v_mov_b32_e32 v127, v193
	v_pk_mul_f32 v[10:11], v[10:11], v[120:121]
	v_pk_mul_f32 v[8:9], v[8:9], v[124:125]
	v_pk_mul_f32 v[18:19], v[18:19], v[126:127]
	v_pk_mul_f32 v[16:17], v[16:17], v[122:123]
	v_cvt_pk_bf16_f32 v8, v8, v9
	v_cvt_pk_bf16_f32 v9, v18, v19
	v_cvt_pk_bf16_f32 v10, v10, v11
	v_pk_fma_f32 v[24:25], v[70:71], v[70:71], v[24:25]
	v_cvt_pk_bf16_f32 v11, v16, v17
	global_store_dwordx4 v[106:107], v[8:11], off offset:3072
	s_nop 1
	s_nop 0
	v_pk_fma_f32 v[24:25], v[78:79], v[78:79], v[24:25]
	s_nop 0
	v_pk_fma_f32 v[24:25], v[42:43], v[42:43], v[24:25]
	s_nop 0
	v_pk_fma_f32 v[24:25], v[74:75], v[74:75], v[24:25]
	s_nop 0
	v_pk_fma_f32 v[24:25], v[54:55], v[54:55], v[24:25]
	s_nop 0
	v_pk_fma_f32 v[24:25], v[56:57], v[56:57], v[24:25]
	s_nop 0
	v_pk_fma_f32 v[24:25], v[38:39], v[38:39], v[24:25]
	s_nop 0
	v_pk_fma_f32 v[24:25], v[66:67], v[66:67], v[24:25]
	s_nop 0
	v_pk_fma_f32 v[24:25], v[58:59], v[58:59], v[24:25]
	s_nop 0
	v_pk_fma_f32 v[24:25], v[60:61], v[60:61], v[24:25]
	s_nop 0
	v_pk_fma_f32 v[24:25], v[14:15], v[14:15], v[24:25]
	s_nop 0
	v_pk_fma_f32 v[24:25], v[30:31], v[30:31], v[24:25]
	s_nop 0
	v_pk_fma_f32 v[24:25], v[4:5], v[4:5], v[24:25]
	s_nop 0
	v_pk_fma_f32 v[24:25], v[32:33], v[32:33], v[24:25]
	s_nop 0
	v_pk_add_f32 v[22:23], v[22:23], v[24:25]
	v_mov_b32_e32 v24, v83
	v_pk_add_f32 v[20:21], v[20:21], v[22:23]
	v_mov_b32_e32 v25, v97
	v_pk_add_f32 v[20:21], v[26:27], v[20:21]
	v_mov_b32_e32 v26, v85
	v_pk_add_f32 v[0:1], v[0:1], v[20:21]
	ds_bpermute_b32 v21, v114, v1
	ds_bpermute_b32 v20, v114, v0
	v_mov_b32_e32 v27, v91
	v_lshl_add_u64 v[22:23], s[14:15], 0, v[40:41]
	v_mov_b32_e32 v83, v96
	v_mov_b32_e32 v85, v90
	s_waitcnt lgkmcnt(0)
	v_pk_add_f32 v[0:1], v[0:1], v[20:21]
	ds_bpermute_b32 v21, v116, v1
	ds_bpermute_b32 v20, v116, v0
	s_waitcnt lgkmcnt(0)
	v_pk_add_f32 v[0:1], v[0:1], v[20:21]
	ds_bpermute_b32 v21, v117, v1
	ds_bpermute_b32 v20, v117, v0
	s_waitcnt lgkmcnt(0)
	v_pk_add_f32 v[0:1], v[0:1], v[20:21]
	ds_bpermute_b32 v21, v118, v1
	ds_bpermute_b32 v20, v118, v0
	s_waitcnt lgkmcnt(0)
	v_pk_add_f32 v[0:1], v[0:1], v[20:21]
	ds_bpermute_b32 v21, v119, v1
	ds_bpermute_b32 v20, v119, v0
	s_waitcnt lgkmcnt(0)
	v_pk_add_f32 v[0:1], v[0:1], v[20:21]
	ds_bpermute_b32 v21, v115, v1
	ds_bpermute_b32 v20, v115, v0
	s_waitcnt lgkmcnt(0)
	v_pk_add_f32 v[0:1], v[0:1], v[20:21]
	s_nop 0
	v_pk_fma_f32 v[20:21], v[0:1], s[46:47], v[108:109] op_sel_hi:[1,0,0]
	v_mov_b32_e32 v1, v95
	v_mul_f32_e32 v0, 0x4b800000, v21
	v_cmp_gt_f32_e32 vcc, s3, v21
	s_nop 1
	v_cndmask_b32_e32 v0, v21, v0, vcc
	v_rsq_f32_e32 v2, v0
	v_mov_b32_e32 v0, v89
	v_mov_b32_e32 v89, v94
	v_mul_f32_e32 v6, 0x45800000, v2
	v_cndmask_b32_e32 v2, v2, v6, vcc
	v_pk_mul_f32 v[44:45], v[44:45], v[2:3] op_sel_hi:[1,0]
	v_pk_mul_f32 v[0:1], v[0:1], v[2:3] op_sel_hi:[1,0]
	v_pk_mul_f32 v[24:25], v[24:25], v[2:3] op_sel_hi:[1,0]
	v_pk_mul_f32 v[26:27], v[26:27], v[2:3] op_sel_hi:[1,0]
	v_mov_b32_e32 v8, v170
	v_mov_b32_e32 v9, v171
	v_mov_b32_e32 v10, v172
	v_mov_b32_e32 v11, v173
	v_mov_b32_e32 v16, v166
	v_mov_b32_e32 v17, v167
	v_mov_b32_e32 v18, v168
	v_mov_b32_e32 v19, v169
	v_pk_mul_f32 v[0:1], v[0:1], v[10:11]
	v_pk_mul_f32 v[10:11], v[44:45], v[8:9]
	v_pk_mul_f32 v[18:19], v[26:27], v[18:19]
	v_pk_mul_f32 v[16:17], v[24:25], v[16:17]
	v_mov_b32_e32 v24, v65
	v_cvt_pk_bf16_f32 v8, v16, v17
	v_cvt_pk_bf16_f32 v9, v18, v19
	v_cvt_pk_bf16_f32 v10, v10, v11
	v_cvt_pk_bf16_f32 v11, v0, v1
	global_store_dwordx4 v[22:23], v[8:11], off
	s_nop 1
	s_nop 0
	v_mov_b32_e32 v25, v81
	v_mov_b32_e32 v0, v63
	v_mov_b32_e32 v1, v77
	v_mov_b32_e32 v26, v69
	v_mov_b32_e32 v27, v73
	v_mov_b32_e32 v44, v71
	v_mov_b32_e32 v45, v79
	v_pk_mul_f32 v[24:25], v[24:25], v[2:3] op_sel_hi:[1,0]
	v_pk_mul_f32 v[0:1], v[0:1], v[2:3] op_sel_hi:[1,0]
	v_pk_mul_f32 v[26:27], v[26:27], v[2:3] op_sel_hi:[1,0]
	v_pk_mul_f32 v[44:45], v[44:45], v[2:3] op_sel_hi:[1,0]
	v_cmp_gt_f32_e32 vcc, s3, v20
	v_mov_b32_e32 v63, v76
	v_mov_b32_e32 v65, v80
	v_mov_b32_e32 v69, v72
	v_mov_b32_e32 v71, v78
	s_lshl_b32 s3, s26, 5
	s_add_i32 s48, s24, s3
	v_mov_b32_e32 v8, v174
	v_mov_b32_e32 v9, v175
	v_mov_b32_e32 v10, v176
	v_mov_b32_e32 v11, v177
	v_mov_b32_e32 v16, v178
	v_mov_b32_e32 v17, v179
	v_mov_b32_e32 v18, v180
	v_mov_b32_e32 v19, v181
	v_pk_mul_f32 v[10:11], v[24:25], v[10:11]
	v_pk_mul_f32 v[0:1], v[0:1], v[8:9]
	v_pk_mul_f32 v[18:19], v[44:45], v[18:19]
	v_pk_mul_f32 v[16:17], v[26:27], v[16:17]
	v_cvt_pk_bf16_f32 v8, v0, v1
	v_cvt_pk_bf16_f32 v9, v10, v11
	v_mov_b32_e32 v24, v55
	v_cvt_pk_bf16_f32 v10, v16, v17
	v_cvt_pk_bf16_f32 v11, v18, v19
	global_store_dwordx4 v[22:23], v[8:11], off offset:1024
	s_nop 1
	s_nop 0
	v_mov_b32_e32 v25, v57
	v_mov_b32_e32 v0, v43
	v_mov_b32_e32 v1, v75
	v_mov_b32_e32 v26, v39
	v_mov_b32_e32 v27, v67
	v_mov_b32_e32 v44, v59
	v_mov_b32_e32 v45, v61
	v_pk_mul_f32 v[24:25], v[24:25], v[2:3] op_sel_hi:[1,0]
	v_pk_mul_f32 v[0:1], v[0:1], v[2:3] op_sel_hi:[1,0]
	v_pk_mul_f32 v[26:27], v[26:27], v[2:3] op_sel_hi:[1,0]
	v_pk_mul_f32 v[44:45], v[44:45], v[2:3] op_sel_hi:[1,0]
	v_mov_b32_e32 v43, v74
	v_mov_b32_e32 v55, v56
	v_mov_b32_e32 v39, v66
	v_mov_b32_e32 v59, v60
	v_mov_b32_e32 v8, v182
	v_mov_b32_e32 v9, v183
	v_mov_b32_e32 v10, v184
	v_mov_b32_e32 v11, v185
	v_mov_b32_e32 v16, v186
	v_mov_b32_e32 v17, v187
	v_mov_b32_e32 v18, v188
	v_mov_b32_e32 v19, v189
	v_pk_mul_f32 v[10:11], v[24:25], v[10:11]
	v_pk_mul_f32 v[0:1], v[0:1], v[8:9]
	v_pk_mul_f32 v[18:19], v[44:45], v[18:19]
	v_pk_mul_f32 v[16:17], v[26:27], v[16:17]
	v_cvt_pk_bf16_f32 v8, v0, v1
	v_cvt_pk_bf16_f32 v9, v10, v11
	v_mov_b32_e32 v0, v15
	v_cvt_pk_bf16_f32 v10, v16, v17
	v_cvt_pk_bf16_f32 v11, v18, v19
	global_store_dwordx4 v[22:23], v[8:11], off offset:2048
	s_nop 1
	s_nop 0
	v_mov_b32_e32 v1, v31
	v_mov_b32_e32 v24, v5
	v_mov_b32_e32 v25, v33
	v_pk_mov_b32 v[26:27], v[104:105], v[98:99] op_sel:[1,0]
	v_pk_mov_b32 v[44:45], v[102:103], v[100:101] op_sel:[1,0]
	v_pk_mul_f32 v[0:1], v[0:1], v[2:3] op_sel_hi:[1,0]
	v_pk_mul_f32 v[24:25], v[24:25], v[2:3] op_sel_hi:[1,0]
	v_pk_mul_f32 v[26:27], v[2:3], v[26:27] op_sel_hi:[0,1]
	v_pk_mul_f32 v[2:3], v[2:3], v[44:45] op_sel_hi:[0,1]
	v_mul_f32_e32 v5, 0x4b800000, v20
	v_cndmask_b32_e32 v5, v20, v5, vcc
	v_rsq_f32_e32 v5, v5
	v_mov_b32_e32 v15, v30
	v_mul_f32_e32 v6, 0x45800000, v5
	v_cndmask_b32_e32 v6, v5, v6, vcc
	v_pk_mul_f32 v[20:21], v[84:85], v[6:7] op_sel_hi:[1,0]
	v_mov_b32_e32 v5, v32
	v_pk_mul_f32 v[14:15], v[14:15], v[6:7] op_sel_hi:[1,0]
	v_pk_mul_f32 v[4:5], v[4:5], v[6:7] op_sel_hi:[1,0]
	v_mov_b32_e32 v8, v190
	v_mov_b32_e32 v9, v191
	v_mov_b32_e32 v10, v192
	v_mov_b32_e32 v11, v193
	v_mov_b32_e32 v16, v200
	v_mov_b32_e32 v17, v201
	v_mov_b32_e32 v18, v202
	v_mov_b32_e32 v19, v203
	v_pk_mul_f32 v[0:1], v[0:1], v[8:9]
	v_pk_mul_f32 v[8:9], v[2:3], v[18:19]
	v_pk_mul_f32 v[2:3], v[26:27], v[16:17]
	v_pk_mul_f32 v[10:11], v[24:25], v[10:11]
	v_cvt_pk_bf16_f32 v0, v0, v1
	v_pk_mul_f32 v[18:19], v[82:83], v[6:7] op_sel_hi:[1,0]
	v_cvt_pk_bf16_f32 v1, v10, v11
	v_cvt_pk_bf16_f32 v2, v2, v3
	v_cvt_pk_bf16_f32 v3, v8, v9
	global_store_dwordx4 v[22:23], v[0:3], off offset:3072
	s_nop 1
	s_nop 0
	v_lshl_add_u64 v[16:17], s[8:9], 0, v[40:41]
	v_pk_mul_f32 v[22:23], v[86:87], v[6:7] op_sel_hi:[1,0]
	v_pk_mul_f32 v[24:25], v[88:89], v[6:7] op_sel_hi:[1,0]
	v_mov_b32_e32 v0, v166
	v_mov_b32_e32 v1, v167
	v_mov_b32_e32 v2, v168
	v_mov_b32_e32 v3, v169
	v_mov_b32_e32 v8, v170
	v_mov_b32_e32 v9, v171
	v_mov_b32_e32 v10, v172
	v_mov_b32_e32 v11, v173
	v_pk_mul_f32 v[2:3], v[20:21], v[2:3]
	v_pk_mul_f32 v[0:1], v[18:19], v[0:1]
	v_pk_mul_f32 v[10:11], v[24:25], v[10:11]
	v_pk_mul_f32 v[8:9], v[22:23], v[8:9]
	v_cvt_pk_bf16_f32 v0, v0, v1
	v_cvt_pk_bf16_f32 v1, v2, v3
	v_pk_mul_f32 v[18:19], v[62:63], v[6:7] op_sel_hi:[1,0]
	v_cvt_pk_bf16_f32 v2, v8, v9
	v_cvt_pk_bf16_f32 v3, v10, v11
	global_store_dwordx4 v[16:17], v[0:3], off
	s_nop 1
	s_nop 0
	v_pk_mul_f32 v[20:21], v[64:65], v[6:7] op_sel_hi:[1,0]
	v_pk_mul_f32 v[22:23], v[68:69], v[6:7] op_sel_hi:[1,0]
	v_pk_mul_f32 v[24:25], v[70:71], v[6:7] op_sel_hi:[1,0]
	v_mov_b32_e32 v0, v174
	v_mov_b32_e32 v1, v175
	v_mov_b32_e32 v2, v176
	v_mov_b32_e32 v3, v177
	v_mov_b32_e32 v8, v178
	v_mov_b32_e32 v9, v179
	v_mov_b32_e32 v10, v180
	v_mov_b32_e32 v11, v181
	v_pk_mul_f32 v[2:3], v[20:21], v[2:3]
	v_pk_mul_f32 v[0:1], v[18:19], v[0:1]
	v_pk_mul_f32 v[10:11], v[24:25], v[10:11]
	v_pk_mul_f32 v[8:9], v[22:23], v[8:9]
	v_cvt_pk_bf16_f32 v0, v0, v1
	v_cvt_pk_bf16_f32 v1, v2, v3
	v_pk_mul_f32 v[18:19], v[42:43], v[6:7] op_sel_hi:[1,0]
	v_cvt_pk_bf16_f32 v2, v8, v9
	v_cvt_pk_bf16_f32 v3, v10, v11
	global_store_dwordx4 v[16:17], v[0:3], off offset:1024
	s_nop 1
	s_nop 0
	v_pk_mul_f32 v[20:21], v[54:55], v[6:7] op_sel_hi:[1,0]
	v_pk_mul_f32 v[22:23], v[38:39], v[6:7] op_sel_hi:[1,0]
	v_pk_mul_f32 v[24:25], v[58:59], v[6:7] op_sel_hi:[1,0]
	v_and_b32_e32 v13, s0, v7
	v_pk_mov_b32 v[12:13], v[28:29], v[12:13] op_sel:[1,0]
	v_mov_b32_e32 v0, v182
	v_mov_b32_e32 v1, v183
	v_mov_b32_e32 v2, v184
	v_mov_b32_e32 v3, v185
	v_mov_b32_e32 v8, v186
	v_mov_b32_e32 v9, v187
	v_mov_b32_e32 v10, v188
	v_mov_b32_e32 v11, v189
	v_pk_mul_f32 v[2:3], v[20:21], v[2:3]
	v_pk_mul_f32 v[0:1], v[18:19], v[0:1]
	v_pk_mul_f32 v[10:11], v[24:25], v[10:11]
	v_pk_mul_f32 v[8:9], v[22:23], v[8:9]
	v_cvt_pk_bf16_f32 v0, v0, v1
	v_cvt_pk_bf16_f32 v1, v2, v3
	v_pk_mov_b32 v[18:19], v[36:37], v[34:35] op_sel:[1,0]
	v_cvt_pk_bf16_f32 v2, v8, v9
	v_cvt_pk_bf16_f32 v3, v10, v11
	global_store_dwordx4 v[16:17], v[0:3], off offset:2048
	s_nop 1
	s_nop 0
	v_pk_mul_f32 v[12:13], v[6:7], v[12:13] op_sel_hi:[0,1]
	v_pk_mul_f32 v[6:7], v[6:7], v[18:19] op_sel_hi:[0,1]
	v_mov_b32_e32 v0, v190
	v_mov_b32_e32 v1, v191
	v_mov_b32_e32 v2, v192
	v_mov_b32_e32 v3, v193
	v_mov_b32_e32 v8, v200
	v_mov_b32_e32 v9, v201
	v_mov_b32_e32 v10, v202
	v_mov_b32_e32 v11, v203
	v_pk_mul_f32 v[2:3], v[4:5], v[2:3]
	v_pk_mul_f32 v[0:1], v[14:15], v[0:1]
	v_pk_mul_f32 v[4:5], v[6:7], v[10:11]
	v_pk_mul_f32 v[6:7], v[12:13], v[8:9]
	v_cvt_pk_bf16_f32 v0, v0, v1
	v_cvt_pk_bf16_f32 v1, v2, v3
	s_nop 0
	v_cvt_pk_bf16_f32 v2, v6, v7
	v_cvt_pk_bf16_f32 v3, v4, v5
	global_store_dwordx4 v[16:17], v[0:3], off offset:3072
	s_nop 1
